# combined: final-norm output stores write-through (sc1) and GEMM epilogue flat stores converted to global stores
# speedup vs baseline: 1.0067x; 1.0067x over previous
.LBB0_384:
	s_waitcnt vmcnt(8)
	v_fmamk_f32 v145, v163, 0x3a800000, v154
	v_rsq_f32_e32 v145, v145
	s_nop 1
	s_nop 0
	s_nop 1
	s_nop 1
	v_lshl_or_b32 v148, s60, 7, v152
	v_ashrrev_i32_e32 v149, 31, v148
	v_lshlrev_b64 v[148:149], 1, v[148:149]
	v_mov_b32_e32 v164, v145
	v_pk_mul_f32 v[124:125], v[124:125], v[164:165] op_sel_hi:[1,0]
	v_pk_mul_f32 v[126:127], v[126:127], v[164:165] op_sel_hi:[1,0]
	v_pk_mul_f32 v[122:123], v[122:123], v[164:165] op_sel_hi:[1,0]
	v_pk_mul_f32 v[120:121], v[120:121], v[164:165] op_sel_hi:[1,0]
	v_pk_mul_f32 v[118:119], v[118:119], v[164:165] op_sel_hi:[1,0]
	v_pk_mul_f32 v[116:117], v[116:117], v[164:165] op_sel_hi:[1,0]
	v_mul_f32_e32 v145, 0xbfb8aa3b, v124
	v_mul_f32_e32 v165, 0xbfb8aa3b, v125
	v_exp_f32_e32 v145, v145
	v_exp_f32_e32 v165, v165
	v_mov_b64_e32 v[146:147], s[12:13]
	v_mad_i64_i32 v[166:167], s[8:9], v144, s59, v[146:147]
	v_pk_mul_f32 v[168:169], v[114:115], v[164:165] op_sel_hi:[1,0]
	v_add_f32_e32 v114, 1.0, v145
	v_rcp_f32_e32 v145, v114
	v_add_f32_e32 v114, 1.0, v165
	v_rcp_f32_e32 v165, v114
	v_lshl_add_u64 v[166:167], v[166:167], 0, v[148:149]
	v_pk_mul_f32 v[114:115], v[112:113], v[164:165] op_sel_hi:[1,0]
	v_mul_f32_e32 v112, v124, v145
	v_mul_f32_e32 v112, v116, v112
	v_mul_f32_e32 v116, 0xbfb8aa3b, v126
	v_mul_f32_e32 v124, 0xbfb8aa3b, v127
	v_exp_f32_e32 v116, v116
	v_exp_f32_e32 v124, v124
	v_mul_f32_e32 v113, v125, v165
	v_mul_f32_e32 v113, v117, v113
	v_add_f32_e32 v116, 1.0, v116
	v_add_f32_e32 v117, 1.0, v124
	v_rcp_f32_e32 v116, v116
	v_rcp_f32_e32 v117, v117
	v_cvt_pk_bf16_f32 v112, v112, v113
	v_mul_f32_e32 v113, v126, v116
	v_mul_f32_e32 v116, v127, v117
	v_mul_f32_e32 v117, 0xbfb8aa3b, v120
	v_mul_f32_e32 v113, v118, v113
	v_exp_f32_e32 v117, v117
	v_mul_f32_e32 v118, 0xbfb8aa3b, v121
	v_exp_f32_e32 v118, v118
	v_mul_f32_e32 v116, v119, v116
	v_cvt_pk_bf16_f32 v113, v113, v116
	v_add_f32_e32 v116, 1.0, v117
	v_rcp_f32_e32 v116, v116
	v_add_f32_e32 v117, 1.0, v118
	v_mul_f32_e32 v118, 0xbfb8aa3b, v122
	v_rcp_f32_e32 v117, v117
	v_exp_f32_e32 v118, v118
	v_mul_f32_e32 v116, v120, v116
	v_mul_f32_e32 v114, v114, v116
	v_mul_f32_e32 v116, v121, v117
	v_add_f32_e32 v117, 1.0, v118
	v_rcp_f32_e32 v117, v117
	v_mul_f32_e32 v118, 0xbfb8aa3b, v123
	v_exp_f32_e32 v118, v118
	v_mul_f32_e32 v115, v115, v116
	v_cvt_pk_bf16_f32 v114, v114, v115
	v_mul_f32_e32 v115, v122, v117
	v_fmamk_f32 v117, v162, 0x3a800000, v154
	v_rsq_f32_e32 v117, v117
	v_add_f32_e32 v116, 1.0, v118
	v_rcp_f32_e32 v116, v116
	v_mul_f32_e32 v115, v168, v115
	v_mul_f32_e32 v116, v123, v116
	v_mul_f32_e32 v116, v169, v116
	v_cvt_pk_bf16_f32 v115, v115, v116
	global_store_dwordx4 v[166:167], v[112:115], off
	s_nop 1
	v_or_b32_e32 v113, 16, v144
	s_nop 0
	s_nop 1
	s_nop 0
	v_mov_b32_e32 v112, v117
	v_pk_mul_f32 v[108:109], v[112:113], v[108:109] op_sel_hi:[0,1]
	v_mad_i64_i32 v[114:115], s[8:9], v113, s59, v[146:147]
	v_pk_mul_f32 v[110:111], v[112:113], v[110:111] op_sel_hi:[0,1]
	v_pk_mul_f32 v[106:107], v[112:113], v[106:107] op_sel_hi:[0,1]
	v_pk_mul_f32 v[104:105], v[112:113], v[104:105] op_sel_hi:[0,1]
	v_pk_mul_f32 v[102:103], v[112:113], v[102:103] op_sel_hi:[0,1]
	v_pk_mul_f32 v[100:101], v[112:113], v[100:101] op_sel_hi:[0,1]
	v_mul_f32_e32 v113, 0xbfb8aa3b, v108
	v_exp_f32_e32 v113, v113
	v_mul_f32_e32 v116, 0xbfb8aa3b, v109
	v_exp_f32_e32 v118, v116
	v_lshl_add_u64 v[114:115], v[114:115], 0, v[148:149]
	v_pk_mul_f32 v[116:117], v[112:113], v[98:99] op_sel_hi:[0,1]
	v_add_f32_e32 v98, 1.0, v113
	v_rcp_f32_e32 v113, v98
	v_add_f32_e32 v98, 1.0, v118
	v_rcp_f32_e32 v118, v98
	v_pk_mul_f32 v[98:99], v[112:113], v[96:97] op_sel_hi:[0,1]
	v_mul_f32_e32 v96, v108, v113
	v_mul_f32_e32 v96, v100, v96
	v_mul_f32_e32 v100, 0xbfb8aa3b, v110
	v_mul_f32_e32 v108, 0xbfb8aa3b, v111
	v_exp_f32_e32 v100, v100
	v_exp_f32_e32 v108, v108
	v_mul_f32_e32 v97, v109, v118
	v_mul_f32_e32 v97, v101, v97
	v_add_f32_e32 v100, 1.0, v100
	v_add_f32_e32 v101, 1.0, v108
	v_rcp_f32_e32 v100, v100
	v_rcp_f32_e32 v101, v101
	v_cvt_pk_bf16_f32 v96, v96, v97
	v_mul_f32_e32 v97, v110, v100
	v_mul_f32_e32 v100, v111, v101
	v_mul_f32_e32 v101, 0xbfb8aa3b, v104
	v_mul_f32_e32 v97, v102, v97
	v_exp_f32_e32 v101, v101
	v_mul_f32_e32 v102, 0xbfb8aa3b, v105
	v_exp_f32_e32 v102, v102
	v_mul_f32_e32 v100, v103, v100
	v_cvt_pk_bf16_f32 v97, v97, v100
	v_add_f32_e32 v100, 1.0, v101
	v_rcp_f32_e32 v100, v100
	v_add_f32_e32 v101, 1.0, v102
	v_mul_f32_e32 v102, 0xbfb8aa3b, v106
	v_rcp_f32_e32 v101, v101
	v_exp_f32_e32 v102, v102
	v_mul_f32_e32 v100, v104, v100
	v_mul_f32_e32 v98, v98, v100
	v_mul_f32_e32 v100, v105, v101
	v_add_f32_e32 v101, 1.0, v102
	v_rcp_f32_e32 v101, v101
	v_mul_f32_e32 v102, 0xbfb8aa3b, v107
	v_exp_f32_e32 v102, v102
	v_mul_f32_e32 v99, v99, v100
	v_cvt_pk_bf16_f32 v98, v98, v99
	v_mul_f32_e32 v99, v106, v101
	v_fmamk_f32 v101, v161, 0x3a800000, v154
	v_rsq_f32_e32 v101, v101
	v_add_f32_e32 v100, 1.0, v102
	v_rcp_f32_e32 v100, v100
	v_mul_f32_e32 v99, v116, v99
	v_mul_f32_e32 v100, v107, v100
	v_mul_f32_e32 v100, v117, v100
	v_cvt_pk_bf16_f32 v99, v99, v100
	global_store_dwordx4 v[114:115], v[96:99], off
	s_nop 1
	v_or_b32_e32 v97, 32, v144
	s_nop 0
	s_nop 1
	s_nop 0
	v_mov_b32_e32 v96, v101
	v_pk_mul_f32 v[92:93], v[96:97], v[92:93] op_sel_hi:[0,1]
	v_mad_i64_i32 v[98:99], s[8:9], v97, s59, v[146:147]
	v_pk_mul_f32 v[94:95], v[96:97], v[94:95] op_sel_hi:[0,1]
	v_pk_mul_f32 v[90:91], v[96:97], v[90:91] op_sel_hi:[0,1]
	v_pk_mul_f32 v[88:89], v[96:97], v[88:89] op_sel_hi:[0,1]
	v_pk_mul_f32 v[86:87], v[96:97], v[86:87] op_sel_hi:[0,1]
	v_pk_mul_f32 v[84:85], v[96:97], v[84:85] op_sel_hi:[0,1]
	v_mul_f32_e32 v97, 0xbfb8aa3b, v92
	v_exp_f32_e32 v97, v97
	v_mul_f32_e32 v100, 0xbfb8aa3b, v93
	v_exp_f32_e32 v102, v100
	v_lshl_add_u64 v[98:99], v[98:99], 0, v[148:149]
	v_pk_mul_f32 v[100:101], v[96:97], v[82:83] op_sel_hi:[0,1]
	v_add_f32_e32 v82, 1.0, v97
	v_rcp_f32_e32 v97, v82
	v_add_f32_e32 v82, 1.0, v102
	v_rcp_f32_e32 v102, v82
	v_pk_mul_f32 v[82:83], v[96:97], v[80:81] op_sel_hi:[0,1]
	v_mul_f32_e32 v80, v92, v97
	v_mul_f32_e32 v80, v84, v80
	v_mul_f32_e32 v84, 0xbfb8aa3b, v94
	v_mul_f32_e32 v92, 0xbfb8aa3b, v95
	v_exp_f32_e32 v84, v84
	v_exp_f32_e32 v92, v92
	v_mul_f32_e32 v81, v93, v102
	v_mul_f32_e32 v81, v85, v81
	v_add_f32_e32 v84, 1.0, v84
	v_add_f32_e32 v85, 1.0, v92
	v_rcp_f32_e32 v84, v84
	v_rcp_f32_e32 v85, v85
	v_cvt_pk_bf16_f32 v80, v80, v81
	v_mul_f32_e32 v81, v94, v84
	v_mul_f32_e32 v84, v95, v85
	v_mul_f32_e32 v85, 0xbfb8aa3b, v88
	v_mul_f32_e32 v81, v86, v81
	v_exp_f32_e32 v85, v85
	v_mul_f32_e32 v86, 0xbfb8aa3b, v89
	v_exp_f32_e32 v86, v86
	v_mul_f32_e32 v84, v87, v84
	v_cvt_pk_bf16_f32 v81, v81, v84
	v_add_f32_e32 v84, 1.0, v85
	v_rcp_f32_e32 v84, v84
	v_add_f32_e32 v85, 1.0, v86
	v_mul_f32_e32 v86, 0xbfb8aa3b, v90
	v_rcp_f32_e32 v85, v85
	v_exp_f32_e32 v86, v86
	v_mul_f32_e32 v84, v88, v84
	v_mul_f32_e32 v82, v82, v84
	v_mul_f32_e32 v84, v89, v85
	v_add_f32_e32 v85, 1.0, v86
	v_rcp_f32_e32 v85, v85
	v_mul_f32_e32 v86, 0xbfb8aa3b, v91
	v_exp_f32_e32 v86, v86
	v_mul_f32_e32 v83, v83, v84
	v_cvt_pk_bf16_f32 v82, v82, v83
	v_mul_f32_e32 v83, v90, v85
	v_fmamk_f32 v85, v160, 0x3a800000, v154
	v_rsq_f32_e32 v85, v85
	v_add_f32_e32 v84, 1.0, v86
	v_rcp_f32_e32 v84, v84
	v_mul_f32_e32 v83, v100, v83
	v_mul_f32_e32 v84, v91, v84
	v_mul_f32_e32 v84, v101, v84
	v_cvt_pk_bf16_f32 v83, v83, v84
	global_store_dwordx4 v[98:99], v[80:83], off
	s_nop 1
	v_or_b32_e32 v81, 48, v144
	s_nop 0
	s_nop 1
	s_nop 0
	v_mov_b32_e32 v80, v85
	v_pk_mul_f32 v[76:77], v[80:81], v[76:77] op_sel_hi:[0,1]
	v_mad_i64_i32 v[82:83], s[8:9], v81, s59, v[146:147]
	v_pk_mul_f32 v[78:79], v[80:81], v[78:79] op_sel_hi:[0,1]
	v_pk_mul_f32 v[74:75], v[80:81], v[74:75] op_sel_hi:[0,1]
	v_pk_mul_f32 v[72:73], v[80:81], v[72:73] op_sel_hi:[0,1]
	v_pk_mul_f32 v[70:71], v[80:81], v[70:71] op_sel_hi:[0,1]
	v_pk_mul_f32 v[68:69], v[80:81], v[68:69] op_sel_hi:[0,1]
	v_mul_f32_e32 v81, 0xbfb8aa3b, v76
	v_exp_f32_e32 v81, v81
	v_mul_f32_e32 v84, 0xbfb8aa3b, v77
	v_exp_f32_e32 v86, v84
	v_lshl_add_u64 v[82:83], v[82:83], 0, v[148:149]
	v_pk_mul_f32 v[84:85], v[80:81], v[66:67] op_sel_hi:[0,1]
	v_add_f32_e32 v66, 1.0, v81
	v_rcp_f32_e32 v81, v66
	v_add_f32_e32 v66, 1.0, v86
	v_rcp_f32_e32 v86, v66
	v_pk_mul_f32 v[66:67], v[80:81], v[64:65] op_sel_hi:[0,1]
	v_mul_f32_e32 v64, v76, v81
	v_mul_f32_e32 v64, v68, v64
	v_mul_f32_e32 v68, 0xbfb8aa3b, v78
	v_mul_f32_e32 v76, 0xbfb8aa3b, v79
	v_exp_f32_e32 v68, v68
	v_exp_f32_e32 v76, v76
	v_mul_f32_e32 v65, v77, v86
	v_mul_f32_e32 v65, v69, v65
	v_add_f32_e32 v68, 1.0, v68
	v_add_f32_e32 v69, 1.0, v76
	v_rcp_f32_e32 v68, v68
	v_rcp_f32_e32 v69, v69
	v_cvt_pk_bf16_f32 v64, v64, v65
	v_mul_f32_e32 v65, v78, v68
	v_mul_f32_e32 v68, v79, v69
	v_mul_f32_e32 v69, 0xbfb8aa3b, v72
	v_mul_f32_e32 v65, v70, v65
	v_exp_f32_e32 v69, v69
	v_mul_f32_e32 v70, 0xbfb8aa3b, v73
	v_exp_f32_e32 v70, v70
	v_mul_f32_e32 v68, v71, v68
	v_cvt_pk_bf16_f32 v65, v65, v68
	v_add_f32_e32 v68, 1.0, v69
	v_rcp_f32_e32 v68, v68
	v_add_f32_e32 v69, 1.0, v70
	v_mul_f32_e32 v70, 0xbfb8aa3b, v74
	v_rcp_f32_e32 v69, v69
	v_exp_f32_e32 v70, v70
	v_mul_f32_e32 v68, v72, v68
	v_mul_f32_e32 v66, v66, v68
	v_mul_f32_e32 v68, v73, v69
	v_add_f32_e32 v69, 1.0, v70
	v_rcp_f32_e32 v69, v69
	v_mul_f32_e32 v70, 0xbfb8aa3b, v75
	v_exp_f32_e32 v70, v70
	v_mul_f32_e32 v67, v67, v68
	v_cvt_pk_bf16_f32 v66, v66, v67
	v_mul_f32_e32 v67, v74, v69
	v_fmamk_f32 v69, v159, 0x3a800000, v154
	v_rsq_f32_e32 v69, v69
	v_add_f32_e32 v68, 1.0, v70
	v_rcp_f32_e32 v68, v68
	v_mul_f32_e32 v67, v84, v67
	v_mul_f32_e32 v68, v75, v68
	v_mul_f32_e32 v68, v85, v68
	v_cvt_pk_bf16_f32 v67, v67, v68
	global_store_dwordx4 v[82:83], v[64:67], off
	s_nop 1
	v_add_u32_e32 v65, 0x80, v144
	s_nop 0
	s_nop 1
	s_nop 0
	v_mov_b32_e32 v64, v69
	v_pk_mul_f32 v[60:61], v[64:65], v[60:61] op_sel_hi:[0,1]
	v_mad_i64_i32 v[66:67], s[8:9], v65, s59, v[146:147]
	v_pk_mul_f32 v[62:63], v[64:65], v[62:63] op_sel_hi:[0,1]
	v_pk_mul_f32 v[58:59], v[64:65], v[58:59] op_sel_hi:[0,1]
	v_pk_mul_f32 v[56:57], v[64:65], v[56:57] op_sel_hi:[0,1]
	v_pk_mul_f32 v[54:55], v[64:65], v[54:55] op_sel_hi:[0,1]
	v_pk_mul_f32 v[52:53], v[64:65], v[52:53] op_sel_hi:[0,1]
	v_mul_f32_e32 v65, 0xbfb8aa3b, v60
	v_exp_f32_e32 v65, v65
	v_mul_f32_e32 v68, 0xbfb8aa3b, v61
	v_exp_f32_e32 v70, v68
	v_lshl_add_u64 v[66:67], v[66:67], 0, v[148:149]
	v_pk_mul_f32 v[68:69], v[64:65], v[50:51] op_sel_hi:[0,1]
	v_add_f32_e32 v50, 1.0, v65
	v_rcp_f32_e32 v65, v50
	v_add_f32_e32 v50, 1.0, v70
	v_rcp_f32_e32 v70, v50
	v_pk_mul_f32 v[50:51], v[64:65], v[48:49] op_sel_hi:[0,1]
	v_mul_f32_e32 v48, v60, v65
	v_mul_f32_e32 v48, v52, v48
	v_mul_f32_e32 v52, 0xbfb8aa3b, v62
	v_mul_f32_e32 v60, 0xbfb8aa3b, v63
	v_exp_f32_e32 v52, v52
	v_exp_f32_e32 v60, v60
	v_mul_f32_e32 v49, v61, v70
	v_mul_f32_e32 v49, v53, v49
	v_add_f32_e32 v52, 1.0, v52
	v_add_f32_e32 v53, 1.0, v60
	v_rcp_f32_e32 v52, v52
	v_rcp_f32_e32 v53, v53
	v_cvt_pk_bf16_f32 v48, v48, v49
	v_mul_f32_e32 v49, v62, v52
	v_mul_f32_e32 v52, v63, v53
	v_mul_f32_e32 v53, 0xbfb8aa3b, v56
	v_mul_f32_e32 v49, v54, v49
	v_exp_f32_e32 v53, v53
	v_mul_f32_e32 v54, 0xbfb8aa3b, v57
	v_exp_f32_e32 v54, v54
	v_mul_f32_e32 v52, v55, v52
	v_cvt_pk_bf16_f32 v49, v49, v52
	v_add_f32_e32 v52, 1.0, v53
	v_rcp_f32_e32 v52, v52
	v_add_f32_e32 v53, 1.0, v54
	v_mul_f32_e32 v54, 0xbfb8aa3b, v58
	v_rcp_f32_e32 v53, v53
	v_exp_f32_e32 v54, v54
	v_mul_f32_e32 v52, v56, v52
	v_mul_f32_e32 v50, v50, v52
	v_mul_f32_e32 v52, v57, v53
	v_add_f32_e32 v53, 1.0, v54
	v_rcp_f32_e32 v53, v53
	v_mul_f32_e32 v54, 0xbfb8aa3b, v59
	v_exp_f32_e32 v54, v54
	v_mul_f32_e32 v51, v51, v52
	v_cvt_pk_bf16_f32 v50, v50, v51
	v_mul_f32_e32 v51, v58, v53
	v_fmamk_f32 v53, v158, 0x3a800000, v154
	v_rsq_f32_e32 v53, v53
	v_add_f32_e32 v52, 1.0, v54
	v_rcp_f32_e32 v52, v52
	v_mul_f32_e32 v51, v68, v51
	v_mul_f32_e32 v52, v59, v52
	v_mul_f32_e32 v52, v69, v52
	v_cvt_pk_bf16_f32 v51, v51, v52
	global_store_dwordx4 v[66:67], v[48:51], off
	s_nop 1
	v_add_u32_e32 v49, 0x90, v144
	s_nop 0
	s_nop 1
	s_nop 0
	v_mov_b32_e32 v48, v53
	v_pk_mul_f32 v[44:45], v[48:49], v[44:45] op_sel_hi:[0,1]
	v_mad_i64_i32 v[50:51], s[8:9], v49, s59, v[146:147]
	v_pk_mul_f32 v[46:47], v[48:49], v[46:47] op_sel_hi:[0,1]
	v_pk_mul_f32 v[42:43], v[48:49], v[42:43] op_sel_hi:[0,1]
	v_pk_mul_f32 v[40:41], v[48:49], v[40:41] op_sel_hi:[0,1]
	v_pk_mul_f32 v[38:39], v[48:49], v[38:39] op_sel_hi:[0,1]
	v_pk_mul_f32 v[36:37], v[48:49], v[36:37] op_sel_hi:[0,1]
	v_mul_f32_e32 v49, 0xbfb8aa3b, v44
	v_exp_f32_e32 v49, v49
	v_mul_f32_e32 v52, 0xbfb8aa3b, v45
	v_exp_f32_e32 v54, v52
	v_lshl_add_u64 v[50:51], v[50:51], 0, v[148:149]
	v_pk_mul_f32 v[52:53], v[48:49], v[34:35] op_sel_hi:[0,1]
	v_add_f32_e32 v34, 1.0, v49
	v_rcp_f32_e32 v49, v34
	v_add_f32_e32 v34, 1.0, v54
	v_rcp_f32_e32 v54, v34
	v_pk_mul_f32 v[34:35], v[48:49], v[32:33] op_sel_hi:[0,1]
	v_mul_f32_e32 v32, v44, v49
	v_mul_f32_e32 v32, v36, v32
	v_mul_f32_e32 v36, 0xbfb8aa3b, v46
	v_mul_f32_e32 v44, 0xbfb8aa3b, v47
	v_exp_f32_e32 v36, v36
	v_exp_f32_e32 v44, v44
	v_mul_f32_e32 v33, v45, v54
	v_mul_f32_e32 v33, v37, v33
	v_add_f32_e32 v36, 1.0, v36
	v_add_f32_e32 v37, 1.0, v44
	v_rcp_f32_e32 v36, v36
	v_rcp_f32_e32 v37, v37
	v_cvt_pk_bf16_f32 v32, v32, v33
	v_mul_f32_e32 v33, v46, v36
	v_mul_f32_e32 v36, v47, v37
	v_mul_f32_e32 v37, 0xbfb8aa3b, v40
	v_mul_f32_e32 v33, v38, v33
	v_exp_f32_e32 v37, v37
	v_mul_f32_e32 v38, 0xbfb8aa3b, v41
	v_exp_f32_e32 v38, v38
	v_mul_f32_e32 v36, v39, v36
	v_cvt_pk_bf16_f32 v33, v33, v36
	v_add_f32_e32 v36, 1.0, v37
	v_rcp_f32_e32 v36, v36
	v_add_f32_e32 v37, 1.0, v38
	v_mul_f32_e32 v38, 0xbfb8aa3b, v42
	v_rcp_f32_e32 v37, v37
	v_exp_f32_e32 v38, v38
	v_mul_f32_e32 v36, v40, v36
	v_mul_f32_e32 v34, v34, v36
	v_mul_f32_e32 v36, v41, v37
	v_add_f32_e32 v37, 1.0, v38
	v_rcp_f32_e32 v37, v37
	v_mul_f32_e32 v38, 0xbfb8aa3b, v43
	v_exp_f32_e32 v38, v38
	v_mul_f32_e32 v35, v35, v36
	v_cvt_pk_bf16_f32 v34, v34, v35
	v_mul_f32_e32 v35, v42, v37
	v_fmamk_f32 v37, v157, 0x3a800000, v154
	v_rsq_f32_e32 v37, v37
	v_add_f32_e32 v36, 1.0, v38
	v_rcp_f32_e32 v36, v36
	v_mul_f32_e32 v35, v52, v35
	v_mul_f32_e32 v36, v43, v36
	v_mul_f32_e32 v36, v53, v36
	v_cvt_pk_bf16_f32 v35, v35, v36
	global_store_dwordx4 v[50:51], v[32:35], off
	s_nop 1
	v_add_u32_e32 v33, 0xa0, v144
	s_nop 0
	s_nop 1
	s_nop 0
	v_mov_b32_e32 v32, v37
	v_pk_mul_f32 v[28:29], v[32:33], v[28:29] op_sel_hi:[0,1]
	v_mad_i64_i32 v[34:35], s[8:9], v33, s59, v[146:147]
	v_pk_mul_f32 v[30:31], v[32:33], v[30:31] op_sel_hi:[0,1]
	v_pk_mul_f32 v[26:27], v[32:33], v[26:27] op_sel_hi:[0,1]
	v_pk_mul_f32 v[24:25], v[32:33], v[24:25] op_sel_hi:[0,1]
	v_pk_mul_f32 v[22:23], v[32:33], v[22:23] op_sel_hi:[0,1]
	v_pk_mul_f32 v[20:21], v[32:33], v[20:21] op_sel_hi:[0,1]
	v_mul_f32_e32 v33, 0xbfb8aa3b, v28
	v_exp_f32_e32 v33, v33
	v_mul_f32_e32 v36, 0xbfb8aa3b, v29
	v_exp_f32_e32 v38, v36
	v_lshl_add_u64 v[34:35], v[34:35], 0, v[148:149]
	v_pk_mul_f32 v[36:37], v[32:33], v[18:19] op_sel_hi:[0,1]
	v_add_f32_e32 v18, 1.0, v33
	v_rcp_f32_e32 v33, v18
	v_add_f32_e32 v18, 1.0, v38
	v_rcp_f32_e32 v38, v18
	v_pk_mul_f32 v[18:19], v[32:33], v[16:17] op_sel_hi:[0,1]
	v_mul_f32_e32 v16, v28, v33
	v_mul_f32_e32 v16, v20, v16
	v_mul_f32_e32 v20, 0xbfb8aa3b, v30
	v_mul_f32_e32 v28, 0xbfb8aa3b, v31
	v_exp_f32_e32 v20, v20
	v_exp_f32_e32 v28, v28
	v_mul_f32_e32 v17, v29, v38
	v_mul_f32_e32 v17, v21, v17
	v_add_f32_e32 v20, 1.0, v20
	v_add_f32_e32 v21, 1.0, v28
	v_rcp_f32_e32 v20, v20
	v_rcp_f32_e32 v21, v21
	v_cvt_pk_bf16_f32 v16, v16, v17
	v_mul_f32_e32 v17, v30, v20
	v_mul_f32_e32 v20, v31, v21
	v_mul_f32_e32 v21, 0xbfb8aa3b, v24
	v_mul_f32_e32 v17, v22, v17
	v_exp_f32_e32 v21, v21
	v_mul_f32_e32 v22, 0xbfb8aa3b, v25
	v_exp_f32_e32 v22, v22
	v_mul_f32_e32 v20, v23, v20
	v_cvt_pk_bf16_f32 v17, v17, v20
	v_add_f32_e32 v20, 1.0, v21
	v_rcp_f32_e32 v20, v20
	v_add_f32_e32 v21, 1.0, v22
	v_mul_f32_e32 v22, 0xbfb8aa3b, v26
	v_rcp_f32_e32 v21, v21
	v_exp_f32_e32 v22, v22
	v_mul_f32_e32 v20, v24, v20
	v_mul_f32_e32 v18, v18, v20
	v_mul_f32_e32 v20, v25, v21
	v_add_f32_e32 v21, 1.0, v22
	v_rcp_f32_e32 v21, v21
	v_mul_f32_e32 v22, 0xbfb8aa3b, v27
	v_exp_f32_e32 v22, v22
	v_mul_f32_e32 v19, v19, v20
	v_cvt_pk_bf16_f32 v18, v18, v19
	v_mul_f32_e32 v19, v26, v21
	v_fmamk_f32 v21, v156, 0x3a800000, v154
	v_rsq_f32_e32 v21, v21
	v_add_f32_e32 v20, 1.0, v22
	v_rcp_f32_e32 v20, v20
	v_mul_f32_e32 v19, v36, v19
	v_mul_f32_e32 v20, v27, v20
	v_mul_f32_e32 v20, v37, v20
	v_cvt_pk_bf16_f32 v19, v19, v20
	global_store_dwordx4 v[34:35], v[16:19], off
	s_nop 1
	v_add_u32_e32 v17, 0xb0, v144
	s_nop 0
	s_nop 1
	s_nop 0
	v_mov_b32_e32 v16, v21
	v_pk_mul_f32 v[12:13], v[16:17], v[12:13] op_sel_hi:[0,1]
	v_mad_i64_i32 v[18:19], s[8:9], v17, s59, v[146:147]
	v_pk_mul_f32 v[14:15], v[16:17], v[14:15] op_sel_hi:[0,1]
	v_pk_mul_f32 v[10:11], v[16:17], v[10:11] op_sel_hi:[0,1]
	v_pk_mul_f32 v[8:9], v[16:17], v[8:9] op_sel_hi:[0,1]
	v_pk_mul_f32 v[6:7], v[16:17], v[6:7] op_sel_hi:[0,1]
	v_pk_mul_f32 v[4:5], v[16:17], v[4:5] op_sel_hi:[0,1]
	v_mul_f32_e32 v17, 0xbfb8aa3b, v12
	v_exp_f32_e32 v17, v17
	v_mul_f32_e32 v20, 0xbfb8aa3b, v13
	v_exp_f32_e32 v22, v20
	v_lshl_add_u64 v[18:19], v[18:19], 0, v[148:149]
	v_pk_mul_f32 v[20:21], v[16:17], v[2:3] op_sel_hi:[0,1]
	v_add_f32_e32 v2, 1.0, v17
	v_rcp_f32_e32 v17, v2
	v_add_f32_e32 v2, 1.0, v22
	v_rcp_f32_e32 v22, v2
	s_andn2_b64 vcc, exec, s[6:7]
	v_pk_mul_f32 v[2:3], v[16:17], v[0:1] op_sel_hi:[0,1]
	v_mul_f32_e32 v0, v12, v17
	v_mul_f32_e32 v0, v4, v0
	v_mul_f32_e32 v4, 0xbfb8aa3b, v14
	v_mul_f32_e32 v12, 0xbfb8aa3b, v15
	v_exp_f32_e32 v4, v4
	v_exp_f32_e32 v12, v12
	v_mul_f32_e32 v1, v13, v22
	v_mul_f32_e32 v1, v5, v1
	v_add_f32_e32 v4, 1.0, v4
	v_add_f32_e32 v5, 1.0, v12
	v_rcp_f32_e32 v4, v4
	v_rcp_f32_e32 v5, v5
	v_cvt_pk_bf16_f32 v0, v0, v1
	s_mov_b64 s[6:7], -1
	v_mul_f32_e32 v1, v14, v4
	v_mul_f32_e32 v4, v15, v5
	v_mul_f32_e32 v5, 0xbfb8aa3b, v8
	v_mul_f32_e32 v1, v6, v1
	v_exp_f32_e32 v5, v5
	v_mul_f32_e32 v6, 0xbfb8aa3b, v9
	v_exp_f32_e32 v6, v6
	v_mul_f32_e32 v4, v7, v4
	v_add_f32_e32 v5, 1.0, v5
	v_rcp_f32_e32 v5, v5
	v_add_f32_e32 v6, 1.0, v6
	v_rcp_f32_e32 v6, v6
	v_cvt_pk_bf16_f32 v1, v1, v4
	v_mul_f32_e32 v4, v8, v5
	v_mul_f32_e32 v5, 0xbfb8aa3b, v10
	v_mul_f32_e32 v2, v2, v4
	v_mul_f32_e32 v4, v9, v6
	v_exp_f32_e32 v5, v5
	v_mul_f32_e32 v6, 0xbfb8aa3b, v11
	v_exp_f32_e32 v6, v6
	v_mul_f32_e32 v3, v3, v4
	v_add_f32_e32 v4, 1.0, v5
	v_rcp_f32_e32 v4, v4
	v_add_f32_e32 v5, 1.0, v6
	v_rcp_f32_e32 v5, v5
	v_cvt_pk_bf16_f32 v2, v2, v3
	v_mul_f32_e32 v3, v10, v4
	v_mul_f32_e32 v3, v20, v3
	v_mul_f32_e32 v4, v11, v5
	v_mul_f32_e32 v4, v21, v4
	v_cvt_pk_bf16_f32 v3, v3, v4
	global_store_dwordx4 v[18:19], v[0:3], off
	s_cbranch_vccnz .LBB0_375
	s_andn2_b64 vcc, exec, s[10:11]
	s_cbranch_vccnz .LBB0_374
	s_barrier
	s_branch .LBB0_374

.LBB0_614:
	v_add_u32_e32 v152, s33, v175
	v_lshl_add_u64 v[132:133], v[152:153], 2, s[12:13]
	flat_load_dwordx4 v[140:143], v[132:133]
	flat_load_dwordx4 v[136:139], v[132:133] offset:16
	flat_load_dwordx4 v[128:131], v[132:133] offset:512
	v_lshlrev_b64 v[134:135], 10, v[162:163]
	v_lshl_add_u64 v[168:169], s[18:19], 0, v[134:135]
	flat_load_dwordx4 v[132:135], v[132:133] offset:528
	v_cndmask_b32_e32 v165, v192, v193, vcc
	v_sqrt_f32_e32 v163, v165
	v_lshlrev_b64 v[170:171], 1, v[152:153]
	v_lshl_add_u64 v[168:169], v[168:169], 0, v[170:171]
	v_add_u32_e32 v152, -1, v163
	v_add_u32_e32 v167, 1, v163
	v_fma_f32 v194, -v152, v163, v165
	v_fma_f32 v195, -v167, v163, v165
	v_cmp_ge_f32_e64 s[10:11], 0, v194
	s_nop 1
	v_cndmask_b32_e64 v152, v163, v152, s[10:11]
	v_cmp_lt_f32_e64 s[10:11], 0, v195
	s_nop 1
	v_cndmask_b32_e64 v152, v152, v167, s[10:11]
	v_mul_f32_e32 v163, 0x37800000, v152
	v_cndmask_b32_e32 v152, v152, v163, vcc
	v_cmp_class_f32_e32 vcc, v165, v178
	s_nop 1
	v_cndmask_b32_e32 v152, v152, v165, vcc
	v_div_scale_f32 v163, s[10:11], v152, v152, 1.0
	v_rcp_f32_e32 v165, v163
	v_div_scale_f32 v167, vcc, 1.0, v152, 1.0
	v_fma_f32 v194, -v163, v165, 1.0
	v_fmac_f32_e32 v165, v194, v165
	v_mul_f32_e32 v194, v167, v165
	v_fma_f32 v195, -v163, v194, v167
	v_fmac_f32_e32 v194, v195, v165
	v_fma_f32 v163, -v163, v194, v167
	v_div_fmas_f32 v163, v163, v165, v194
	v_div_fixup_f32 v152, v163, v152, 1.0
	s_waitcnt vmcnt(0) lgkmcnt(0)
	v_pk_fma_f32 v[194:195], v[126:127], v[152:153], v[142:143] op_sel_hi:[1,0,1]
	v_pk_fma_f32 v[196:197], v[124:125], v[152:153], v[140:141] op_sel_hi:[1,0,1]
	v_pk_fma_f32 v[198:199], v[122:123], v[152:153], v[138:139] op_sel_hi:[1,0,1]
	v_pk_fma_f32 v[200:201], v[120:121], v[152:153], v[136:137] op_sel_hi:[1,0,1]
	v_mul_f32_e64 v163, |v196|, s74
	v_mul_f32_e64 v165, |v197|, s74
	v_mul_f32_e64 v167, |v194|, s74
	v_mul_f32_e64 v206, |v195|, s74
	v_mul_f32_e64 v207, |v200|, s74
	v_mul_f32_e64 v208, |v201|, s74
	v_mul_f32_e64 v209, |v198|, s74
	v_mul_f32_e64 v210, |v199|, s74
	v_exp_f32_e32 v163, v163
	v_exp_f32_e32 v165, v165
	v_exp_f32_e32 v167, v167
	v_exp_f32_e32 v206, v206
	v_exp_f32_e32 v207, v207
	v_exp_f32_e32 v208, v208
	v_exp_f32_e32 v209, v209
	v_exp_f32_e32 v210, v210
	v_add_f32_e32 v163, 1.0, v163
	v_add_f32_e32 v165, 1.0, v165
	v_add_f32_e32 v167, 1.0, v167
	v_add_f32_e32 v211, 1.0, v206
	v_add_f32_e32 v212, 1.0, v207
	v_add_f32_e32 v213, 1.0, v208
	v_add_f32_e32 v214, 1.0, v209
	v_add_f32_e32 v215, 1.0, v210
	v_pk_fma_f32 v[204:205], v[116:117], v[152:153], v[128:129] op_sel_hi:[1,0,1]
	v_log_f32_e32 v206, v163
	v_log_f32_e32 v207, v165
	v_log_f32_e32 v208, v167
	v_log_f32_e32 v209, v211
	v_log_f32_e32 v210, v212
	v_log_f32_e32 v211, v213
	v_log_f32_e32 v212, v214
	v_log_f32_e32 v213, v215
	v_mul_f32_e64 v163, |v204|, s74
	v_exp_f32_e32 v163, v163
	v_mul_f32_e64 v165, |v205|, s74
	v_min_f32_e32 v196, 0, v196
	v_min_f32_e32 v197, 0, v197
	v_min_f32_e32 v194, 0, v194
	v_min_f32_e32 v195, 0, v195
	v_min_f32_e32 v200, 0, v200
	v_min_f32_e32 v201, 0, v201
	v_min_f32_e32 v198, 0, v198
	v_min_f32_e32 v199, 0, v199
	v_exp_f32_e32 v165, v165
	v_pk_fma_f32 v[196:197], v[206:207], s[26:27], v[196:197] op_sel_hi:[1,0,1] neg_lo:[1,0,0] neg_hi:[1,0,0]
	v_pk_fma_f32 v[194:195], v[208:209], s[26:27], v[194:195] op_sel_hi:[1,0,1] neg_lo:[1,0,0] neg_hi:[1,0,0]
	v_pk_fma_f32 v[200:201], v[210:211], s[26:27], v[200:201] op_sel_hi:[1,0,1] neg_lo:[1,0,0] neg_hi:[1,0,0]
	v_pk_fma_f32 v[198:199], v[212:213], s[26:27], v[198:199] op_sel_hi:[1,0,1] neg_lo:[1,0,0] neg_hi:[1,0,0]
	v_pk_mul_f32 v[196:197], v[196:197], s[28:29] op_sel_hi:[1,0]
	v_pk_mul_f32 v[206:207], v[194:195], s[28:29] op_sel_hi:[1,0]
	v_pk_mul_f32 v[200:201], v[200:201], s[28:29] op_sel_hi:[1,0]
	v_pk_mul_f32 v[198:199], v[198:199], s[28:29] op_sel_hi:[1,0]
	v_pk_fma_f32 v[202:203], v[118:119], v[152:153], v[130:131] op_sel_hi:[1,0,1]
	v_cvt_pk_f16_f32 v194, v196, v197
	v_cvt_pk_f16_f32 v195, v206, v207
	v_cvt_pk_f16_f32 v196, v200, v201
	v_cvt_pk_f16_f32 v197, v198, v199
	v_add_f32_e32 v163, 1.0, v163
	global_store_dwordx4 v[168:169], v[194:197], off
	v_pk_fma_f32 v[198:199], v[114:115], v[152:153], v[134:135] op_sel_hi:[1,0,1]
	v_min_f32_e32 v200, 0, v204
	v_log_f32_e32 v194, v163
	v_add_f32_e32 v163, 1.0, v165
	v_pk_fma_f32 v[196:197], v[112:113], v[152:153], v[132:133] op_sel_hi:[1,0,1]
	v_mul_f32_e64 v152, |v202|, s74
	v_log_f32_e32 v195, v163
	v_exp_f32_e32 v152, v152
	v_mul_f32_e64 v163, |v203|, s74
	v_exp_f32_e32 v163, v163
	v_min_f32_e32 v201, 0, v205
	v_add_f32_e32 v152, 1.0, v152
	v_pk_fma_f32 v[194:195], v[194:195], s[26:27], v[200:201] op_sel_hi:[1,0,1] neg_lo:[1,0,0] neg_hi:[1,0,0]
	v_log_f32_e32 v200, v152
	v_add_f32_e32 v152, 1.0, v163
	v_log_f32_e32 v201, v152
	v_mul_f32_e64 v152, |v196|, s74
	v_exp_f32_e32 v152, v152
	v_mul_f32_e64 v163, |v197|, s74
	v_exp_f32_e32 v163, v163
	v_min_f32_e32 v202, 0, v202
	v_min_f32_e32 v203, 0, v203
	v_add_f32_e32 v152, 1.0, v152
	v_pk_fma_f32 v[200:201], v[200:201], s[26:27], v[202:203] op_sel_hi:[1,0,1] neg_lo:[1,0,0] neg_hi:[1,0,0]
	v_log_f32_e32 v202, v152
	v_add_f32_e32 v152, 1.0, v163
	v_log_f32_e32 v203, v152
	v_mul_f32_e64 v152, |v198|, s74
	v_exp_f32_e32 v152, v152
	v_mul_f32_e64 v163, |v199|, s74
	v_exp_f32_e32 v163, v163
	v_pk_mul_f32 v[194:195], v[194:195], s[28:29] op_sel_hi:[1,0]
	v_pk_mul_f32 v[200:201], v[200:201], s[28:29] op_sel_hi:[1,0]
	v_add_f32_e32 v152, 1.0, v152
	v_cvt_pk_f16_f32 v194, v194, v195
	v_cvt_pk_f16_f32 v195, v200, v201
	v_log_f32_e32 v200, v152
	v_add_f32_e32 v152, 1.0, v163
	v_log_f32_e32 v201, v152
	v_cndmask_b32_e64 v152, v190, v191, s[8:9]
	v_sqrt_f32_e32 v163, v152
	v_min_f32_e32 v196, 0, v196
	v_min_f32_e32 v197, 0, v197
	v_min_f32_e32 v198, 0, v198
	v_add_u32_e32 v165, -1, v163
	v_fma_f32 v167, -v165, v163, v152
	v_cmp_ge_f32_e32 vcc, 0, v167
	v_add_u32_e32 v167, 1, v163
	v_min_f32_e32 v199, 0, v199
	v_cndmask_b32_e32 v165, v163, v165, vcc
	v_fma_f32 v163, -v167, v163, v152
	v_cmp_lt_f32_e32 vcc, 0, v163
	v_pk_fma_f32 v[196:197], v[202:203], s[26:27], v[196:197] op_sel_hi:[1,0,1] neg_lo:[1,0,0] neg_hi:[1,0,0]
	v_pk_fma_f32 v[198:199], v[200:201], s[26:27], v[198:199] op_sel_hi:[1,0,1] neg_lo:[1,0,0] neg_hi:[1,0,0]
	v_cndmask_b32_e32 v163, v165, v167, vcc
	v_mul_f32_e32 v165, 0x37800000, v163
	v_cndmask_b32_e64 v163, v163, v165, s[8:9]
	v_cmp_class_f32_e32 vcc, v152, v178
	v_pk_mul_f32 v[196:197], v[196:197], s[28:29] op_sel_hi:[1,0]
	v_pk_mul_f32 v[198:199], v[198:199], s[28:29] op_sel_hi:[1,0]
	v_cndmask_b32_e32 v152, v163, v152, vcc
	v_div_scale_f32 v163, s[8:9], v152, v152, 1.0
	v_rcp_f32_e32 v165, v163
	v_cvt_pk_f16_f32 v196, v196, v197
	v_cvt_pk_f16_f32 v197, v198, v199
	global_store_dwordx4 v[168:169], v[194:197], off offset:256
	v_fma_f32 v167, -v163, v165, 1.0
	v_fmac_f32_e32 v165, v167, v165
	v_div_scale_f32 v167, vcc, 1.0, v152, 1.0
	v_mul_f32_e32 v194, v167, v165
	v_fma_f32 v195, -v163, v194, v167
	v_fmac_f32_e32 v194, v195, v165
	v_fma_f32 v163, -v163, v194, v167
	v_ashrrev_i32_e32 v167, 31, v166
	v_div_fmas_f32 v163, v163, v165, v194
	v_lshlrev_b64 v[194:195], 10, v[166:167]
	v_div_fixup_f32 v152, v163, v152, 1.0
	v_lshl_add_u64 v[194:195], s[18:19], 0, v[194:195]
	v_lshl_add_u64 v[198:199], v[194:195], 0, v[170:171]
	v_pk_fma_f32 v[194:195], v[152:153], v[108:109], v[140:141] op_sel_hi:[0,1,1]
	v_mul_f32_e64 v163, |v194|, s74
	v_exp_f32_e32 v163, v163
	v_mul_f32_e64 v165, |v195|, s74
	v_exp_f32_e32 v165, v165
	v_pk_fma_f32 v[196:197], v[152:153], v[110:111], v[142:143] op_sel_hi:[0,1,1]
	v_add_f32_e32 v163, 1.0, v163
	v_log_f32_e32 v202, v163
	v_add_f32_e32 v163, 1.0, v165
	v_log_f32_e32 v203, v163
	v_mul_f32_e64 v163, |v196|, s74
	v_exp_f32_e32 v163, v163
	v_mul_f32_e64 v165, |v197|, s74
	v_exp_f32_e32 v165, v165
	v_min_f32_e32 v194, 0, v194
	v_min_f32_e32 v195, 0, v195
	v_add_f32_e32 v163, 1.0, v163
	v_pk_fma_f32 v[204:205], v[152:153], v[104:105], v[136:137] op_sel_hi:[0,1,1]
	v_pk_fma_f32 v[194:195], v[202:203], s[26:27], v[194:195] op_sel_hi:[1,0,1] neg_lo:[1,0,0] neg_hi:[1,0,0]
	v_log_f32_e32 v202, v163
	v_add_f32_e32 v163, 1.0, v165
	v_log_f32_e32 v203, v163
	v_mul_f32_e64 v163, |v204|, s74
	v_exp_f32_e32 v163, v163
	v_mul_f32_e64 v165, |v205|, s74
	v_exp_f32_e32 v165, v165
	v_min_f32_e32 v196, 0, v196
	v_min_f32_e32 v197, 0, v197
	v_add_f32_e32 v163, 1.0, v163
	v_pk_fma_f32 v[200:201], v[152:153], v[106:107], v[138:139] op_sel_hi:[0,1,1]
	v_pk_fma_f32 v[196:197], v[202:203], s[26:27], v[196:197] op_sel_hi:[1,0,1] neg_lo:[1,0,0] neg_hi:[1,0,0]
	v_log_f32_e32 v202, v163
	v_add_f32_e32 v163, 1.0, v165
	v_log_f32_e32 v203, v163
	v_mul_f32_e64 v163, |v200|, s74
	v_exp_f32_e32 v163, v163
	v_mul_f32_e64 v165, |v201|, s74
	v_exp_f32_e32 v165, v165
	v_pk_mul_f32 v[194:195], v[194:195], s[28:29] op_sel_hi:[1,0]
	v_pk_mul_f32 v[196:197], v[196:197], s[28:29] op_sel_hi:[1,0]
	v_cvt_pk_f16_f32 v194, v194, v195
	v_cvt_pk_f16_f32 v195, v196, v197
	v_min_f32_e32 v196, 0, v204
	v_min_f32_e32 v197, 0, v205
	v_add_f32_e32 v163, 1.0, v163
	v_pk_fma_f32 v[196:197], v[202:203], s[26:27], v[196:197] op_sel_hi:[1,0,1] neg_lo:[1,0,0] neg_hi:[1,0,0]
	v_log_f32_e32 v202, v163
	v_add_f32_e32 v163, 1.0, v165
	v_log_f32_e32 v203, v163
	v_min_f32_e32 v200, 0, v200
	v_min_f32_e32 v201, 0, v201
	v_pk_mul_f32 v[196:197], v[196:197], s[28:29] op_sel_hi:[1,0]
	v_pk_fma_f32 v[200:201], v[202:203], s[26:27], v[200:201] op_sel_hi:[1,0,1] neg_lo:[1,0,0] neg_hi:[1,0,0]
	v_cvt_pk_f16_f32 v196, v196, v197
	v_pk_mul_f32 v[200:201], v[200:201], s[28:29] op_sel_hi:[1,0]
	v_pk_fma_f32 v[204:205], v[152:153], v[96:97], v[132:133] op_sel_hi:[0,1,1]
	v_cvt_pk_f16_f32 v197, v200, v201
	global_store_dwordx4 v[198:199], v[194:197], off
	v_pk_fma_f32 v[200:201], v[152:153], v[98:99], v[134:135] op_sel_hi:[0,1,1]
	v_cmp_gt_f32_e32 vcc, s73, v189
	v_pk_fma_f32 v[194:195], v[152:153], v[100:101], v[128:129] op_sel_hi:[0,1,1]
	v_mul_f32_e64 v163, |v194|, s74
	v_exp_f32_e32 v163, v163
	v_mul_f32_e64 v165, |v195|, s74
	v_exp_f32_e32 v165, v165
	v_pk_fma_f32 v[196:197], v[152:153], v[102:103], v[130:131] op_sel_hi:[0,1,1]
	v_add_f32_e32 v163, 1.0, v163
	v_log_f32_e32 v202, v163
	v_add_f32_e32 v163, 1.0, v165
	v_mul_f32_e64 v152, |v196|, s74
	v_log_f32_e32 v203, v163
	v_exp_f32_e32 v152, v152
	v_mul_f32_e64 v163, |v197|, s74
	v_exp_f32_e32 v163, v163
	v_min_f32_e32 v194, 0, v194
	v_min_f32_e32 v195, 0, v195
	v_add_f32_e32 v152, 1.0, v152
	v_pk_fma_f32 v[194:195], v[202:203], s[26:27], v[194:195] op_sel_hi:[1,0,1] neg_lo:[1,0,0] neg_hi:[1,0,0]
	v_log_f32_e32 v202, v152
	v_add_f32_e32 v152, 1.0, v163
	v_log_f32_e32 v203, v152
	v_mul_f32_e64 v152, |v204|, s74
	v_exp_f32_e32 v152, v152
	v_mul_f32_e64 v163, |v205|, s74
	v_exp_f32_e32 v163, v163
	v_min_f32_e32 v196, 0, v196
	v_min_f32_e32 v197, 0, v197
	v_add_f32_e32 v152, 1.0, v152
	v_pk_fma_f32 v[196:197], v[202:203], s[26:27], v[196:197] op_sel_hi:[1,0,1] neg_lo:[1,0,0] neg_hi:[1,0,0]
	v_log_f32_e32 v202, v152
	v_add_f32_e32 v152, 1.0, v163
	v_log_f32_e32 v203, v152
	v_mul_f32_e64 v152, |v200|, s74
	v_exp_f32_e32 v152, v152
	v_mul_f32_e64 v163, |v201|, s74
	v_exp_f32_e32 v163, v163
	v_pk_mul_f32 v[194:195], v[194:195], s[28:29] op_sel_hi:[1,0]
	v_pk_mul_f32 v[196:197], v[196:197], s[28:29] op_sel_hi:[1,0]
	v_cvt_pk_f16_f32 v194, v194, v195
	v_cvt_pk_f16_f32 v195, v196, v197
	v_min_f32_e32 v196, 0, v204
	v_min_f32_e32 v197, 0, v205
	v_add_f32_e32 v152, 1.0, v152
	v_pk_fma_f32 v[196:197], v[202:203], s[26:27], v[196:197] op_sel_hi:[1,0,1] neg_lo:[1,0,0] neg_hi:[1,0,0]
	v_log_f32_e32 v202, v152
	v_add_f32_e32 v152, 1.0, v163
	v_log_f32_e32 v203, v152
	v_mul_f32_e32 v152, 0x4f800000, v189
	v_cndmask_b32_e32 v152, v189, v152, vcc
	v_sqrt_f32_e32 v163, v152
	v_min_f32_e32 v200, 0, v200
	v_min_f32_e32 v201, 0, v201
	v_pk_fma_f32 v[200:201], v[202:203], s[26:27], v[200:201] op_sel_hi:[1,0,1] neg_lo:[1,0,0] neg_hi:[1,0,0]
	v_add_u32_e32 v165, -1, v163
	v_fma_f32 v167, -v165, v163, v152
	v_cmp_ge_f32_e64 s[8:9], 0, v167
	v_add_u32_e32 v167, 1, v163
	v_pk_mul_f32 v[196:197], v[196:197], s[28:29] op_sel_hi:[1,0]
	v_cndmask_b32_e64 v165, v163, v165, s[8:9]
	v_fma_f32 v163, -v167, v163, v152
	v_cmp_lt_f32_e64 s[8:9], 0, v163
	v_pk_mul_f32 v[200:201], v[200:201], s[28:29] op_sel_hi:[1,0]
	v_cvt_pk_f16_f32 v196, v196, v197
	v_cndmask_b32_e64 v163, v165, v167, s[8:9]
	v_mul_f32_e32 v165, 0x37800000, v163
	v_cndmask_b32_e32 v163, v163, v165, vcc
	v_cmp_class_f32_e32 vcc, v152, v178
	v_cvt_pk_f16_f32 v197, v200, v201
	global_store_dwordx4 v[198:199], v[194:197], off offset:256
	v_cndmask_b32_e32 v152, v163, v152, vcc
	v_div_scale_f32 v163, s[8:9], v152, v152, 1.0
	v_rcp_f32_e32 v165, v163
	s_nop 0
	v_fma_f32 v167, -v163, v165, 1.0
	v_fmac_f32_e32 v165, v167, v165
	v_div_scale_f32 v167, vcc, 1.0, v152, 1.0
	v_mul_f32_e32 v194, v167, v165
	v_fma_f32 v195, -v163, v194, v167
	v_fmac_f32_e32 v194, v195, v165
	v_fma_f32 v163, -v163, v194, v167
	v_div_fmas_f32 v163, v163, v165, v194
	v_ashrrev_i32_e32 v165, 31, v164
	v_lshlrev_b64 v[194:195], 10, v[164:165]
	v_div_fixup_f32 v152, v163, v152, 1.0
	v_lshl_add_u64 v[194:195], s[18:19], 0, v[194:195]
	v_lshl_add_u64 v[198:199], v[194:195], 0, v[170:171]
	v_pk_fma_f32 v[194:195], v[152:153], v[92:93], v[140:141] op_sel_hi:[0,1,1]
	v_mul_f32_e64 v163, |v194|, s74
	v_exp_f32_e32 v163, v163
	v_mul_f32_e64 v165, |v195|, s74
	v_exp_f32_e32 v165, v165
	v_pk_fma_f32 v[196:197], v[152:153], v[94:95], v[142:143] op_sel_hi:[0,1,1]
	v_add_f32_e32 v163, 1.0, v163
	v_log_f32_e32 v202, v163
	v_add_f32_e32 v163, 1.0, v165
	v_log_f32_e32 v203, v163
	v_mul_f32_e64 v163, |v196|, s74
	v_exp_f32_e32 v163, v163
	v_mul_f32_e64 v165, |v197|, s74
	v_exp_f32_e32 v165, v165
	v_min_f32_e32 v194, 0, v194
	v_min_f32_e32 v195, 0, v195
	v_add_f32_e32 v163, 1.0, v163
	v_pk_fma_f32 v[204:205], v[152:153], v[88:89], v[136:137] op_sel_hi:[0,1,1]
	v_pk_fma_f32 v[194:195], v[202:203], s[26:27], v[194:195] op_sel_hi:[1,0,1] neg_lo:[1,0,0] neg_hi:[1,0,0]
	v_log_f32_e32 v202, v163
	v_add_f32_e32 v163, 1.0, v165
	v_log_f32_e32 v203, v163
	v_mul_f32_e64 v163, |v204|, s74
	v_exp_f32_e32 v163, v163
	v_mul_f32_e64 v165, |v205|, s74
	v_exp_f32_e32 v165, v165
	v_min_f32_e32 v196, 0, v196
	v_min_f32_e32 v197, 0, v197
	v_add_f32_e32 v163, 1.0, v163
	v_pk_fma_f32 v[200:201], v[152:153], v[90:91], v[138:139] op_sel_hi:[0,1,1]
	v_pk_fma_f32 v[196:197], v[202:203], s[26:27], v[196:197] op_sel_hi:[1,0,1] neg_lo:[1,0,0] neg_hi:[1,0,0]
	v_log_f32_e32 v202, v163
	v_add_f32_e32 v163, 1.0, v165
	v_log_f32_e32 v203, v163
	v_mul_f32_e64 v163, |v200|, s74
	v_exp_f32_e32 v163, v163
	v_mul_f32_e64 v165, |v201|, s74
	v_exp_f32_e32 v165, v165
	v_pk_mul_f32 v[194:195], v[194:195], s[28:29] op_sel_hi:[1,0]
	v_pk_mul_f32 v[196:197], v[196:197], s[28:29] op_sel_hi:[1,0]
	v_cvt_pk_f16_f32 v194, v194, v195
	v_cvt_pk_f16_f32 v195, v196, v197
	v_min_f32_e32 v196, 0, v204
	v_min_f32_e32 v197, 0, v205
	v_add_f32_e32 v163, 1.0, v163
	v_pk_fma_f32 v[196:197], v[202:203], s[26:27], v[196:197] op_sel_hi:[1,0,1] neg_lo:[1,0,0] neg_hi:[1,0,0]
	v_log_f32_e32 v202, v163
	v_add_f32_e32 v163, 1.0, v165
	v_log_f32_e32 v203, v163
	v_min_f32_e32 v200, 0, v200
	v_min_f32_e32 v201, 0, v201
	v_pk_mul_f32 v[196:197], v[196:197], s[28:29] op_sel_hi:[1,0]
	v_pk_fma_f32 v[200:201], v[202:203], s[26:27], v[200:201] op_sel_hi:[1,0,1] neg_lo:[1,0,0] neg_hi:[1,0,0]
	v_cvt_pk_f16_f32 v196, v196, v197
	v_pk_mul_f32 v[200:201], v[200:201], s[28:29] op_sel_hi:[1,0]
	v_pk_fma_f32 v[204:205], v[152:153], v[80:81], v[132:133] op_sel_hi:[0,1,1]
	v_cvt_pk_f16_f32 v197, v200, v201
	global_store_dwordx4 v[198:199], v[194:197], off
	v_pk_fma_f32 v[200:201], v[152:153], v[82:83], v[134:135] op_sel_hi:[0,1,1]
	s_nop 0
	v_pk_fma_f32 v[194:195], v[152:153], v[84:85], v[128:129] op_sel_hi:[0,1,1]
	v_mul_f32_e64 v163, |v194|, s74
	v_exp_f32_e32 v163, v163
	v_mul_f32_e64 v165, |v195|, s74
	v_exp_f32_e32 v165, v165
	v_pk_fma_f32 v[196:197], v[152:153], v[86:87], v[130:131] op_sel_hi:[0,1,1]
	v_add_f32_e32 v163, 1.0, v163
	v_log_f32_e32 v202, v163
	v_add_f32_e32 v163, 1.0, v165
	v_mul_f32_e64 v152, |v196|, s74
	v_log_f32_e32 v203, v163
	v_exp_f32_e32 v152, v152
	v_mul_f32_e64 v163, |v197|, s74
	v_exp_f32_e32 v163, v163
	v_min_f32_e32 v194, 0, v194
	v_min_f32_e32 v195, 0, v195
	v_add_f32_e32 v152, 1.0, v152
	v_pk_fma_f32 v[194:195], v[202:203], s[26:27], v[194:195] op_sel_hi:[1,0,1] neg_lo:[1,0,0] neg_hi:[1,0,0]
	v_log_f32_e32 v202, v152
	v_add_f32_e32 v152, 1.0, v163
	v_log_f32_e32 v203, v152
	v_mul_f32_e64 v152, |v204|, s74
	v_exp_f32_e32 v152, v152
	v_mul_f32_e64 v163, |v205|, s74
	v_exp_f32_e32 v163, v163
	v_min_f32_e32 v196, 0, v196
	v_min_f32_e32 v197, 0, v197
	v_add_f32_e32 v152, 1.0, v152
	v_pk_fma_f32 v[196:197], v[202:203], s[26:27], v[196:197] op_sel_hi:[1,0,1] neg_lo:[1,0,0] neg_hi:[1,0,0]
	v_log_f32_e32 v202, v152
	v_add_f32_e32 v152, 1.0, v163
	v_log_f32_e32 v203, v152
	v_mul_f32_e64 v152, |v200|, s74
	v_exp_f32_e32 v152, v152
	v_mul_f32_e64 v163, |v201|, s74
	v_exp_f32_e32 v163, v163
	v_pk_mul_f32 v[194:195], v[194:195], s[28:29] op_sel_hi:[1,0]
	v_pk_mul_f32 v[196:197], v[196:197], s[28:29] op_sel_hi:[1,0]
	v_cvt_pk_f16_f32 v194, v194, v195
	v_cvt_pk_f16_f32 v195, v196, v197
	v_min_f32_e32 v196, 0, v204
	v_min_f32_e32 v197, 0, v205
	v_add_f32_e32 v152, 1.0, v152
	v_pk_fma_f32 v[196:197], v[202:203], s[26:27], v[196:197] op_sel_hi:[1,0,1] neg_lo:[1,0,0] neg_hi:[1,0,0]
	v_log_f32_e32 v202, v152
	v_add_f32_e32 v152, 1.0, v163
	v_log_f32_e32 v203, v152
	v_fmamk_f32 v152, v185, 0x3a800000, v177
	v_mul_f32_e32 v163, 0x4f800000, v152
	v_cmp_gt_f32_e32 vcc, s73, v152
	v_min_f32_e32 v200, 0, v200
	v_min_f32_e32 v201, 0, v201
	v_cndmask_b32_e32 v152, v152, v163, vcc
	v_sqrt_f32_e32 v163, v152
	v_pk_fma_f32 v[200:201], v[202:203], s[26:27], v[200:201] op_sel_hi:[1,0,1] neg_lo:[1,0,0] neg_hi:[1,0,0]
	v_pk_mul_f32 v[196:197], v[196:197], s[28:29] op_sel_hi:[1,0]
	v_pk_mul_f32 v[200:201], v[200:201], s[28:29] op_sel_hi:[1,0]
	v_add_u32_e32 v165, -1, v163
	v_fma_f32 v167, -v165, v163, v152
	v_cmp_ge_f32_e64 s[8:9], 0, v167
	v_add_u32_e32 v167, 1, v163
	v_cvt_pk_f16_f32 v196, v196, v197
	v_cndmask_b32_e64 v165, v163, v165, s[8:9]
	v_fma_f32 v163, -v167, v163, v152
	v_cmp_lt_f32_e64 s[8:9], 0, v163
	v_cvt_pk_f16_f32 v197, v200, v201
	global_store_dwordx4 v[198:199], v[194:197], off offset:256
	v_cndmask_b32_e64 v163, v165, v167, s[8:9]
	v_mul_f32_e32 v165, 0x37800000, v163
	v_cndmask_b32_e32 v163, v163, v165, vcc
	v_cmp_class_f32_e32 vcc, v152, v178
	v_or_b32_e32 v194, 48, v162
	s_nop 0
	v_cndmask_b32_e32 v152, v163, v152, vcc
	v_div_scale_f32 v163, s[8:9], v152, v152, 1.0
	v_rcp_f32_e32 v165, v163
	s_nop 0
	v_fma_f32 v167, -v163, v165, 1.0
	v_fmac_f32_e32 v165, v167, v165
	v_div_scale_f32 v167, vcc, 1.0, v152, 1.0
	v_mul_f32_e32 v195, v167, v165
	v_fma_f32 v196, -v163, v195, v167
	v_fmac_f32_e32 v195, v196, v165
	v_fma_f32 v163, -v163, v195, v167
	v_div_fmas_f32 v163, v163, v165, v195
	v_ashrrev_i32_e32 v195, 31, v194
	v_lshlrev_b64 v[194:195], 10, v[194:195]
	v_div_fixup_f32 v152, v163, v152, 1.0
	v_lshl_add_u64 v[194:195], s[18:19], 0, v[194:195]
	v_lshl_add_u64 v[170:171], v[194:195], 0, v[170:171]
	v_pk_fma_f32 v[194:195], v[152:153], v[76:77], v[140:141] op_sel_hi:[0,1,1]
	v_mul_f32_e64 v163, |v194|, s74
	v_exp_f32_e32 v163, v163
	v_mul_f32_e64 v165, |v195|, s74
	v_exp_f32_e32 v165, v165
	v_pk_fma_f32 v[196:197], v[152:153], v[78:79], v[142:143] op_sel_hi:[0,1,1]
	v_add_f32_e32 v163, 1.0, v163
	v_log_f32_e32 v200, v163
	v_add_f32_e32 v163, 1.0, v165
	v_log_f32_e32 v201, v163
	v_mul_f32_e64 v163, |v196|, s74
	v_exp_f32_e32 v163, v163
	v_mul_f32_e64 v165, |v197|, s74
	v_exp_f32_e32 v165, v165
	v_min_f32_e32 v194, 0, v194
	v_min_f32_e32 v195, 0, v195
	v_add_f32_e32 v163, 1.0, v163
	v_pk_fma_f32 v[202:203], v[152:153], v[72:73], v[136:137] op_sel_hi:[0,1,1]
	v_pk_fma_f32 v[194:195], v[200:201], s[26:27], v[194:195] op_sel_hi:[1,0,1] neg_lo:[1,0,0] neg_hi:[1,0,0]
	v_log_f32_e32 v200, v163
	v_add_f32_e32 v163, 1.0, v165
	v_log_f32_e32 v201, v163
	v_mul_f32_e64 v163, |v202|, s74
	v_exp_f32_e32 v163, v163
	v_mul_f32_e64 v165, |v203|, s74
	v_exp_f32_e32 v165, v165
	v_min_f32_e32 v196, 0, v196
	v_min_f32_e32 v197, 0, v197
	v_add_f32_e32 v163, 1.0, v163
	v_pk_fma_f32 v[198:199], v[152:153], v[74:75], v[138:139] op_sel_hi:[0,1,1]
	v_pk_fma_f32 v[196:197], v[200:201], s[26:27], v[196:197] op_sel_hi:[1,0,1] neg_lo:[1,0,0] neg_hi:[1,0,0]
	v_log_f32_e32 v200, v163
	v_add_f32_e32 v163, 1.0, v165
	v_log_f32_e32 v201, v163
	v_mul_f32_e64 v163, |v198|, s74
	v_exp_f32_e32 v163, v163
	v_mul_f32_e64 v165, |v199|, s74
	v_exp_f32_e32 v165, v165
	v_pk_mul_f32 v[194:195], v[194:195], s[28:29] op_sel_hi:[1,0]
	v_pk_mul_f32 v[196:197], v[196:197], s[28:29] op_sel_hi:[1,0]
	v_cvt_pk_f16_f32 v194, v194, v195
	v_cvt_pk_f16_f32 v195, v196, v197
	v_min_f32_e32 v196, 0, v202
	v_min_f32_e32 v197, 0, v203
	v_add_f32_e32 v163, 1.0, v163
	v_pk_fma_f32 v[196:197], v[200:201], s[26:27], v[196:197] op_sel_hi:[1,0,1] neg_lo:[1,0,0] neg_hi:[1,0,0]
	v_log_f32_e32 v200, v163
	v_add_f32_e32 v163, 1.0, v165
	v_log_f32_e32 v201, v163
	v_min_f32_e32 v198, 0, v198
	v_min_f32_e32 v199, 0, v199
	v_pk_mul_f32 v[196:197], v[196:197], s[28:29] op_sel_hi:[1,0]
	v_pk_fma_f32 v[198:199], v[200:201], s[26:27], v[198:199] op_sel_hi:[1,0,1] neg_lo:[1,0,0] neg_hi:[1,0,0]
	v_cvt_pk_f16_f32 v196, v196, v197
	v_pk_mul_f32 v[198:199], v[198:199], s[28:29] op_sel_hi:[1,0]
	v_pk_fma_f32 v[202:203], v[152:153], v[64:65], v[132:133] op_sel_hi:[0,1,1]
	v_cvt_pk_f16_f32 v197, v198, v199
	global_store_dwordx4 v[170:171], v[194:197], off
	v_pk_fma_f32 v[198:199], v[152:153], v[66:67], v[134:135] op_sel_hi:[0,1,1]
	s_nop 0
	v_pk_fma_f32 v[194:195], v[152:153], v[68:69], v[128:129] op_sel_hi:[0,1,1]
	v_mul_f32_e64 v163, |v194|, s74
	v_exp_f32_e32 v163, v163
	v_mul_f32_e64 v165, |v195|, s74
	v_exp_f32_e32 v165, v165
	v_pk_fma_f32 v[196:197], v[152:153], v[70:71], v[130:131] op_sel_hi:[0,1,1]
	v_add_f32_e32 v163, 1.0, v163
	v_log_f32_e32 v200, v163
	v_add_f32_e32 v163, 1.0, v165
	v_mul_f32_e64 v152, |v196|, s74
	v_log_f32_e32 v201, v163
	v_exp_f32_e32 v152, v152
	v_mul_f32_e64 v163, |v197|, s74
	v_exp_f32_e32 v163, v163
	v_min_f32_e32 v194, 0, v194
	v_min_f32_e32 v195, 0, v195
	v_add_f32_e32 v152, 1.0, v152
	v_pk_fma_f32 v[194:195], v[200:201], s[26:27], v[194:195] op_sel_hi:[1,0,1] neg_lo:[1,0,0] neg_hi:[1,0,0]
	v_log_f32_e32 v200, v152
	v_add_f32_e32 v152, 1.0, v163
	v_log_f32_e32 v201, v152
	v_mul_f32_e64 v152, |v202|, s74
	v_exp_f32_e32 v152, v152
	v_mul_f32_e64 v163, |v203|, s74
	v_exp_f32_e32 v163, v163
	v_min_f32_e32 v196, 0, v196
	v_min_f32_e32 v197, 0, v197
	v_add_f32_e32 v152, 1.0, v152
	v_pk_fma_f32 v[196:197], v[200:201], s[26:27], v[196:197] op_sel_hi:[1,0,1] neg_lo:[1,0,0] neg_hi:[1,0,0]
	v_log_f32_e32 v200, v152
	v_add_f32_e32 v152, 1.0, v163
	v_log_f32_e32 v201, v152
	v_mul_f32_e64 v152, |v198|, s74
	v_exp_f32_e32 v152, v152
	v_mul_f32_e64 v163, |v199|, s74
	v_exp_f32_e32 v163, v163
	v_pk_mul_f32 v[194:195], v[194:195], s[28:29] op_sel_hi:[1,0]
	v_pk_mul_f32 v[196:197], v[196:197], s[28:29] op_sel_hi:[1,0]
	v_cvt_pk_f16_f32 v194, v194, v195
	v_cvt_pk_f16_f32 v195, v196, v197
	v_min_f32_e32 v196, 0, v202
	v_min_f32_e32 v197, 0, v203
	v_add_f32_e32 v152, 1.0, v152
	v_pk_fma_f32 v[196:197], v[200:201], s[26:27], v[196:197] op_sel_hi:[1,0,1] neg_lo:[1,0,0] neg_hi:[1,0,0]
	v_log_f32_e32 v200, v152
	v_add_f32_e32 v152, 1.0, v163
	v_log_f32_e32 v201, v152
	v_fmamk_f32 v152, v184, 0x3a800000, v177
	v_mul_f32_e32 v163, 0x4f800000, v152
	v_cmp_gt_f32_e32 vcc, s73, v152
	v_min_f32_e32 v198, 0, v198
	v_min_f32_e32 v199, 0, v199
	v_cndmask_b32_e32 v152, v152, v163, vcc
	v_sqrt_f32_e32 v163, v152
	v_pk_fma_f32 v[198:199], v[200:201], s[26:27], v[198:199] op_sel_hi:[1,0,1] neg_lo:[1,0,0] neg_hi:[1,0,0]
	v_pk_mul_f32 v[196:197], v[196:197], s[28:29] op_sel_hi:[1,0]
	v_pk_mul_f32 v[198:199], v[198:199], s[28:29] op_sel_hi:[1,0]
	v_add_u32_e32 v165, -1, v163
	v_fma_f32 v167, -v165, v163, v152
	v_cmp_ge_f32_e64 s[8:9], 0, v167
	v_add_u32_e32 v167, 1, v163
	v_cvt_pk_f16_f32 v196, v196, v197
	v_cndmask_b32_e64 v165, v163, v165, s[8:9]
	v_fma_f32 v163, -v167, v163, v152
	v_cmp_lt_f32_e64 s[8:9], 0, v163
	v_cvt_pk_f16_f32 v197, v198, v199
	global_store_dwordx4 v[170:171], v[194:197], off offset:256
	v_cndmask_b32_e64 v163, v165, v167, s[8:9]
	v_mul_f32_e32 v165, 0x37800000, v163
	v_cndmask_b32_e32 v163, v163, v165, vcc
	v_cmp_class_f32_e32 vcc, v152, v178
	s_nop 1
	v_cndmask_b32_e32 v152, v163, v152, vcc
	v_div_scale_f32 v163, s[8:9], v152, v152, 1.0
	v_rcp_f32_e32 v165, v163
	s_nop 0
	v_fma_f32 v167, -v163, v165, 1.0
	v_fmac_f32_e32 v165, v167, v165
	v_div_scale_f32 v167, vcc, 1.0, v152, 1.0
	v_mul_f32_e32 v170, v167, v165
	v_fma_f32 v171, -v163, v170, v167
	v_fmac_f32_e32 v170, v171, v165
	v_fma_f32 v163, -v163, v170, v167
	v_div_fmas_f32 v163, v163, v165, v170
	v_div_fixup_f32 v152, v163, v152, 1.0
	v_pk_fma_f32 v[194:195], v[152:153], v[60:61], v[140:141] op_sel_hi:[0,1,1]
	v_mul_f32_e64 v163, |v194|, s74
	v_exp_f32_e32 v163, v163
	v_mul_f32_e64 v165, |v195|, s74
	v_exp_f32_e32 v165, v165
	v_pk_fma_f32 v[196:197], v[152:153], v[62:63], v[142:143] op_sel_hi:[0,1,1]
	v_add_f32_e32 v163, 1.0, v163
	v_log_f32_e32 v200, v163
	v_add_f32_e32 v163, 1.0, v165
	v_log_f32_e32 v201, v163
	v_mul_f32_e64 v163, |v196|, s74
	v_exp_f32_e32 v163, v163
	v_mul_f32_e64 v165, |v197|, s74
	v_exp_f32_e32 v165, v165
	v_min_f32_e32 v194, 0, v194
	v_min_f32_e32 v195, 0, v195
	v_add_f32_e32 v163, 1.0, v163
	v_pk_fma_f32 v[202:203], v[152:153], v[56:57], v[136:137] op_sel_hi:[0,1,1]
	v_pk_fma_f32 v[194:195], v[200:201], s[26:27], v[194:195] op_sel_hi:[1,0,1] neg_lo:[1,0,0] neg_hi:[1,0,0]
	v_log_f32_e32 v200, v163
	v_add_f32_e32 v163, 1.0, v165
	v_log_f32_e32 v201, v163
	v_mul_f32_e64 v163, |v202|, s74
	v_exp_f32_e32 v163, v163
	v_mul_f32_e64 v165, |v203|, s74
	v_exp_f32_e32 v165, v165
	v_min_f32_e32 v196, 0, v196
	v_min_f32_e32 v197, 0, v197
	v_add_f32_e32 v163, 1.0, v163
	v_pk_fma_f32 v[198:199], v[152:153], v[58:59], v[138:139] op_sel_hi:[0,1,1]
	v_pk_fma_f32 v[196:197], v[200:201], s[26:27], v[196:197] op_sel_hi:[1,0,1] neg_lo:[1,0,0] neg_hi:[1,0,0]
	v_log_f32_e32 v200, v163
	v_add_f32_e32 v163, 1.0, v165
	v_log_f32_e32 v201, v163
	v_mul_f32_e64 v163, |v198|, s74
	v_exp_f32_e32 v163, v163
	v_mul_f32_e64 v165, |v199|, s74
	v_exp_f32_e32 v165, v165
	v_pk_mul_f32 v[194:195], v[194:195], s[28:29] op_sel_hi:[1,0]
	v_pk_mul_f32 v[196:197], v[196:197], s[28:29] op_sel_hi:[1,0]
	v_cvt_pk_f16_f32 v194, v194, v195
	v_cvt_pk_f16_f32 v195, v196, v197
	v_min_f32_e32 v196, 0, v202
	v_min_f32_e32 v197, 0, v203
	v_add_f32_e32 v163, 1.0, v163
	v_pk_fma_f32 v[196:197], v[200:201], s[26:27], v[196:197] op_sel_hi:[1,0,1] neg_lo:[1,0,0] neg_hi:[1,0,0]
	v_log_f32_e32 v200, v163
	v_add_f32_e32 v163, 1.0, v165
	v_log_f32_e32 v201, v163
	v_min_f32_e32 v198, 0, v198
	v_min_f32_e32 v199, 0, v199
	v_pk_mul_f32 v[196:197], v[196:197], s[28:29] op_sel_hi:[1,0]
	v_pk_fma_f32 v[198:199], v[200:201], s[26:27], v[198:199] op_sel_hi:[1,0,1] neg_lo:[1,0,0] neg_hi:[1,0,0]
	v_cvt_pk_f16_f32 v196, v196, v197
	v_pk_mul_f32 v[198:199], v[198:199], s[28:29] op_sel_hi:[1,0]
	v_pk_fma_f32 v[202:203], v[152:153], v[48:49], v[132:133] op_sel_hi:[0,1,1]
	v_cvt_pk_f16_f32 v197, v198, v199
	v_add_co_u32_e32 v198, vcc, s75, v168
	v_lshl_add_u64 v[170:171], v[168:169], 0, s[30:31]
	s_nop 0
	v_addc_co_u32_e32 v199, vcc, 0, v169, vcc
	global_store_dwordx4 v[198:199], v[194:197], off
	v_pk_fma_f32 v[198:199], v[152:153], v[50:51], v[134:135] op_sel_hi:[0,1,1]
	s_nop 0
	v_pk_fma_f32 v[194:195], v[152:153], v[52:53], v[128:129] op_sel_hi:[0,1,1]
	v_mul_f32_e64 v163, |v194|, s74
	v_exp_f32_e32 v163, v163
	v_mul_f32_e64 v165, |v195|, s74
	v_exp_f32_e32 v165, v165
	v_pk_fma_f32 v[196:197], v[152:153], v[54:55], v[130:131] op_sel_hi:[0,1,1]
	v_add_f32_e32 v163, 1.0, v163
	v_log_f32_e32 v200, v163
	v_add_f32_e32 v163, 1.0, v165
	v_mul_f32_e64 v152, |v196|, s74
	v_log_f32_e32 v201, v163
	v_exp_f32_e32 v152, v152
	v_mul_f32_e64 v163, |v197|, s74
	v_exp_f32_e32 v163, v163
	v_min_f32_e32 v194, 0, v194
	v_min_f32_e32 v195, 0, v195
	v_add_f32_e32 v152, 1.0, v152
	v_pk_fma_f32 v[194:195], v[200:201], s[26:27], v[194:195] op_sel_hi:[1,0,1] neg_lo:[1,0,0] neg_hi:[1,0,0]
	v_log_f32_e32 v200, v152
	v_add_f32_e32 v152, 1.0, v163
	v_log_f32_e32 v201, v152
	v_mul_f32_e64 v152, |v202|, s74
	v_exp_f32_e32 v152, v152
	v_mul_f32_e64 v163, |v203|, s74
	v_exp_f32_e32 v163, v163
	v_min_f32_e32 v196, 0, v196
	v_min_f32_e32 v197, 0, v197
	v_add_f32_e32 v152, 1.0, v152
	v_pk_fma_f32 v[196:197], v[200:201], s[26:27], v[196:197] op_sel_hi:[1,0,1] neg_lo:[1,0,0] neg_hi:[1,0,0]
	v_log_f32_e32 v200, v152
	v_add_f32_e32 v152, 1.0, v163
	v_log_f32_e32 v201, v152
	v_mul_f32_e64 v152, |v198|, s74
	v_exp_f32_e32 v152, v152
	v_mul_f32_e64 v163, |v199|, s74
	v_exp_f32_e32 v163, v163
	v_pk_mul_f32 v[194:195], v[194:195], s[28:29] op_sel_hi:[1,0]
	v_pk_mul_f32 v[196:197], v[196:197], s[28:29] op_sel_hi:[1,0]
	v_cvt_pk_f16_f32 v194, v194, v195
	v_cvt_pk_f16_f32 v195, v196, v197
	v_min_f32_e32 v196, 0, v202
	v_min_f32_e32 v197, 0, v203
	v_add_f32_e32 v152, 1.0, v152
	v_pk_fma_f32 v[196:197], v[200:201], s[26:27], v[196:197] op_sel_hi:[1,0,1] neg_lo:[1,0,0] neg_hi:[1,0,0]
	v_log_f32_e32 v200, v152
	v_add_f32_e32 v152, 1.0, v163
	v_log_f32_e32 v201, v152
	v_fmamk_f32 v152, v183, 0x3a800000, v177
	v_mul_f32_e32 v163, 0x4f800000, v152
	v_cmp_gt_f32_e32 vcc, s73, v152
	v_min_f32_e32 v198, 0, v198
	v_min_f32_e32 v199, 0, v199
	v_cndmask_b32_e32 v152, v152, v163, vcc
	v_sqrt_f32_e32 v163, v152
	v_pk_fma_f32 v[198:199], v[200:201], s[26:27], v[198:199] op_sel_hi:[1,0,1] neg_lo:[1,0,0] neg_hi:[1,0,0]
	v_pk_mul_f32 v[196:197], v[196:197], s[28:29] op_sel_hi:[1,0]
	v_pk_mul_f32 v[198:199], v[198:199], s[28:29] op_sel_hi:[1,0]
	v_add_u32_e32 v165, -1, v163
	v_fma_f32 v167, -v165, v163, v152
	v_cmp_ge_f32_e64 s[8:9], 0, v167
	v_add_u32_e32 v167, 1, v163
	v_cvt_pk_f16_f32 v196, v196, v197
	v_cndmask_b32_e64 v165, v163, v165, s[8:9]
	v_fma_f32 v163, -v167, v163, v152
	v_cmp_lt_f32_e64 s[8:9], 0, v163
	v_cvt_pk_f16_f32 v197, v198, v199
	global_store_dwordx4 v[170:171], v[194:197], off offset:256
	v_cndmask_b32_e64 v163, v165, v167, s[8:9]
	v_mul_f32_e32 v165, 0x37800000, v163
	v_cndmask_b32_e32 v163, v163, v165, vcc
	v_cmp_class_f32_e32 vcc, v152, v178
	s_nop 1
	v_cndmask_b32_e32 v152, v163, v152, vcc
	v_div_scale_f32 v163, s[8:9], v152, v152, 1.0
	v_rcp_f32_e32 v165, v163
	s_nop 0
	v_fma_f32 v167, -v163, v165, 1.0
	v_fmac_f32_e32 v165, v167, v165
	v_div_scale_f32 v167, vcc, 1.0, v152, 1.0
	v_mul_f32_e32 v170, v167, v165
	v_fma_f32 v171, -v163, v170, v167
	v_fmac_f32_e32 v170, v171, v165
	v_fma_f32 v163, -v163, v170, v167
	v_div_fmas_f32 v163, v163, v165, v170
	v_div_fixup_f32 v152, v163, v152, 1.0
	v_pk_fma_f32 v[194:195], v[152:153], v[44:45], v[140:141] op_sel_hi:[0,1,1]
	v_mul_f32_e64 v163, |v194|, s74
	v_exp_f32_e32 v163, v163
	v_mul_f32_e64 v165, |v195|, s74
	v_exp_f32_e32 v165, v165
	v_pk_fma_f32 v[196:197], v[152:153], v[46:47], v[142:143] op_sel_hi:[0,1,1]
	v_add_f32_e32 v163, 1.0, v163
	v_log_f32_e32 v200, v163
	v_add_f32_e32 v163, 1.0, v165
	v_log_f32_e32 v201, v163
	v_mul_f32_e64 v163, |v196|, s74
	v_exp_f32_e32 v163, v163
	v_mul_f32_e64 v165, |v197|, s74
	v_exp_f32_e32 v165, v165
	v_min_f32_e32 v194, 0, v194
	v_min_f32_e32 v195, 0, v195
	v_add_f32_e32 v163, 1.0, v163
	v_pk_fma_f32 v[202:203], v[152:153], v[40:41], v[136:137] op_sel_hi:[0,1,1]
	v_pk_fma_f32 v[194:195], v[200:201], s[26:27], v[194:195] op_sel_hi:[1,0,1] neg_lo:[1,0,0] neg_hi:[1,0,0]
	v_log_f32_e32 v200, v163
	v_add_f32_e32 v163, 1.0, v165
	v_log_f32_e32 v201, v163
	v_mul_f32_e64 v163, |v202|, s74
	v_exp_f32_e32 v163, v163
	v_mul_f32_e64 v165, |v203|, s74
	v_exp_f32_e32 v165, v165
	v_min_f32_e32 v196, 0, v196
	v_min_f32_e32 v197, 0, v197
	v_add_f32_e32 v163, 1.0, v163
	v_pk_fma_f32 v[198:199], v[152:153], v[42:43], v[138:139] op_sel_hi:[0,1,1]
	v_pk_fma_f32 v[196:197], v[200:201], s[26:27], v[196:197] op_sel_hi:[1,0,1] neg_lo:[1,0,0] neg_hi:[1,0,0]
	v_log_f32_e32 v200, v163
	v_add_f32_e32 v163, 1.0, v165
	v_log_f32_e32 v201, v163
	v_mul_f32_e64 v163, |v198|, s74
	v_exp_f32_e32 v163, v163
	v_mul_f32_e64 v165, |v199|, s74
	v_exp_f32_e32 v165, v165
	v_pk_mul_f32 v[194:195], v[194:195], s[28:29] op_sel_hi:[1,0]
	v_pk_mul_f32 v[196:197], v[196:197], s[28:29] op_sel_hi:[1,0]
	v_cvt_pk_f16_f32 v194, v194, v195
	v_cvt_pk_f16_f32 v195, v196, v197
	v_min_f32_e32 v196, 0, v202
	v_min_f32_e32 v197, 0, v203
	v_add_f32_e32 v163, 1.0, v163
	v_pk_fma_f32 v[196:197], v[200:201], s[26:27], v[196:197] op_sel_hi:[1,0,1] neg_lo:[1,0,0] neg_hi:[1,0,0]
	v_log_f32_e32 v200, v163
	v_add_f32_e32 v163, 1.0, v165
	v_log_f32_e32 v201, v163
	v_min_f32_e32 v198, 0, v198
	v_min_f32_e32 v199, 0, v199
	v_pk_mul_f32 v[196:197], v[196:197], s[28:29] op_sel_hi:[1,0]
	v_pk_fma_f32 v[198:199], v[200:201], s[26:27], v[198:199] op_sel_hi:[1,0,1] neg_lo:[1,0,0] neg_hi:[1,0,0]
	v_cvt_pk_f16_f32 v196, v196, v197
	v_pk_mul_f32 v[198:199], v[198:199], s[28:29] op_sel_hi:[1,0]
	v_pk_fma_f32 v[202:203], v[152:153], v[32:33], v[132:133] op_sel_hi:[0,1,1]
	v_cvt_pk_f16_f32 v197, v198, v199
	v_add_co_u32_e32 v198, vcc, s78, v168
	v_lshl_add_u64 v[170:171], v[168:169], 0, s[34:35]
	s_nop 0
	v_addc_co_u32_e32 v199, vcc, 0, v169, vcc
	global_store_dwordx4 v[198:199], v[194:197], off
	v_pk_fma_f32 v[198:199], v[152:153], v[34:35], v[134:135] op_sel_hi:[0,1,1]
	s_nop 0
	v_pk_fma_f32 v[194:195], v[152:153], v[36:37], v[128:129] op_sel_hi:[0,1,1]
	v_mul_f32_e64 v163, |v194|, s74
	v_exp_f32_e32 v163, v163
	v_mul_f32_e64 v165, |v195|, s74
	v_exp_f32_e32 v165, v165
	v_pk_fma_f32 v[196:197], v[152:153], v[38:39], v[130:131] op_sel_hi:[0,1,1]
	v_add_f32_e32 v163, 1.0, v163
	v_log_f32_e32 v200, v163
	v_add_f32_e32 v163, 1.0, v165
	v_mul_f32_e64 v152, |v196|, s74
	v_log_f32_e32 v201, v163
	v_exp_f32_e32 v152, v152
	v_mul_f32_e64 v163, |v197|, s74
	v_exp_f32_e32 v163, v163
	v_min_f32_e32 v194, 0, v194
	v_min_f32_e32 v195, 0, v195
	v_add_f32_e32 v152, 1.0, v152
	v_pk_fma_f32 v[194:195], v[200:201], s[26:27], v[194:195] op_sel_hi:[1,0,1] neg_lo:[1,0,0] neg_hi:[1,0,0]
	v_log_f32_e32 v200, v152
	v_add_f32_e32 v152, 1.0, v163
	v_log_f32_e32 v201, v152
	v_mul_f32_e64 v152, |v202|, s74
	v_exp_f32_e32 v152, v152
	v_mul_f32_e64 v163, |v203|, s74
	v_exp_f32_e32 v163, v163
	v_min_f32_e32 v196, 0, v196
	v_min_f32_e32 v197, 0, v197
	v_add_f32_e32 v152, 1.0, v152
	v_pk_fma_f32 v[196:197], v[200:201], s[26:27], v[196:197] op_sel_hi:[1,0,1] neg_lo:[1,0,0] neg_hi:[1,0,0]
	v_log_f32_e32 v200, v152
	v_add_f32_e32 v152, 1.0, v163
	v_log_f32_e32 v201, v152
	v_mul_f32_e64 v152, |v198|, s74
	v_exp_f32_e32 v152, v152
	v_mul_f32_e64 v163, |v199|, s74
	v_exp_f32_e32 v163, v163
	v_pk_mul_f32 v[194:195], v[194:195], s[28:29] op_sel_hi:[1,0]
	v_pk_mul_f32 v[196:197], v[196:197], s[28:29] op_sel_hi:[1,0]
	v_cvt_pk_f16_f32 v194, v194, v195
	v_cvt_pk_f16_f32 v195, v196, v197
	v_min_f32_e32 v196, 0, v202
	v_min_f32_e32 v197, 0, v203
	v_add_f32_e32 v152, 1.0, v152
	v_pk_fma_f32 v[196:197], v[200:201], s[26:27], v[196:197] op_sel_hi:[1,0,1] neg_lo:[1,0,0] neg_hi:[1,0,0]
	v_log_f32_e32 v200, v152
	v_add_f32_e32 v152, 1.0, v163
	v_log_f32_e32 v201, v152
	v_fmamk_f32 v152, v181, 0x3a800000, v177
	v_mul_f32_e32 v163, 0x4f800000, v152
	v_cmp_gt_f32_e32 vcc, s73, v152
	v_min_f32_e32 v198, 0, v198
	v_min_f32_e32 v199, 0, v199
	v_cndmask_b32_e32 v152, v152, v163, vcc
	v_sqrt_f32_e32 v163, v152
	v_pk_fma_f32 v[198:199], v[200:201], s[26:27], v[198:199] op_sel_hi:[1,0,1] neg_lo:[1,0,0] neg_hi:[1,0,0]
	v_pk_mul_f32 v[196:197], v[196:197], s[28:29] op_sel_hi:[1,0]
	v_pk_mul_f32 v[198:199], v[198:199], s[28:29] op_sel_hi:[1,0]
	v_add_u32_e32 v165, -1, v163
	v_fma_f32 v167, -v165, v163, v152
	v_cmp_ge_f32_e64 s[8:9], 0, v167
	v_add_u32_e32 v167, 1, v163
	v_cvt_pk_f16_f32 v196, v196, v197
	v_cndmask_b32_e64 v165, v163, v165, s[8:9]
	v_fma_f32 v163, -v167, v163, v152
	v_cmp_lt_f32_e64 s[8:9], 0, v163
	v_cvt_pk_f16_f32 v197, v198, v199
	global_store_dwordx4 v[170:171], v[194:197], off offset:256
	v_cndmask_b32_e64 v163, v165, v167, s[8:9]
	v_mul_f32_e32 v165, 0x37800000, v163
	v_cndmask_b32_e32 v163, v163, v165, vcc
	v_cmp_class_f32_e32 vcc, v152, v178
	s_nop 1
	v_cndmask_b32_e32 v152, v163, v152, vcc
	v_div_scale_f32 v163, s[8:9], v152, v152, 1.0
	v_rcp_f32_e32 v165, v163
	s_nop 0
	v_fma_f32 v167, -v163, v165, 1.0
	v_fmac_f32_e32 v165, v167, v165
	v_div_scale_f32 v167, vcc, 1.0, v152, 1.0
	v_mul_f32_e32 v170, v167, v165
	v_fma_f32 v171, -v163, v170, v167
	v_fmac_f32_e32 v170, v171, v165
	v_fma_f32 v163, -v163, v170, v167
	v_div_fmas_f32 v163, v163, v165, v170
	v_div_fixup_f32 v152, v163, v152, 1.0
	v_pk_fma_f32 v[194:195], v[152:153], v[28:29], v[140:141] op_sel_hi:[0,1,1]
	v_mul_f32_e64 v163, |v194|, s74
	v_exp_f32_e32 v163, v163
	v_mul_f32_e64 v165, |v195|, s74
	v_exp_f32_e32 v165, v165
	v_pk_fma_f32 v[196:197], v[152:153], v[30:31], v[142:143] op_sel_hi:[0,1,1]
	v_add_f32_e32 v163, 1.0, v163
	v_log_f32_e32 v200, v163
	v_add_f32_e32 v163, 1.0, v165
	v_log_f32_e32 v201, v163
	v_mul_f32_e64 v163, |v196|, s74
	v_exp_f32_e32 v163, v163
	v_mul_f32_e64 v165, |v197|, s74
	v_exp_f32_e32 v165, v165
	v_min_f32_e32 v194, 0, v194
	v_min_f32_e32 v195, 0, v195
	v_add_f32_e32 v163, 1.0, v163
	v_pk_fma_f32 v[202:203], v[152:153], v[24:25], v[136:137] op_sel_hi:[0,1,1]
	v_pk_fma_f32 v[194:195], v[200:201], s[26:27], v[194:195] op_sel_hi:[1,0,1] neg_lo:[1,0,0] neg_hi:[1,0,0]
	v_log_f32_e32 v200, v163
	v_add_f32_e32 v163, 1.0, v165
	v_log_f32_e32 v201, v163
	v_mul_f32_e64 v163, |v202|, s74
	v_exp_f32_e32 v163, v163
	v_mul_f32_e64 v165, |v203|, s74
	v_exp_f32_e32 v165, v165
	v_min_f32_e32 v196, 0, v196
	v_min_f32_e32 v197, 0, v197
	v_add_f32_e32 v163, 1.0, v163
	v_pk_fma_f32 v[198:199], v[152:153], v[26:27], v[138:139] op_sel_hi:[0,1,1]
	v_pk_fma_f32 v[196:197], v[200:201], s[26:27], v[196:197] op_sel_hi:[1,0,1] neg_lo:[1,0,0] neg_hi:[1,0,0]
	v_log_f32_e32 v200, v163
	v_add_f32_e32 v163, 1.0, v165
	v_log_f32_e32 v201, v163
	v_mul_f32_e64 v163, |v198|, s74
	v_exp_f32_e32 v163, v163
	v_mul_f32_e64 v165, |v199|, s74
	v_exp_f32_e32 v165, v165
	v_pk_mul_f32 v[194:195], v[194:195], s[28:29] op_sel_hi:[1,0]
	v_pk_mul_f32 v[196:197], v[196:197], s[28:29] op_sel_hi:[1,0]
	v_cvt_pk_f16_f32 v194, v194, v195
	v_cvt_pk_f16_f32 v195, v196, v197
	v_min_f32_e32 v196, 0, v202
	v_min_f32_e32 v197, 0, v203
	v_add_f32_e32 v163, 1.0, v163
	v_pk_fma_f32 v[196:197], v[200:201], s[26:27], v[196:197] op_sel_hi:[1,0,1] neg_lo:[1,0,0] neg_hi:[1,0,0]
	v_log_f32_e32 v200, v163
	v_add_f32_e32 v163, 1.0, v165
	v_log_f32_e32 v201, v163
	v_min_f32_e32 v198, 0, v198
	v_min_f32_e32 v199, 0, v199
	v_pk_mul_f32 v[196:197], v[196:197], s[28:29] op_sel_hi:[1,0]
	v_pk_fma_f32 v[198:199], v[200:201], s[26:27], v[198:199] op_sel_hi:[1,0,1] neg_lo:[1,0,0] neg_hi:[1,0,0]
	v_cvt_pk_f16_f32 v196, v196, v197
	v_pk_mul_f32 v[198:199], v[198:199], s[28:29] op_sel_hi:[1,0]
	v_pk_fma_f32 v[202:203], v[152:153], v[16:17], v[132:133] op_sel_hi:[0,1,1]
	v_cvt_pk_f16_f32 v197, v198, v199
	v_add_co_u32_e32 v198, vcc, s81, v168
	v_lshl_add_u64 v[170:171], v[168:169], 0, s[36:37]
	s_nop 0
	v_addc_co_u32_e32 v199, vcc, 0, v169, vcc
	global_store_dwordx4 v[198:199], v[194:197], off
	v_pk_fma_f32 v[198:199], v[152:153], v[18:19], v[134:135] op_sel_hi:[0,1,1]
	s_nop 0
	v_pk_fma_f32 v[194:195], v[152:153], v[20:21], v[128:129] op_sel_hi:[0,1,1]
	v_mul_f32_e64 v163, |v194|, s74
	v_exp_f32_e32 v163, v163
	v_mul_f32_e64 v165, |v195|, s74
	v_exp_f32_e32 v165, v165
	v_pk_fma_f32 v[196:197], v[152:153], v[22:23], v[130:131] op_sel_hi:[0,1,1]
	v_add_f32_e32 v163, 1.0, v163
	v_log_f32_e32 v200, v163
	v_add_f32_e32 v163, 1.0, v165
	v_mul_f32_e64 v152, |v196|, s74
	v_log_f32_e32 v201, v163
	v_exp_f32_e32 v152, v152
	v_mul_f32_e64 v163, |v197|, s74
	v_exp_f32_e32 v163, v163
	v_min_f32_e32 v194, 0, v194
	v_min_f32_e32 v195, 0, v195
	v_add_f32_e32 v152, 1.0, v152
	v_pk_fma_f32 v[194:195], v[200:201], s[26:27], v[194:195] op_sel_hi:[1,0,1] neg_lo:[1,0,0] neg_hi:[1,0,0]
	v_log_f32_e32 v200, v152
	v_add_f32_e32 v152, 1.0, v163
	v_log_f32_e32 v201, v152
	v_mul_f32_e64 v152, |v202|, s74
	v_exp_f32_e32 v152, v152
	v_mul_f32_e64 v163, |v203|, s74
	v_exp_f32_e32 v163, v163
	v_min_f32_e32 v196, 0, v196
	v_min_f32_e32 v197, 0, v197
	v_add_f32_e32 v152, 1.0, v152
	v_pk_fma_f32 v[196:197], v[200:201], s[26:27], v[196:197] op_sel_hi:[1,0,1] neg_lo:[1,0,0] neg_hi:[1,0,0]
	v_log_f32_e32 v200, v152
	v_add_f32_e32 v152, 1.0, v163
	v_log_f32_e32 v201, v152
	v_mul_f32_e64 v152, |v198|, s74
	v_exp_f32_e32 v152, v152
	v_mul_f32_e64 v163, |v199|, s74
	v_exp_f32_e32 v163, v163
	v_pk_mul_f32 v[194:195], v[194:195], s[28:29] op_sel_hi:[1,0]
	v_pk_mul_f32 v[196:197], v[196:197], s[28:29] op_sel_hi:[1,0]
	v_cvt_pk_f16_f32 v194, v194, v195
	v_cvt_pk_f16_f32 v195, v196, v197
	v_min_f32_e32 v196, 0, v202
	v_min_f32_e32 v197, 0, v203
	v_add_f32_e32 v152, 1.0, v152
	v_pk_fma_f32 v[196:197], v[200:201], s[26:27], v[196:197] op_sel_hi:[1,0,1] neg_lo:[1,0,0] neg_hi:[1,0,0]
	v_log_f32_e32 v200, v152
	v_add_f32_e32 v152, 1.0, v163
	v_log_f32_e32 v201, v152
	v_fmamk_f32 v152, v179, 0x3a800000, v177
	v_mul_f32_e32 v163, 0x4f800000, v152
	v_cmp_gt_f32_e32 vcc, s73, v152
	v_min_f32_e32 v198, 0, v198
	v_min_f32_e32 v199, 0, v199
	v_cndmask_b32_e32 v152, v152, v163, vcc
	v_sqrt_f32_e32 v163, v152
	v_pk_fma_f32 v[198:199], v[200:201], s[26:27], v[198:199] op_sel_hi:[1,0,1] neg_lo:[1,0,0] neg_hi:[1,0,0]
	v_pk_mul_f32 v[196:197], v[196:197], s[28:29] op_sel_hi:[1,0]
	v_pk_mul_f32 v[198:199], v[198:199], s[28:29] op_sel_hi:[1,0]
	v_add_u32_e32 v165, -1, v163
	v_fma_f32 v167, -v165, v163, v152
	v_cmp_ge_f32_e64 s[8:9], 0, v167
	v_add_u32_e32 v167, 1, v163
	v_cvt_pk_f16_f32 v196, v196, v197
	v_cndmask_b32_e64 v165, v163, v165, s[8:9]
	v_fma_f32 v163, -v167, v163, v152
	v_cmp_lt_f32_e64 s[8:9], 0, v163
	v_cvt_pk_f16_f32 v197, v198, v199
	global_store_dwordx4 v[170:171], v[194:197], off offset:256
	v_cndmask_b32_e64 v163, v165, v167, s[8:9]
	v_mul_f32_e32 v165, 0x37800000, v163
	v_cndmask_b32_e32 v163, v163, v165, vcc
	v_cmp_class_f32_e32 vcc, v152, v178
	s_nop 1
	v_cndmask_b32_e32 v152, v163, v152, vcc
	v_div_scale_f32 v163, s[8:9], v152, v152, 1.0
	v_rcp_f32_e32 v165, v163
	s_nop 0
	v_fma_f32 v167, -v163, v165, 1.0
	v_fmac_f32_e32 v165, v167, v165
	v_div_scale_f32 v167, vcc, 1.0, v152, 1.0
	v_mul_f32_e32 v170, v167, v165
	v_fma_f32 v171, -v163, v170, v167
	v_fmac_f32_e32 v170, v171, v165
	v_fma_f32 v163, -v163, v170, v167
	v_div_fmas_f32 v163, v163, v165, v170
	v_div_fixup_f32 v152, v163, v152, 1.0
	v_pk_fma_f32 v[140:141], v[152:153], v[12:13], v[140:141] op_sel_hi:[0,1,1]
	v_mul_f32_e64 v163, |v140|, s74
	v_mul_f32_e64 v165, |v141|, s74
	v_exp_f32_e32 v163, v163
	v_exp_f32_e32 v165, v165
	v_pk_fma_f32 v[194:195], v[152:153], v[10:11], v[138:139] op_sel_hi:[0,1,1]
	v_pk_fma_f32 v[142:143], v[152:153], v[14:15], v[142:143] op_sel_hi:[0,1,1]
	v_add_f32_e32 v138, 1.0, v163
	v_add_f32_e32 v139, 1.0, v165
	v_log_f32_e32 v138, v138
	v_log_f32_e32 v139, v139
	v_pk_fma_f32 v[196:197], v[152:153], v[8:9], v[136:137] op_sel_hi:[0,1,1]
	v_min_f32_e32 v136, 0, v140
	v_min_f32_e32 v137, 0, v141
	v_pk_fma_f32 v[136:137], v[138:139], s[26:27], v[136:137] op_sel_hi:[1,0,1] neg_lo:[1,0,0] neg_hi:[1,0,0]
	v_mul_f32_e64 v138, |v142|, s74
	v_mul_f32_e64 v139, |v143|, s74
	v_exp_f32_e32 v138, v138
	v_exp_f32_e32 v139, v139
	v_pk_mul_f32 v[136:137], v[136:137], s[28:29] op_sel_hi:[1,0]
	v_min_f32_e32 v140, 0, v142
	v_add_f32_e32 v138, 1.0, v138
	v_add_f32_e32 v139, 1.0, v139
	v_log_f32_e32 v138, v138
	v_log_f32_e32 v139, v139
	v_cvt_pk_f16_f32 v136, v136, v137
	v_min_f32_e32 v141, 0, v143
	v_mul_f32_e64 v137, |v196|, s74
	v_pk_fma_f32 v[138:139], v[138:139], s[26:27], v[140:141] op_sel_hi:[1,0,1] neg_lo:[1,0,0] neg_hi:[1,0,0]
	v_exp_f32_e32 v137, v137
	v_mul_f32_e64 v140, |v197|, s74
	v_exp_f32_e32 v141, v140
	v_pk_mul_f32 v[138:139], v[138:139], s[28:29] op_sel_hi:[1,0]
	v_add_f32_e32 v137, 1.0, v137
	v_log_f32_e32 v140, v137
	v_add_f32_e32 v137, 1.0, v141
	v_log_f32_e32 v141, v137
	v_cvt_pk_f16_f32 v137, v138, v139
	v_min_f32_e32 v138, 0, v196
	v_min_f32_e32 v139, 0, v197
	v_pk_fma_f32 v[138:139], v[140:141], s[26:27], v[138:139] op_sel_hi:[1,0,1] neg_lo:[1,0,0] neg_hi:[1,0,0]
	v_mul_f32_e64 v140, |v194|, s74
	v_mul_f32_e64 v141, |v195|, s74
	v_exp_f32_e32 v140, v140
	v_exp_f32_e32 v141, v141
	v_min_f32_e32 v142, 0, v194
	v_min_f32_e32 v143, 0, v195
	v_add_f32_e32 v140, 1.0, v140
	v_add_f32_e32 v141, 1.0, v141
	v_log_f32_e32 v140, v140
	v_log_f32_e32 v141, v141
	v_pk_mul_f32 v[138:139], v[138:139], s[28:29] op_sel_hi:[1,0]
	v_pk_fma_f32 v[128:129], v[152:153], v[4:5], v[128:129] op_sel_hi:[0,1,1]
	v_cvt_pk_f16_f32 v138, v138, v139
	v_pk_fma_f32 v[140:141], v[140:141], s[26:27], v[142:143] op_sel_hi:[1,0,1] neg_lo:[1,0,0] neg_hi:[1,0,0]
	v_pk_fma_f32 v[130:131], v[152:153], v[6:7], v[130:131] op_sel_hi:[0,1,1]
	v_pk_mul_f32 v[140:141], v[140:141], s[28:29] op_sel_hi:[1,0]
	v_pk_fma_f32 v[132:133], v[152:153], v[0:1], v[132:133] op_sel_hi:[0,1,1]
	v_cvt_pk_f16_f32 v139, v140, v141
	v_add_co_u32_e32 v140, vcc, s82, v168
	v_pk_fma_f32 v[134:135], v[152:153], v[2:3], v[134:135] op_sel_hi:[0,1,1]
	s_nop 0
	v_addc_co_u32_e32 v141, vcc, 0, v169, vcc
	global_store_dwordx4 v[140:141], v[136:139], off
	v_lshl_add_u64 v[170:171], v[168:169], 0, s[38:39]
	s_nop 0
	v_mul_f32_e64 v136, |v128|, s74
	v_mul_f32_e64 v137, |v129|, s74
	v_exp_f32_e32 v136, v136
	v_exp_f32_e32 v137, v137
	v_min_f32_e32 v128, 0, v128
	v_min_f32_e32 v129, 0, v129
	v_add_f32_e32 v136, 1.0, v136
	v_add_f32_e32 v137, 1.0, v137
	v_log_f32_e32 v136, v136
	v_log_f32_e32 v137, v137
	s_nop 0
	v_pk_fma_f32 v[128:129], v[136:137], s[26:27], v[128:129] op_sel_hi:[1,0,1] neg_lo:[1,0,0] neg_hi:[1,0,0]
	v_mul_f32_e64 v136, |v130|, s74
	v_mul_f32_e64 v137, |v131|, s74
	v_exp_f32_e32 v136, v136
	v_exp_f32_e32 v137, v137
	v_pk_mul_f32 v[128:129], v[128:129], s[28:29] op_sel_hi:[1,0]
	v_min_f32_e32 v130, 0, v130
	v_add_f32_e32 v136, 1.0, v136
	v_add_f32_e32 v137, 1.0, v137
	v_log_f32_e32 v136, v136
	v_log_f32_e32 v137, v137
	v_cvt_pk_f16_f32 v128, v128, v129
	v_min_f32_e32 v131, 0, v131
	v_mul_f32_e64 v129, |v132|, s74
	v_pk_fma_f32 v[130:131], v[136:137], s[26:27], v[130:131] op_sel_hi:[1,0,1] neg_lo:[1,0,0] neg_hi:[1,0,0]
	v_exp_f32_e32 v129, v129
	v_mul_f32_e64 v136, |v133|, s74
	v_exp_f32_e32 v137, v136
	v_pk_mul_f32 v[130:131], v[130:131], s[28:29] op_sel_hi:[1,0]
	v_add_f32_e32 v129, 1.0, v129
	v_log_f32_e32 v136, v129
	v_add_f32_e32 v129, 1.0, v137
	v_log_f32_e32 v137, v129
	v_cvt_pk_f16_f32 v129, v130, v131
	v_min_f32_e32 v130, 0, v132
	v_min_f32_e32 v131, 0, v133
	v_mul_f32_e64 v132, |v134|, s74
	v_mul_f32_e64 v133, |v135|, s74
	v_exp_f32_e32 v132, v132
	v_exp_f32_e32 v133, v133
	v_min_f32_e32 v134, 0, v134
	v_min_f32_e32 v135, 0, v135
	v_add_f32_e32 v132, 1.0, v132
	v_add_f32_e32 v133, 1.0, v133
	v_log_f32_e32 v132, v132
	v_log_f32_e32 v133, v133
	v_pk_fma_f32 v[130:131], v[136:137], s[26:27], v[130:131] op_sel_hi:[1,0,1] neg_lo:[1,0,0] neg_hi:[1,0,0]
	v_pk_fma_f32 v[132:133], v[132:133], s[26:27], v[134:135] op_sel_hi:[1,0,1] neg_lo:[1,0,0] neg_hi:[1,0,0]
	v_pk_mul_f32 v[130:131], v[130:131], s[28:29] op_sel_hi:[1,0]
	v_pk_mul_f32 v[132:133], v[132:133], s[28:29] op_sel_hi:[1,0]
	v_cvt_pk_f16_f32 v130, v130, v131
	v_cvt_pk_f16_f32 v131, v132, v133
	global_store_dwordx4 v[170:171], v[128:131], off offset:256
	s_cbranch_execnz .LBB0_613
.LBB0_615:
	v_cmp_gt_f32_e32 vcc, s73, v192
	s_nop 1
	v_cndmask_b32_e32 v128, v192, v193, vcc
	v_sqrt_f32_e32 v129, v128
	s_nop 0
	v_add_u32_e32 v130, -1, v129
	v_fma_f32 v132, -v130, v129, v128
	v_add_u32_e32 v131, 1, v129
	v_cmp_ge_f32_e64 s[8:9], 0, v132
	s_nop 1
	v_cndmask_b32_e64 v130, v129, v130, s[8:9]
	v_fma_f32 v129, -v131, v129, v128
	v_cmp_lt_f32_e64 s[8:9], 0, v129
	s_nop 1
	v_cndmask_b32_e64 v129, v130, v131, s[8:9]
	v_mul_f32_e32 v130, 0x37800000, v129
	v_cndmask_b32_e32 v129, v129, v130, vcc
	v_cmp_class_f32_e32 vcc, v128, v178
	v_or_b32_e32 v130, s33, v174
	v_ashrrev_i32_e32 v131, 31, v130
	v_cndmask_b32_e32 v128, v129, v128, vcc
	v_div_scale_f32 v129, s[8:9], v128, v128, 1.0
	v_rcp_f32_e32 v132, v129
	v_lshlrev_b64 v[130:131], 1, v[130:131]
	v_fma_f32 v133, -v129, v132, 1.0
	v_fmac_f32_e32 v132, v133, v132
	v_div_scale_f32 v133, vcc, 1.0, v128, 1.0
	v_mul_f32_e32 v134, v133, v132
	v_fma_f32 v135, -v129, v134, v133
	v_fmac_f32_e32 v134, v135, v132
	v_fma_f32 v129, -v129, v134, v133
	v_div_fmas_f32 v129, v129, v132, v134
	v_div_fixup_f32 v132, v129, v128, 1.0
	v_mov_b64_e32 v[128:129], s[16:17]
	v_mad_i64_i32 v[134:135], s[8:9], v162, s83, v[128:129]
	v_pk_mul_f32 v[136:137], v[122:123], v[132:133] op_sel_hi:[1,0]
	v_pk_mul_f32 v[122:123], v[120:121], v[132:133] op_sel_hi:[1,0]
	v_lshl_add_u64 v[134:135], v[134:135], 0, v[130:131]
	v_pk_mul_f32 v[126:127], v[126:127], v[132:133] op_sel_hi:[1,0]
	v_pk_mul_f32 v[124:125], v[124:125], v[132:133] op_sel_hi:[1,0]
	v_cmp_gt_f32_e32 vcc, s73, v190
	v_cvt_pk_bf16_f32 v120, v124, v125
	v_cvt_pk_bf16_f32 v121, v126, v127
	v_cvt_pk_bf16_f32 v122, v122, v123
	v_cvt_pk_bf16_f32 v123, v136, v137
	global_store_dwordx4 v[134:135], v[120:123], off
	v_pk_mul_f32 v[116:117], v[116:117], v[132:133] op_sel_hi:[1,0]
	v_pk_mul_f32 v[118:119], v[118:119], v[132:133] op_sel_hi:[1,0]
	v_cndmask_b32_e32 v122, v190, v191, vcc
	v_sqrt_f32_e32 v123, v122
	v_pk_mul_f32 v[120:121], v[114:115], v[132:133] op_sel_hi:[1,0]
	v_pk_mul_f32 v[114:115], v[112:113], v[132:133] op_sel_hi:[1,0]
	v_cvt_pk_bf16_f32 v112, v116, v117
	v_add_u32_e32 v116, -1, v123
	v_fma_f32 v117, -v116, v123, v122
	v_cmp_ge_f32_e64 s[8:9], 0, v117
	v_add_u32_e32 v117, 1, v123
	v_cvt_pk_bf16_f32 v113, v118, v119
	v_fma_f32 v118, -v117, v123, v122
	v_cndmask_b32_e64 v116, v123, v116, s[8:9]
	v_cmp_lt_f32_e64 s[8:9], 0, v118
	v_cvt_pk_bf16_f32 v114, v114, v115
	v_cvt_pk_bf16_f32 v115, v120, v121
	global_store_dwordx4 v[134:135], v[112:115], off offset:256
	s_nop 0
	v_cndmask_b32_e64 v116, v116, v117, s[8:9]
	v_mul_f32_e32 v117, 0x37800000, v116
	v_cndmask_b32_e32 v116, v116, v117, vcc
	v_cmp_class_f32_e32 vcc, v122, v178
	s_nop 1
	v_cndmask_b32_e32 v116, v116, v122, vcc
	v_div_scale_f32 v117, s[8:9], v116, v116, 1.0
	v_rcp_f32_e32 v118, v117
	s_nop 0
	v_fma_f32 v112, -v117, v118, 1.0
	v_fmac_f32_e32 v118, v112, v118
	v_div_scale_f32 v112, vcc, 1.0, v116, 1.0
	v_mul_f32_e32 v113, v112, v118
	v_fma_f32 v114, -v117, v113, v112
	v_fmac_f32_e32 v113, v114, v118
	v_fma_f32 v112, -v117, v113, v112
	v_div_fmas_f32 v112, v112, v118, v113
	v_div_fixup_f32 v112, v112, v116, 1.0
	v_mad_i64_i32 v[114:115], s[8:9], v166, s83, v[128:129]
	v_lshl_add_u64 v[114:115], v[114:115], 0, v[130:131]
	v_pk_mul_f32 v[110:111], v[112:113], v[110:111] op_sel_hi:[0,1]
	v_pk_mul_f32 v[108:109], v[112:113], v[108:109] op_sel_hi:[0,1]
	v_pk_mul_f32 v[116:117], v[112:113], v[106:107] op_sel_hi:[0,1]
	v_pk_mul_f32 v[106:107], v[112:113], v[104:105] op_sel_hi:[0,1]
	v_cvt_pk_bf16_f32 v104, v108, v109
	v_cvt_pk_bf16_f32 v105, v110, v111
	v_cvt_pk_bf16_f32 v106, v106, v107
	v_cvt_pk_bf16_f32 v107, v116, v117
	global_store_dwordx4 v[114:115], v[104:107], off
	v_cmp_gt_f32_e32 vcc, s73, v189
	v_pk_mul_f32 v[100:101], v[112:113], v[100:101] op_sel_hi:[0,1]
	v_pk_mul_f32 v[104:105], v[112:113], v[98:99] op_sel_hi:[0,1]
	v_mul_f32_e32 v98, 0x4f800000, v189
	v_cndmask_b32_e32 v106, v189, v98, vcc
	v_sqrt_f32_e32 v107, v106
	v_pk_mul_f32 v[98:99], v[112:113], v[96:97] op_sel_hi:[0,1]
	v_cvt_pk_bf16_f32 v96, v100, v101
	v_pk_mul_f32 v[102:103], v[112:113], v[102:103] op_sel_hi:[0,1]
	v_add_u32_e32 v100, -1, v107
	v_fma_f32 v101, -v100, v107, v106
	v_cmp_ge_f32_e64 s[8:9], 0, v101
	v_add_u32_e32 v101, 1, v107
	v_cvt_pk_bf16_f32 v97, v102, v103
	v_fma_f32 v102, -v101, v107, v106
	v_cndmask_b32_e64 v100, v107, v100, s[8:9]
	v_cmp_lt_f32_e64 s[8:9], 0, v102
	v_cvt_pk_bf16_f32 v98, v98, v99
	v_cvt_pk_bf16_f32 v99, v104, v105
	global_store_dwordx4 v[114:115], v[96:99], off offset:256
	s_nop 0
	v_cndmask_b32_e64 v100, v100, v101, s[8:9]
	v_mul_f32_e32 v101, 0x37800000, v100
	v_cndmask_b32_e32 v100, v100, v101, vcc
	v_cmp_class_f32_e32 vcc, v106, v178
	s_nop 1
	v_cndmask_b32_e32 v100, v100, v106, vcc
	v_div_scale_f32 v101, s[8:9], v100, v100, 1.0
	v_rcp_f32_e32 v102, v101
	s_nop 0
	v_fma_f32 v96, -v101, v102, 1.0
	v_fmac_f32_e32 v102, v96, v102
	v_div_scale_f32 v96, vcc, 1.0, v100, 1.0
	v_mul_f32_e32 v97, v96, v102
	v_fma_f32 v98, -v101, v97, v96
	v_fmac_f32_e32 v97, v98, v102
	v_fma_f32 v96, -v101, v97, v96
	v_div_fmas_f32 v96, v96, v102, v97
	v_div_fixup_f32 v96, v96, v100, 1.0
	v_mad_i64_i32 v[98:99], s[8:9], v164, s83, v[128:129]
	v_lshl_add_u64 v[98:99], v[98:99], 0, v[130:131]
	v_pk_mul_f32 v[94:95], v[96:97], v[94:95] op_sel_hi:[0,1]
	v_pk_mul_f32 v[92:93], v[96:97], v[92:93] op_sel_hi:[0,1]
	v_pk_mul_f32 v[100:101], v[96:97], v[90:91] op_sel_hi:[0,1]
	v_pk_mul_f32 v[90:91], v[96:97], v[88:89] op_sel_hi:[0,1]
	v_cvt_pk_bf16_f32 v88, v92, v93
	v_cvt_pk_bf16_f32 v89, v94, v95
	v_cvt_pk_bf16_f32 v90, v90, v91
	v_cvt_pk_bf16_f32 v91, v100, v101
	global_store_dwordx4 v[98:99], v[88:91], off
	v_pk_mul_f32 v[86:87], v[96:97], v[86:87] op_sel_hi:[0,1]
	v_pk_mul_f32 v[84:85], v[96:97], v[84:85] op_sel_hi:[0,1]
	v_pk_mul_f32 v[88:89], v[96:97], v[82:83] op_sel_hi:[0,1]
	v_pk_mul_f32 v[82:83], v[96:97], v[80:81] op_sel_hi:[0,1]
	v_fmamk_f32 v80, v185, 0x3a800000, v177
	v_mul_f32_e32 v81, 0x4f800000, v80
	v_cmp_gt_f32_e32 vcc, s73, v80
	s_nop 1
	v_cndmask_b32_e32 v90, v80, v81, vcc
	v_sqrt_f32_e32 v91, v90
	v_cvt_pk_bf16_f32 v80, v84, v85
	v_cvt_pk_bf16_f32 v81, v86, v87
	v_cvt_pk_bf16_f32 v82, v82, v83
	s_nop 0
	v_add_u32_e32 v83, -1, v91
	v_fma_f32 v84, -v83, v91, v90
	v_cmp_ge_f32_e64 s[8:9], 0, v84
	v_add_u32_e32 v84, 1, v91
	v_fma_f32 v85, -v84, v91, v90
	v_cndmask_b32_e64 v83, v91, v83, s[8:9]
	v_cmp_lt_f32_e64 s[8:9], 0, v85
	s_nop 1
	v_cndmask_b32_e64 v83, v83, v84, s[8:9]
	v_mul_f32_e32 v84, 0x37800000, v83
	v_cndmask_b32_e32 v83, v83, v84, vcc
	v_cmp_class_f32_e32 vcc, v90, v178
	s_nop 1
	v_cndmask_b32_e32 v84, v83, v90, vcc
	v_div_scale_f32 v85, s[8:9], v84, v84, 1.0
	v_rcp_f32_e32 v86, v85
	v_cvt_pk_bf16_f32 v83, v88, v89
	global_store_dwordx4 v[98:99], v[80:83], off offset:256
	s_nop 1
	v_fma_f32 v80, -v85, v86, 1.0
	v_fmac_f32_e32 v86, v80, v86
	v_div_scale_f32 v80, vcc, 1.0, v84, 1.0
	v_mul_f32_e32 v82, v80, v86
	v_fma_f32 v83, -v85, v82, v80
	v_fmac_f32_e32 v82, v83, v86
	v_fma_f32 v80, -v85, v82, v80
	v_or_b32_e32 v81, 48, v162
	v_div_fmas_f32 v80, v80, v86, v82
	v_div_fixup_f32 v80, v80, v84, 1.0
	v_mad_i64_i32 v[82:83], s[8:9], v81, s83, v[128:129]
	v_lshl_add_u64 v[82:83], v[82:83], 0, v[130:131]
	v_pk_mul_f32 v[78:79], v[80:81], v[78:79] op_sel_hi:[0,1]
	v_pk_mul_f32 v[76:77], v[80:81], v[76:77] op_sel_hi:[0,1]
	v_pk_mul_f32 v[84:85], v[80:81], v[74:75] op_sel_hi:[0,1]
	v_pk_mul_f32 v[74:75], v[80:81], v[72:73] op_sel_hi:[0,1]
	v_cvt_pk_bf16_f32 v72, v76, v77
	v_cvt_pk_bf16_f32 v73, v78, v79
	v_cvt_pk_bf16_f32 v74, v74, v75
	v_cvt_pk_bf16_f32 v75, v84, v85
	global_store_dwordx4 v[82:83], v[72:75], off
	v_pk_mul_f32 v[70:71], v[80:81], v[70:71] op_sel_hi:[0,1]
	v_pk_mul_f32 v[68:69], v[80:81], v[68:69] op_sel_hi:[0,1]
	v_pk_mul_f32 v[72:73], v[80:81], v[66:67] op_sel_hi:[0,1]
	v_pk_mul_f32 v[66:67], v[80:81], v[64:65] op_sel_hi:[0,1]
	v_fmamk_f32 v64, v184, 0x3a800000, v177
	v_mul_f32_e32 v65, 0x4f800000, v64
	v_cmp_gt_f32_e32 vcc, s73, v64
	s_nop 1
	v_cndmask_b32_e32 v74, v64, v65, vcc
	v_sqrt_f32_e32 v75, v74
	v_cvt_pk_bf16_f32 v64, v68, v69
	v_cvt_pk_bf16_f32 v65, v70, v71
	v_cvt_pk_bf16_f32 v66, v66, v67
	s_nop 0
	v_add_u32_e32 v67, -1, v75
	v_fma_f32 v68, -v67, v75, v74
	v_cmp_ge_f32_e64 s[8:9], 0, v68
	v_add_u32_e32 v68, 1, v75
	v_fma_f32 v69, -v68, v75, v74
	v_cndmask_b32_e64 v67, v75, v67, s[8:9]
	v_cmp_lt_f32_e64 s[8:9], 0, v69
	s_nop 1
	v_cndmask_b32_e64 v67, v67, v68, s[8:9]
	v_mul_f32_e32 v68, 0x37800000, v67
	v_cndmask_b32_e32 v67, v67, v68, vcc
	v_cmp_class_f32_e32 vcc, v74, v178
	s_nop 1
	v_cndmask_b32_e32 v68, v67, v74, vcc
	v_div_scale_f32 v69, s[8:9], v68, v68, 1.0
	v_rcp_f32_e32 v70, v69
	v_cvt_pk_bf16_f32 v67, v72, v73
	global_store_dwordx4 v[82:83], v[64:67], off offset:256
	s_nop 1
	v_fma_f32 v64, -v69, v70, 1.0
	v_fmac_f32_e32 v70, v64, v70
	v_div_scale_f32 v64, vcc, 1.0, v68, 1.0
	v_mul_f32_e32 v66, v64, v70
	v_fma_f32 v67, -v69, v66, v64
	v_fmac_f32_e32 v66, v67, v70
	v_fma_f32 v64, -v69, v66, v64
	v_add_u32_e32 v65, 0x80, v162
	v_div_fmas_f32 v64, v64, v70, v66
	v_div_fixup_f32 v64, v64, v68, 1.0
	v_mad_i64_i32 v[66:67], s[8:9], v65, s83, v[128:129]
	v_lshl_add_u64 v[66:67], v[66:67], 0, v[130:131]
	v_pk_mul_f32 v[62:63], v[64:65], v[62:63] op_sel_hi:[0,1]
	v_pk_mul_f32 v[60:61], v[64:65], v[60:61] op_sel_hi:[0,1]
	v_pk_mul_f32 v[68:69], v[64:65], v[58:59] op_sel_hi:[0,1]
	v_pk_mul_f32 v[58:59], v[64:65], v[56:57] op_sel_hi:[0,1]
	v_cvt_pk_bf16_f32 v56, v60, v61
	v_cvt_pk_bf16_f32 v57, v62, v63
	v_cvt_pk_bf16_f32 v58, v58, v59
	v_cvt_pk_bf16_f32 v59, v68, v69
	global_store_dwordx4 v[66:67], v[56:59], off
	v_pk_mul_f32 v[54:55], v[64:65], v[54:55] op_sel_hi:[0,1]
	v_pk_mul_f32 v[52:53], v[64:65], v[52:53] op_sel_hi:[0,1]
	v_pk_mul_f32 v[56:57], v[64:65], v[50:51] op_sel_hi:[0,1]
	v_pk_mul_f32 v[50:51], v[64:65], v[48:49] op_sel_hi:[0,1]
	v_fmamk_f32 v48, v183, 0x3a800000, v177
	v_mul_f32_e32 v49, 0x4f800000, v48
	v_cmp_gt_f32_e32 vcc, s73, v48
	s_nop 1
	v_cndmask_b32_e32 v58, v48, v49, vcc
	v_sqrt_f32_e32 v59, v58
	v_cvt_pk_bf16_f32 v48, v52, v53
	v_cvt_pk_bf16_f32 v49, v54, v55
	v_cvt_pk_bf16_f32 v50, v50, v51
	s_nop 0
	v_add_u32_e32 v51, -1, v59
	v_fma_f32 v52, -v51, v59, v58
	v_cmp_ge_f32_e64 s[8:9], 0, v52
	v_add_u32_e32 v52, 1, v59
	v_fma_f32 v53, -v52, v59, v58
	v_cndmask_b32_e64 v51, v59, v51, s[8:9]
	v_cmp_lt_f32_e64 s[8:9], 0, v53
	s_nop 1
	v_cndmask_b32_e64 v51, v51, v52, s[8:9]
	v_mul_f32_e32 v52, 0x37800000, v51
	v_cndmask_b32_e32 v51, v51, v52, vcc
	v_cmp_class_f32_e32 vcc, v58, v178
	s_nop 1
	v_cndmask_b32_e32 v52, v51, v58, vcc
	v_div_scale_f32 v53, s[8:9], v52, v52, 1.0
	v_rcp_f32_e32 v54, v53
	v_cvt_pk_bf16_f32 v51, v56, v57
	global_store_dwordx4 v[66:67], v[48:51], off offset:256
	s_nop 1
	v_fma_f32 v48, -v53, v54, 1.0
	v_fmac_f32_e32 v54, v48, v54
	v_div_scale_f32 v48, vcc, 1.0, v52, 1.0
	v_mul_f32_e32 v50, v48, v54
	v_fma_f32 v51, -v53, v50, v48
	v_fmac_f32_e32 v50, v51, v54
	v_fma_f32 v48, -v53, v50, v48
	v_add_u32_e32 v49, 0x90, v162
	v_div_fmas_f32 v48, v48, v54, v50
	v_div_fixup_f32 v48, v48, v52, 1.0
	v_mad_i64_i32 v[50:51], s[8:9], v49, s83, v[128:129]
	v_lshl_add_u64 v[50:51], v[50:51], 0, v[130:131]
	v_pk_mul_f32 v[46:47], v[48:49], v[46:47] op_sel_hi:[0,1]
	v_pk_mul_f32 v[44:45], v[48:49], v[44:45] op_sel_hi:[0,1]
	v_pk_mul_f32 v[52:53], v[48:49], v[42:43] op_sel_hi:[0,1]
	v_pk_mul_f32 v[42:43], v[48:49], v[40:41] op_sel_hi:[0,1]
	v_cvt_pk_bf16_f32 v40, v44, v45
	v_cvt_pk_bf16_f32 v41, v46, v47
	v_cvt_pk_bf16_f32 v42, v42, v43
	v_cvt_pk_bf16_f32 v43, v52, v53
	global_store_dwordx4 v[50:51], v[40:43], off
	v_pk_mul_f32 v[38:39], v[48:49], v[38:39] op_sel_hi:[0,1]
	v_pk_mul_f32 v[36:37], v[48:49], v[36:37] op_sel_hi:[0,1]
	v_pk_mul_f32 v[40:41], v[48:49], v[34:35] op_sel_hi:[0,1]
	v_pk_mul_f32 v[34:35], v[48:49], v[32:33] op_sel_hi:[0,1]
	v_fmamk_f32 v32, v181, 0x3a800000, v177
	v_mul_f32_e32 v33, 0x4f800000, v32
	v_cmp_gt_f32_e32 vcc, s73, v32
	s_nop 1
	v_cndmask_b32_e32 v42, v32, v33, vcc
	v_sqrt_f32_e32 v43, v42
	v_cvt_pk_bf16_f32 v32, v36, v37
	v_cvt_pk_bf16_f32 v33, v38, v39
	v_cvt_pk_bf16_f32 v34, v34, v35
	s_nop 0
	v_add_u32_e32 v35, -1, v43
	v_fma_f32 v36, -v35, v43, v42
	v_cmp_ge_f32_e64 s[8:9], 0, v36
	v_add_u32_e32 v36, 1, v43
	v_fma_f32 v37, -v36, v43, v42
	v_cndmask_b32_e64 v35, v43, v35, s[8:9]
	v_cmp_lt_f32_e64 s[8:9], 0, v37
	s_nop 1
	v_cndmask_b32_e64 v35, v35, v36, s[8:9]
	v_mul_f32_e32 v36, 0x37800000, v35
	v_cndmask_b32_e32 v35, v35, v36, vcc
	v_cmp_class_f32_e32 vcc, v42, v178
	s_nop 1
	v_cndmask_b32_e32 v36, v35, v42, vcc
	v_div_scale_f32 v37, s[8:9], v36, v36, 1.0
	v_rcp_f32_e32 v38, v37
	v_cvt_pk_bf16_f32 v35, v40, v41
	global_store_dwordx4 v[50:51], v[32:35], off offset:256
	s_nop 1
	v_fma_f32 v32, -v37, v38, 1.0
	v_fmac_f32_e32 v38, v32, v38
	v_div_scale_f32 v32, vcc, 1.0, v36, 1.0
	v_mul_f32_e32 v34, v32, v38
	v_fma_f32 v35, -v37, v34, v32
	v_fmac_f32_e32 v34, v35, v38
	v_fma_f32 v32, -v37, v34, v32
	v_add_u32_e32 v33, 0xa0, v162
	v_div_fmas_f32 v32, v32, v38, v34
	v_div_fixup_f32 v32, v32, v36, 1.0
	v_mad_i64_i32 v[34:35], s[8:9], v33, s83, v[128:129]
	v_lshl_add_u64 v[34:35], v[34:35], 0, v[130:131]
	v_pk_mul_f32 v[30:31], v[32:33], v[30:31] op_sel_hi:[0,1]
	v_pk_mul_f32 v[28:29], v[32:33], v[28:29] op_sel_hi:[0,1]
	v_pk_mul_f32 v[36:37], v[32:33], v[26:27] op_sel_hi:[0,1]
	v_pk_mul_f32 v[26:27], v[32:33], v[24:25] op_sel_hi:[0,1]
	v_cvt_pk_bf16_f32 v24, v28, v29
	v_cvt_pk_bf16_f32 v25, v30, v31
	v_cvt_pk_bf16_f32 v26, v26, v27
	v_cvt_pk_bf16_f32 v27, v36, v37
	global_store_dwordx4 v[34:35], v[24:27], off
	v_pk_mul_f32 v[22:23], v[32:33], v[22:23] op_sel_hi:[0,1]
	v_pk_mul_f32 v[20:21], v[32:33], v[20:21] op_sel_hi:[0,1]
	v_pk_mul_f32 v[24:25], v[32:33], v[18:19] op_sel_hi:[0,1]
	v_pk_mul_f32 v[18:19], v[32:33], v[16:17] op_sel_hi:[0,1]
	v_fmamk_f32 v16, v179, 0x3a800000, v177
	v_mul_f32_e32 v17, 0x4f800000, v16
	v_cmp_gt_f32_e32 vcc, s73, v16
	s_nop 1
	v_cndmask_b32_e32 v26, v16, v17, vcc
	v_sqrt_f32_e32 v27, v26
	v_cvt_pk_bf16_f32 v16, v20, v21
	v_cvt_pk_bf16_f32 v17, v22, v23
	v_cvt_pk_bf16_f32 v18, v18, v19
	s_nop 0
	v_add_u32_e32 v19, -1, v27
	v_fma_f32 v20, -v19, v27, v26
	v_cmp_ge_f32_e64 s[8:9], 0, v20
	v_add_u32_e32 v20, 1, v27
	v_fma_f32 v21, -v20, v27, v26
	v_cndmask_b32_e64 v19, v27, v19, s[8:9]
	v_cmp_lt_f32_e64 s[8:9], 0, v21
	s_nop 1
	v_cndmask_b32_e64 v19, v19, v20, s[8:9]
	v_mul_f32_e32 v20, 0x37800000, v19
	v_cndmask_b32_e32 v19, v19, v20, vcc
	v_cmp_class_f32_e32 vcc, v26, v178
	s_nop 1
	v_cndmask_b32_e32 v20, v19, v26, vcc
	v_div_scale_f32 v21, s[8:9], v20, v20, 1.0
	v_rcp_f32_e32 v22, v21
	v_cvt_pk_bf16_f32 v19, v24, v25
	global_store_dwordx4 v[34:35], v[16:19], off offset:256
	s_nop 1
	v_fma_f32 v16, -v21, v22, 1.0
	v_fmac_f32_e32 v22, v16, v22
	v_div_scale_f32 v16, vcc, 1.0, v20, 1.0
	v_mul_f32_e32 v18, v16, v22
	v_fma_f32 v19, -v21, v18, v16
	v_fmac_f32_e32 v18, v19, v22
	v_fma_f32 v16, -v21, v18, v16
	v_add_u32_e32 v17, 0xb0, v162
	v_div_fmas_f32 v16, v16, v22, v18
	v_div_fixup_f32 v16, v16, v20, 1.0
	v_mad_i64_i32 v[18:19], s[8:9], v17, s83, v[128:129]
	v_lshl_add_u64 v[18:19], v[18:19], 0, v[130:131]
	v_pk_mul_f32 v[14:15], v[16:17], v[14:15] op_sel_hi:[0,1]
	v_pk_mul_f32 v[12:13], v[16:17], v[12:13] op_sel_hi:[0,1]
	v_pk_mul_f32 v[20:21], v[16:17], v[10:11] op_sel_hi:[0,1]
	v_pk_mul_f32 v[10:11], v[16:17], v[8:9] op_sel_hi:[0,1]
	v_cvt_pk_bf16_f32 v8, v12, v13
	v_cvt_pk_bf16_f32 v9, v14, v15
	v_cvt_pk_bf16_f32 v10, v10, v11
	v_cvt_pk_bf16_f32 v11, v20, v21
	global_store_dwordx4 v[18:19], v[8:11], off
	v_pk_mul_f32 v[6:7], v[16:17], v[6:7] op_sel_hi:[0,1]
	v_pk_mul_f32 v[4:5], v[16:17], v[4:5] op_sel_hi:[0,1]
	v_pk_mul_f32 v[8:9], v[16:17], v[2:3] op_sel_hi:[0,1]
	v_pk_mul_f32 v[2:3], v[16:17], v[0:1] op_sel_hi:[0,1]
	v_cvt_pk_bf16_f32 v0, v4, v5
	v_cvt_pk_bf16_f32 v1, v6, v7
	v_cvt_pk_bf16_f32 v2, v2, v3
	v_cvt_pk_bf16_f32 v3, v8, v9
	global_store_dwordx4 v[18:19], v[0:3], off offset:256
	s_andn2_b64 vcc, exec, s[6:7]
	s_mov_b64 s[6:7], -1
	s_cbranch_vccnz .LBB0_602

.LBB0_2200:
	s_waitcnt vmcnt(8)
	v_fmamk_f32 v141, v159, 0x3a800000, v150
	v_mul_f32_e32 v142, 0x4f800000, v141
	v_cmp_gt_f32_e32 vcc, s49, v141
	s_nop 1
	v_cndmask_b32_e32 v141, v141, v142, vcc
	v_sqrt_f32_e32 v142, v141
	s_nop 0
	v_add_u32_e32 v143, -1, v142
	v_fma_f32 v145, -v143, v142, v141
	v_add_u32_e32 v144, 1, v142
	v_cmp_ge_f32_e64 s[8:9], 0, v145
	s_nop 1
	v_cndmask_b32_e64 v143, v142, v143, s[8:9]
	v_fma_f32 v142, -v144, v142, v141
	v_cmp_lt_f32_e64 s[8:9], 0, v142
	s_nop 1
	v_cndmask_b32_e64 v142, v143, v144, s[8:9]
	v_mul_f32_e32 v143, 0x37800000, v142
	v_cndmask_b32_e32 v142, v142, v143, vcc
	v_cmp_class_f32_e32 vcc, v141, v151
	v_lshl_or_b32 v144, s59, 8, v148
	v_ashrrev_i32_e32 v145, 31, v144
	v_cndmask_b32_e32 v141, v142, v141, vcc
	v_div_scale_f32 v142, s[8:9], v141, v141, 1.0
	v_rcp_f32_e32 v143, v142
	v_lshlrev_b64 v[144:145], 2, v[144:145]
	v_fma_f32 v160, -v142, v143, 1.0
	v_fmac_f32_e32 v143, v160, v143
	v_div_scale_f32 v160, vcc, 1.0, v141, 1.0
	v_mul_f32_e32 v161, v160, v143
	v_fma_f32 v162, -v142, v161, v160
	v_fmac_f32_e32 v161, v162, v143
	v_fma_f32 v142, -v142, v161, v160
	v_div_fmas_f32 v142, v142, v143, v161
	v_div_fixup_f32 v160, v142, v141, 1.0
	v_mov_b64_e32 v[142:143], s[12:13]
	v_mad_i64_i32 v[162:163], s[8:9], v140, s57, v[142:143]
	v_lshl_add_u64 v[162:163], v[162:163], 0, v[144:145]
	v_pk_mul_f32 v[122:123], v[122:123], v[160:161] op_sel_hi:[1,0]
	v_pk_mul_f32 v[120:121], v[120:121], v[160:161] op_sel_hi:[1,0]
	global_store_dwordx4 v[162:163], v[120:123], off offset:64
	v_pk_mul_f32 v[118:119], v[118:119], v[160:161] op_sel_hi:[1,0]
	v_pk_mul_f32 v[116:117], v[116:117], v[160:161] op_sel_hi:[1,0]
	v_fmamk_f32 v120, v158, 0x3a800000, v150
	v_mul_f32_e32 v121, 0x4f800000, v120
	v_cmp_gt_f32_e32 vcc, s49, v120
	global_store_dwordx4 v[162:163], v[116:119], off offset:512
	v_pk_mul_f32 v[110:111], v[110:111], v[160:161] op_sel_hi:[1,0]
	v_cndmask_b32_e32 v120, v120, v121, vcc
	v_sqrt_f32_e32 v121, v120
	v_pk_mul_f32 v[108:109], v[108:109], v[160:161] op_sel_hi:[1,0]
	global_store_dwordx4 v[162:163], v[108:111], off offset:576
	v_pk_mul_f32 v[126:127], v[126:127], v[160:161] op_sel_hi:[1,0]
	v_add_u32_e32 v116, -1, v121
	v_fma_f32 v117, -v116, v121, v120
	v_cmp_ge_f32_e64 s[8:9], 0, v117
	v_add_u32_e32 v117, 1, v121
	v_fma_f32 v118, -v117, v121, v120
	v_cndmask_b32_e64 v116, v121, v116, s[8:9]
	v_cmp_lt_f32_e64 s[8:9], 0, v118
	v_or_b32_e32 v108, 16, v140
	v_pk_mul_f32 v[124:125], v[124:125], v[160:161] op_sel_hi:[1,0]
	v_cndmask_b32_e64 v116, v116, v117, s[8:9]
	v_mul_f32_e32 v117, 0x37800000, v116
	v_cndmask_b32_e32 v116, v116, v117, vcc
	v_cmp_class_f32_e32 vcc, v120, v151
	global_store_dwordx4 v[162:163], v[124:127], off
	s_nop 0
	v_cndmask_b32_e32 v116, v116, v120, vcc
	v_div_scale_f32 v117, s[8:9], v116, v116, 1.0
	v_rcp_f32_e32 v118, v117
	s_nop 0
	v_fma_f32 v109, -v117, v118, 1.0
	v_fmac_f32_e32 v118, v109, v118
	v_div_scale_f32 v109, vcc, 1.0, v116, 1.0
	v_mul_f32_e32 v110, v109, v118
	v_fma_f32 v111, -v117, v110, v109
	v_fmac_f32_e32 v110, v111, v118
	v_fma_f32 v109, -v117, v110, v109
	v_div_fmas_f32 v109, v109, v118, v110
	v_div_fixup_f32 v116, v109, v116, 1.0
	v_mad_i64_i32 v[108:109], s[8:9], v108, s57, v[142:143]
	v_lshl_add_u64 v[118:119], v[108:109], 0, v[144:145]
	v_pk_mul_f32 v[106:107], v[116:117], v[106:107] op_sel_hi:[0,1]
	v_pk_mul_f32 v[104:105], v[116:117], v[104:105] op_sel_hi:[0,1]
	global_store_dwordx4 v[118:119], v[104:107], off offset:64
	v_pk_mul_f32 v[102:103], v[116:117], v[102:103] op_sel_hi:[0,1]
	v_pk_mul_f32 v[100:101], v[116:117], v[100:101] op_sel_hi:[0,1]
	v_fmamk_f32 v104, v157, 0x3a800000, v150
	v_mul_f32_e32 v105, 0x4f800000, v104
	v_cmp_gt_f32_e32 vcc, s49, v104
	global_store_dwordx4 v[118:119], v[100:103], off offset:512
	v_pk_mul_f32 v[94:95], v[116:117], v[94:95] op_sel_hi:[0,1]
	v_cndmask_b32_e32 v104, v104, v105, vcc
	v_sqrt_f32_e32 v105, v104
	v_pk_mul_f32 v[92:93], v[116:117], v[92:93] op_sel_hi:[0,1]
	global_store_dwordx4 v[118:119], v[92:95], off offset:576
	v_pk_mul_f32 v[110:111], v[116:117], v[114:115] op_sel_hi:[0,1]
	v_add_u32_e32 v100, -1, v105
	v_fma_f32 v101, -v100, v105, v104
	v_cmp_ge_f32_e64 s[8:9], 0, v101
	v_add_u32_e32 v101, 1, v105
	v_fma_f32 v102, -v101, v105, v104
	v_cndmask_b32_e64 v100, v105, v100, s[8:9]
	v_cmp_lt_f32_e64 s[8:9], 0, v102
	v_or_b32_e32 v92, 32, v140
	v_pk_mul_f32 v[108:109], v[116:117], v[112:113] op_sel_hi:[0,1]
	v_cndmask_b32_e64 v100, v100, v101, s[8:9]
	v_mul_f32_e32 v101, 0x37800000, v100
	v_cndmask_b32_e32 v100, v100, v101, vcc
	v_cmp_class_f32_e32 vcc, v104, v151
	global_store_dwordx4 v[118:119], v[108:111], off
	s_nop 0
	v_cndmask_b32_e32 v100, v100, v104, vcc
	v_div_scale_f32 v101, s[8:9], v100, v100, 1.0
	v_rcp_f32_e32 v102, v101
	s_nop 0
	v_fma_f32 v93, -v101, v102, 1.0
	v_fmac_f32_e32 v102, v93, v102
	v_div_scale_f32 v93, vcc, 1.0, v100, 1.0
	v_mul_f32_e32 v94, v93, v102
	v_fma_f32 v95, -v101, v94, v93
	v_fmac_f32_e32 v94, v95, v102
	v_fma_f32 v93, -v101, v94, v93
	v_div_fmas_f32 v93, v93, v102, v94
	v_div_fixup_f32 v100, v93, v100, 1.0
	v_mad_i64_i32 v[92:93], s[8:9], v92, s57, v[142:143]
	v_lshl_add_u64 v[102:103], v[92:93], 0, v[144:145]
	v_pk_mul_f32 v[90:91], v[100:101], v[90:91] op_sel_hi:[0,1]
	v_pk_mul_f32 v[88:89], v[100:101], v[88:89] op_sel_hi:[0,1]
	global_store_dwordx4 v[102:103], v[88:91], off offset:64
	v_pk_mul_f32 v[86:87], v[100:101], v[86:87] op_sel_hi:[0,1]
	v_pk_mul_f32 v[84:85], v[100:101], v[84:85] op_sel_hi:[0,1]
	v_fmamk_f32 v88, v156, 0x3a800000, v150
	v_mul_f32_e32 v89, 0x4f800000, v88
	v_cmp_gt_f32_e32 vcc, s49, v88
	global_store_dwordx4 v[102:103], v[84:87], off offset:512
	v_pk_mul_f32 v[78:79], v[100:101], v[78:79] op_sel_hi:[0,1]
	v_cndmask_b32_e32 v88, v88, v89, vcc
	v_sqrt_f32_e32 v89, v88
	v_pk_mul_f32 v[76:77], v[100:101], v[76:77] op_sel_hi:[0,1]
	global_store_dwordx4 v[102:103], v[76:79], off offset:576
	v_pk_mul_f32 v[94:95], v[100:101], v[98:99] op_sel_hi:[0,1]
	v_add_u32_e32 v84, -1, v89
	v_fma_f32 v85, -v84, v89, v88
	v_cmp_ge_f32_e64 s[8:9], 0, v85
	v_add_u32_e32 v85, 1, v89
	v_fma_f32 v86, -v85, v89, v88
	v_cndmask_b32_e64 v84, v89, v84, s[8:9]
	v_cmp_lt_f32_e64 s[8:9], 0, v86
	v_or_b32_e32 v76, 48, v140
	v_pk_mul_f32 v[92:93], v[100:101], v[96:97] op_sel_hi:[0,1]
	v_cndmask_b32_e64 v84, v84, v85, s[8:9]
	v_mul_f32_e32 v85, 0x37800000, v84
	v_cndmask_b32_e32 v84, v84, v85, vcc
	v_cmp_class_f32_e32 vcc, v88, v151
	global_store_dwordx4 v[102:103], v[92:95], off
	s_nop 0
	v_cndmask_b32_e32 v84, v84, v88, vcc
	v_div_scale_f32 v85, s[8:9], v84, v84, 1.0
	v_rcp_f32_e32 v86, v85
	s_nop 0
	v_fma_f32 v77, -v85, v86, 1.0
	v_fmac_f32_e32 v86, v77, v86
	v_div_scale_f32 v77, vcc, 1.0, v84, 1.0
	v_mul_f32_e32 v78, v77, v86
	v_fma_f32 v79, -v85, v78, v77
	v_fmac_f32_e32 v78, v79, v86
	v_fma_f32 v77, -v85, v78, v77
	v_div_fmas_f32 v77, v77, v86, v78
	v_div_fixup_f32 v84, v77, v84, 1.0
	v_mad_i64_i32 v[76:77], s[8:9], v76, s57, v[142:143]
	v_lshl_add_u64 v[86:87], v[76:77], 0, v[144:145]
	v_pk_mul_f32 v[74:75], v[84:85], v[74:75] op_sel_hi:[0,1]
	v_pk_mul_f32 v[72:73], v[84:85], v[72:73] op_sel_hi:[0,1]
	global_store_dwordx4 v[86:87], v[72:75], off offset:64
	v_pk_mul_f32 v[70:71], v[84:85], v[70:71] op_sel_hi:[0,1]
	v_pk_mul_f32 v[68:69], v[84:85], v[68:69] op_sel_hi:[0,1]
	v_fmamk_f32 v72, v155, 0x3a800000, v150
	v_mul_f32_e32 v73, 0x4f800000, v72
	v_cmp_gt_f32_e32 vcc, s49, v72
	global_store_dwordx4 v[86:87], v[68:71], off offset:512
	v_pk_mul_f32 v[66:67], v[84:85], v[66:67] op_sel_hi:[0,1]
	v_cndmask_b32_e32 v72, v72, v73, vcc
	v_sqrt_f32_e32 v73, v72
	v_pk_mul_f32 v[64:65], v[84:85], v[64:65] op_sel_hi:[0,1]
	global_store_dwordx4 v[86:87], v[64:67], off offset:576
	v_pk_mul_f32 v[78:79], v[84:85], v[82:83] op_sel_hi:[0,1]
	v_add_u32_e32 v68, -1, v73
	v_fma_f32 v69, -v68, v73, v72
	v_cmp_ge_f32_e64 s[8:9], 0, v69
	v_add_u32_e32 v69, 1, v73
	v_fma_f32 v70, -v69, v73, v72
	v_cndmask_b32_e64 v68, v73, v68, s[8:9]
	v_cmp_lt_f32_e64 s[8:9], 0, v70
	v_add_u32_e32 v65, 0x80, v140
	v_pk_mul_f32 v[76:77], v[84:85], v[80:81] op_sel_hi:[0,1]
	v_cndmask_b32_e64 v68, v68, v69, s[8:9]
	v_mul_f32_e32 v69, 0x37800000, v68
	v_cndmask_b32_e32 v68, v68, v69, vcc
	v_cmp_class_f32_e32 vcc, v72, v151
	global_store_dwordx4 v[86:87], v[76:79], off
	s_nop 0
	v_cndmask_b32_e32 v68, v68, v72, vcc
	v_div_scale_f32 v69, s[8:9], v68, v68, 1.0
	v_rcp_f32_e32 v70, v69
	s_nop 0
	v_fma_f32 v64, -v69, v70, 1.0
	v_fmac_f32_e32 v70, v64, v70
	v_div_scale_f32 v64, vcc, 1.0, v68, 1.0
	v_mul_f32_e32 v66, v64, v70
	v_fma_f32 v67, -v69, v66, v64
	v_fmac_f32_e32 v66, v67, v70
	v_fma_f32 v64, -v69, v66, v64
	v_div_fmas_f32 v64, v64, v70, v66
	v_div_fixup_f32 v64, v64, v68, 1.0
	v_mad_i64_i32 v[66:67], s[8:9], v65, s57, v[142:143]
	v_lshl_add_u64 v[66:67], v[66:67], 0, v[144:145]
	v_pk_mul_f32 v[58:59], v[64:65], v[58:59] op_sel_hi:[0,1]
	v_pk_mul_f32 v[56:57], v[64:65], v[56:57] op_sel_hi:[0,1]
	global_store_dwordx4 v[66:67], v[56:59], off offset:64
	v_pk_mul_f32 v[54:55], v[64:65], v[54:55] op_sel_hi:[0,1]
	v_pk_mul_f32 v[52:53], v[64:65], v[52:53] op_sel_hi:[0,1]
	v_fmamk_f32 v56, v154, 0x3a800000, v150
	v_mul_f32_e32 v57, 0x4f800000, v56
	v_cmp_gt_f32_e32 vcc, s49, v56
	global_store_dwordx4 v[66:67], v[52:55], off offset:512
	v_pk_mul_f32 v[46:47], v[64:65], v[46:47] op_sel_hi:[0,1]
	v_cndmask_b32_e32 v56, v56, v57, vcc
	v_sqrt_f32_e32 v57, v56
	v_pk_mul_f32 v[44:45], v[64:65], v[44:45] op_sel_hi:[0,1]
	global_store_dwordx4 v[66:67], v[44:47], off offset:576
	v_pk_mul_f32 v[62:63], v[64:65], v[62:63] op_sel_hi:[0,1]
	v_add_u32_e32 v52, -1, v57
	v_fma_f32 v53, -v52, v57, v56
	v_cmp_ge_f32_e64 s[8:9], 0, v53
	v_add_u32_e32 v53, 1, v57
	v_fma_f32 v54, -v53, v57, v56
	v_cndmask_b32_e64 v52, v57, v52, s[8:9]
	v_cmp_lt_f32_e64 s[8:9], 0, v54
	v_add_u32_e32 v44, 0x90, v140
	v_pk_mul_f32 v[60:61], v[64:65], v[60:61] op_sel_hi:[0,1]
	v_cndmask_b32_e64 v52, v52, v53, s[8:9]
	v_mul_f32_e32 v53, 0x37800000, v52
	v_cndmask_b32_e32 v52, v52, v53, vcc
	v_cmp_class_f32_e32 vcc, v56, v151
	global_store_dwordx4 v[66:67], v[60:63], off
	s_nop 0
	v_cndmask_b32_e32 v52, v52, v56, vcc
	v_div_scale_f32 v53, s[8:9], v52, v52, 1.0
	v_rcp_f32_e32 v54, v53
	s_nop 0
	v_fma_f32 v45, -v53, v54, 1.0
	v_fmac_f32_e32 v54, v45, v54
	v_div_scale_f32 v45, vcc, 1.0, v52, 1.0
	v_mul_f32_e32 v46, v45, v54
	v_fma_f32 v47, -v53, v46, v45
	v_fmac_f32_e32 v46, v47, v54
	v_fma_f32 v45, -v53, v46, v45
	v_div_fmas_f32 v45, v45, v54, v46
	v_div_fixup_f32 v52, v45, v52, 1.0
	v_mad_i64_i32 v[44:45], s[8:9], v44, s57, v[142:143]
	v_lshl_add_u64 v[54:55], v[44:45], 0, v[144:145]
	v_pk_mul_f32 v[42:43], v[52:53], v[42:43] op_sel_hi:[0,1]
	v_pk_mul_f32 v[40:41], v[52:53], v[40:41] op_sel_hi:[0,1]
	global_store_dwordx4 v[54:55], v[40:43], off offset:64
	v_pk_mul_f32 v[38:39], v[52:53], v[38:39] op_sel_hi:[0,1]
	v_pk_mul_f32 v[36:37], v[52:53], v[36:37] op_sel_hi:[0,1]
	v_fmamk_f32 v40, v153, 0x3a800000, v150
	v_mul_f32_e32 v41, 0x4f800000, v40
	v_cmp_gt_f32_e32 vcc, s49, v40
	global_store_dwordx4 v[54:55], v[36:39], off offset:512
	v_pk_mul_f32 v[30:31], v[52:53], v[30:31] op_sel_hi:[0,1]
	v_cndmask_b32_e32 v40, v40, v41, vcc
	v_sqrt_f32_e32 v41, v40
	v_pk_mul_f32 v[28:29], v[52:53], v[28:29] op_sel_hi:[0,1]
	global_store_dwordx4 v[54:55], v[28:31], off offset:576
	v_pk_mul_f32 v[46:47], v[52:53], v[50:51] op_sel_hi:[0,1]
	v_add_u32_e32 v36, -1, v41
	v_fma_f32 v37, -v36, v41, v40
	v_cmp_ge_f32_e64 s[8:9], 0, v37
	v_add_u32_e32 v37, 1, v41
	v_fma_f32 v38, -v37, v41, v40
	v_cndmask_b32_e64 v36, v41, v36, s[8:9]
	v_cmp_lt_f32_e64 s[8:9], 0, v38
	v_add_u32_e32 v28, 0xa0, v140
	v_pk_mul_f32 v[44:45], v[52:53], v[48:49] op_sel_hi:[0,1]
	v_cndmask_b32_e64 v36, v36, v37, s[8:9]
	v_mul_f32_e32 v37, 0x37800000, v36
	v_cndmask_b32_e32 v36, v36, v37, vcc
	v_cmp_class_f32_e32 vcc, v40, v151
	global_store_dwordx4 v[54:55], v[44:47], off
	s_nop 0
	v_cndmask_b32_e32 v36, v36, v40, vcc
	v_div_scale_f32 v37, s[8:9], v36, v36, 1.0
	v_rcp_f32_e32 v38, v37
	s_nop 0
	v_fma_f32 v29, -v37, v38, 1.0
	v_fmac_f32_e32 v38, v29, v38
	v_div_scale_f32 v29, vcc, 1.0, v36, 1.0
	v_mul_f32_e32 v30, v29, v38
	v_fma_f32 v31, -v37, v30, v29
	v_fmac_f32_e32 v30, v31, v38
	v_fma_f32 v29, -v37, v30, v29
	v_div_fmas_f32 v29, v29, v38, v30
	v_div_fixup_f32 v36, v29, v36, 1.0
	v_mad_i64_i32 v[28:29], s[8:9], v28, s57, v[142:143]
	v_lshl_add_u64 v[38:39], v[28:29], 0, v[144:145]
	v_pk_mul_f32 v[26:27], v[36:37], v[26:27] op_sel_hi:[0,1]
	v_pk_mul_f32 v[24:25], v[36:37], v[24:25] op_sel_hi:[0,1]
	global_store_dwordx4 v[38:39], v[24:27], off offset:64
	v_pk_mul_f32 v[22:23], v[36:37], v[22:23] op_sel_hi:[0,1]
	v_pk_mul_f32 v[20:21], v[36:37], v[20:21] op_sel_hi:[0,1]
	v_fmamk_f32 v24, v152, 0x3a800000, v150
	v_mul_f32_e32 v25, 0x4f800000, v24
	v_cmp_gt_f32_e32 vcc, s49, v24
	global_store_dwordx4 v[38:39], v[20:23], off offset:512
	v_pk_mul_f32 v[14:15], v[36:37], v[14:15] op_sel_hi:[0,1]
	v_cndmask_b32_e32 v24, v24, v25, vcc
	v_sqrt_f32_e32 v25, v24
	v_pk_mul_f32 v[12:13], v[36:37], v[12:13] op_sel_hi:[0,1]
	global_store_dwordx4 v[38:39], v[12:15], off offset:576
	v_pk_mul_f32 v[30:31], v[36:37], v[34:35] op_sel_hi:[0,1]
	v_add_u32_e32 v20, -1, v25
	v_fma_f32 v21, -v20, v25, v24
	v_cmp_ge_f32_e64 s[8:9], 0, v21
	v_add_u32_e32 v21, 1, v25
	v_fma_f32 v22, -v21, v25, v24
	v_cndmask_b32_e64 v20, v25, v20, s[8:9]
	v_cmp_lt_f32_e64 s[8:9], 0, v22
	v_add_u32_e32 v12, 0xb0, v140
	v_pk_mul_f32 v[28:29], v[36:37], v[32:33] op_sel_hi:[0,1]
	v_cndmask_b32_e64 v20, v20, v21, s[8:9]
	v_mul_f32_e32 v21, 0x37800000, v20
	v_cndmask_b32_e32 v20, v20, v21, vcc
	v_cmp_class_f32_e32 vcc, v24, v151
	global_store_dwordx4 v[38:39], v[28:31], off
	s_nop 0
	v_cndmask_b32_e32 v20, v20, v24, vcc
	v_div_scale_f32 v21, s[8:9], v20, v20, 1.0
	v_rcp_f32_e32 v22, v21
	s_nop 0
	v_fma_f32 v13, -v21, v22, 1.0
	v_fmac_f32_e32 v22, v13, v22
	v_div_scale_f32 v13, vcc, 1.0, v20, 1.0
	v_mul_f32_e32 v14, v13, v22
	v_fma_f32 v15, -v21, v14, v13
	v_fmac_f32_e32 v14, v15, v22
	v_fma_f32 v13, -v21, v14, v13
	v_div_fmas_f32 v13, v13, v22, v14
	v_div_fixup_f32 v20, v13, v20, 1.0
	v_mad_i64_i32 v[12:13], s[8:9], v12, s57, v[142:143]
	v_lshl_add_u64 v[22:23], v[12:13], 0, v[144:145]
	v_pk_mul_f32 v[14:15], v[20:21], v[18:19] op_sel_hi:[0,1]
	v_pk_mul_f32 v[12:13], v[20:21], v[16:17] op_sel_hi:[0,1]
	v_pk_mul_f32 v[10:11], v[20:21], v[10:11] op_sel_hi:[0,1]
	v_pk_mul_f32 v[8:9], v[20:21], v[8:9] op_sel_hi:[0,1]
	v_pk_mul_f32 v[6:7], v[20:21], v[6:7] op_sel_hi:[0,1]
	v_pk_mul_f32 v[4:5], v[20:21], v[4:5] op_sel_hi:[0,1]
	v_pk_mul_f32 v[2:3], v[20:21], v[2:3] op_sel_hi:[0,1]
	v_pk_mul_f32 v[0:1], v[20:21], v[0:1] op_sel_hi:[0,1]
	s_andn2_b64 vcc, exec, s[6:7]
	s_mov_b64 s[6:7], -1
	global_store_dwordx4 v[22:23], v[12:15], off
	global_store_dwordx4 v[22:23], v[8:11], off offset:64
	global_store_dwordx4 v[22:23], v[4:7], off offset:512
	global_store_dwordx4 v[22:23], v[0:3], off offset:576
	s_cbranch_vccnz .LBB0_2191
	s_andn2_b64 vcc, exec, s[10:11]
	s_cbranch_vccnz .LBB0_2190
	s_barrier
	s_branch .LBB0_2190

.LBB0_2328:
	v_lshl_add_u32 v168, s48, 8, v154
	v_mad_i64_i32 v[164:165], s[22:23], v168, s45, v[140:141]
	s_mul_i32 s22, s49, 0x180
	s_ashr_i32 s23, s22, 31
	v_pk_mul_f32 v[124:125], v[124:125], s[18:19] op_sel_hi:[1,0]
	s_lshl_b64 s[22:23], s[22:23], 1
	v_pk_mul_f32 v[126:127], v[126:127], s[18:19] op_sel_hi:[1,0]
	v_pk_mul_f32 v[166:167], v[122:123], s[18:19] op_sel_hi:[1,0]
	v_pk_mul_f32 v[122:123], v[120:121], s[18:19] op_sel_hi:[1,0]
	v_cvt_pk_bf16_f32 v120, v124, v125
	v_cvt_pk_bf16_f32 v121, v126, v127
	v_lshl_add_u64 v[124:125], v[164:165], 0, s[22:23]
	v_cvt_pk_bf16_f32 v122, v122, v123
	v_cvt_pk_bf16_f32 v123, v166, v167
	global_store_dwordx4 v[124:125], v[120:123], off
	v_pk_mul_f32 v[116:117], v[116:117], s[18:19] op_sel_hi:[1,0]
	v_pk_mul_f32 v[118:119], v[118:119], s[18:19] op_sel_hi:[1,0]
	v_pk_mul_f32 v[120:121], v[110:111], s[18:19] op_sel_hi:[1,0]
	v_pk_mul_f32 v[110:111], v[108:109], s[18:19] op_sel_hi:[1,0]
	v_cvt_pk_bf16_f32 v108, v116, v117
	v_cvt_pk_bf16_f32 v109, v118, v119
	v_pk_mul_f32 v[112:113], v[112:113], s[18:19] op_sel_hi:[1,0]
	v_cvt_pk_bf16_f32 v110, v110, v111
	v_cvt_pk_bf16_f32 v111, v120, v121
	global_store_dwordx4 v[124:125], v[108:111], off offset:384
	v_pk_mul_f32 v[100:101], v[100:101], s[18:19] op_sel_hi:[1,0]
	v_pk_mul_f32 v[102:103], v[102:103], s[18:19] op_sel_hi:[1,0]
	v_or_b32_e32 v108, 16, v168
	v_mad_i64_i32 v[108:109], s[24:25], v108, s45, v[140:141]
	v_pk_mul_f32 v[110:111], v[114:115], s[18:19] op_sel_hi:[1,0]
	v_pk_mul_f32 v[114:115], v[106:107], s[18:19] op_sel_hi:[1,0]
	v_pk_mul_f32 v[106:107], v[104:105], s[18:19] op_sel_hi:[1,0]
	v_cvt_pk_bf16_f32 v104, v112, v113
	v_cvt_pk_bf16_f32 v105, v110, v111
	v_lshl_add_u64 v[108:109], v[108:109], 0, s[22:23]
	v_cvt_pk_bf16_f32 v106, v106, v107
	v_cvt_pk_bf16_f32 v107, v114, v115
	global_store_dwordx4 v[108:109], v[104:107], off
	v_pk_mul_f32 v[96:97], v[96:97], s[18:19] op_sel_hi:[1,0]
	v_pk_mul_f32 v[84:85], v[84:85], s[18:19] op_sel_hi:[1,0]
	v_pk_mul_f32 v[104:105], v[94:95], s[18:19] op_sel_hi:[1,0]
	v_pk_mul_f32 v[94:95], v[92:93], s[18:19] op_sel_hi:[1,0]
	v_cvt_pk_bf16_f32 v92, v100, v101
	v_cvt_pk_bf16_f32 v93, v102, v103
	v_pk_mul_f32 v[86:87], v[86:87], s[18:19] op_sel_hi:[1,0]
	v_cvt_pk_bf16_f32 v94, v94, v95
	v_cvt_pk_bf16_f32 v95, v104, v105
	global_store_dwordx4 v[108:109], v[92:95], off offset:384
	v_pk_mul_f32 v[80:81], v[80:81], s[18:19] op_sel_hi:[1,0]
	v_pk_mul_f32 v[68:69], v[68:69], s[18:19] op_sel_hi:[1,0]
	v_or_b32_e32 v92, 32, v168
	v_mad_i64_i32 v[92:93], s[24:25], v92, s45, v[140:141]
	v_pk_mul_f32 v[94:95], v[98:99], s[18:19] op_sel_hi:[1,0]
	v_pk_mul_f32 v[98:99], v[90:91], s[18:19] op_sel_hi:[1,0]
	v_pk_mul_f32 v[90:91], v[88:89], s[18:19] op_sel_hi:[1,0]
	v_cvt_pk_bf16_f32 v88, v96, v97
	v_cvt_pk_bf16_f32 v89, v94, v95
	v_lshl_add_u64 v[92:93], v[92:93], 0, s[22:23]
	v_cvt_pk_bf16_f32 v90, v90, v91
	v_cvt_pk_bf16_f32 v91, v98, v99
	global_store_dwordx4 v[92:93], v[88:91], off
	v_pk_mul_f32 v[70:71], v[70:71], s[18:19] op_sel_hi:[1,0]
	v_pk_mul_f32 v[60:61], v[60:61], s[18:19] op_sel_hi:[1,0]
	v_pk_mul_f32 v[88:89], v[78:79], s[18:19] op_sel_hi:[1,0]
	v_pk_mul_f32 v[78:79], v[76:77], s[18:19] op_sel_hi:[1,0]
	v_cvt_pk_bf16_f32 v76, v84, v85
	v_cvt_pk_bf16_f32 v77, v86, v87
	v_pk_mul_f32 v[62:63], v[62:63], s[18:19] op_sel_hi:[1,0]
	v_cvt_pk_bf16_f32 v78, v78, v79
	v_cvt_pk_bf16_f32 v79, v88, v89
	global_store_dwordx4 v[92:93], v[76:79], off offset:384
	v_pk_mul_f32 v[52:53], v[52:53], s[18:19] op_sel_hi:[1,0]
	v_pk_mul_f32 v[54:55], v[54:55], s[18:19] op_sel_hi:[1,0]
	v_or_b32_e32 v76, 48, v168
	v_mad_i64_i32 v[76:77], s[24:25], v76, s45, v[140:141]
	v_pk_mul_f32 v[78:79], v[82:83], s[18:19] op_sel_hi:[1,0]
	v_pk_mul_f32 v[82:83], v[74:75], s[18:19] op_sel_hi:[1,0]
	v_pk_mul_f32 v[74:75], v[72:73], s[18:19] op_sel_hi:[1,0]
	v_cvt_pk_bf16_f32 v72, v80, v81
	v_cvt_pk_bf16_f32 v73, v78, v79
	v_lshl_add_u64 v[76:77], v[76:77], 0, s[22:23]
	v_cvt_pk_bf16_f32 v74, v74, v75
	v_cvt_pk_bf16_f32 v75, v82, v83
	global_store_dwordx4 v[76:77], v[72:75], off
	v_pk_mul_f32 v[48:49], v[48:49], s[18:19] op_sel_hi:[1,0]
	v_pk_mul_f32 v[36:37], v[36:37], s[18:19] op_sel_hi:[1,0]
	v_pk_mul_f32 v[72:73], v[66:67], s[18:19] op_sel_hi:[1,0]
	v_pk_mul_f32 v[66:67], v[64:65], s[18:19] op_sel_hi:[1,0]
	v_cvt_pk_bf16_f32 v64, v68, v69
	v_cvt_pk_bf16_f32 v65, v70, v71
	v_pk_mul_f32 v[38:39], v[38:39], s[18:19] op_sel_hi:[1,0]
	v_cvt_pk_bf16_f32 v66, v66, v67
	v_cvt_pk_bf16_f32 v67, v72, v73
	global_store_dwordx4 v[76:77], v[64:67], off offset:384
	v_pk_mul_f32 v[32:33], v[32:33], s[18:19] op_sel_hi:[1,0]
	v_pk_mul_f32 v[20:21], v[20:21], s[18:19] op_sel_hi:[1,0]
	v_add_u32_e32 v64, 0x80, v168
	v_mad_i64_i32 v[64:65], s[24:25], v64, s45, v[140:141]
	v_pk_mul_f32 v[66:67], v[58:59], s[18:19] op_sel_hi:[1,0]
	v_pk_mul_f32 v[58:59], v[56:57], s[18:19] op_sel_hi:[1,0]
	v_cvt_pk_bf16_f32 v56, v60, v61
	v_cvt_pk_bf16_f32 v57, v62, v63
	v_lshl_add_u64 v[60:61], v[64:65], 0, s[22:23]
	v_cvt_pk_bf16_f32 v58, v58, v59
	v_cvt_pk_bf16_f32 v59, v66, v67
	global_store_dwordx4 v[60:61], v[56:59], off
	v_pk_mul_f32 v[22:23], v[22:23], s[18:19] op_sel_hi:[1,0]
	v_pk_mul_f32 v[16:17], v[16:17], s[18:19] op_sel_hi:[1,0]
	v_pk_mul_f32 v[56:57], v[46:47], s[18:19] op_sel_hi:[1,0]
	v_pk_mul_f32 v[46:47], v[44:45], s[18:19] op_sel_hi:[1,0]
	v_cvt_pk_bf16_f32 v44, v52, v53
	v_cvt_pk_bf16_f32 v45, v54, v55
	s_and_b64 vcc, exec, s[6:7]
	v_cvt_pk_bf16_f32 v46, v46, v47
	v_cvt_pk_bf16_f32 v47, v56, v57
	global_store_dwordx4 v[60:61], v[44:47], off offset:384
	s_mov_b64 s[6:7], -1
	v_pk_mul_f32 v[6:7], v[6:7], s[18:19] op_sel_hi:[1,0]
	v_add_u32_e32 v44, 0x90, v168
	v_mad_i64_i32 v[44:45], s[24:25], v44, s45, v[140:141]
	v_pk_mul_f32 v[46:47], v[50:51], s[18:19] op_sel_hi:[1,0]
	v_pk_mul_f32 v[50:51], v[42:43], s[18:19] op_sel_hi:[1,0]
	v_pk_mul_f32 v[42:43], v[40:41], s[18:19] op_sel_hi:[1,0]
	v_cvt_pk_bf16_f32 v40, v48, v49
	v_cvt_pk_bf16_f32 v41, v46, v47
	v_lshl_add_u64 v[44:45], v[44:45], 0, s[22:23]
	v_cvt_pk_bf16_f32 v42, v42, v43
	v_cvt_pk_bf16_f32 v43, v50, v51
	global_store_dwordx4 v[44:45], v[40:43], off
	v_pk_mul_f32 v[4:5], v[4:5], s[18:19] op_sel_hi:[1,0]
	s_nop 0
	v_pk_mul_f32 v[40:41], v[30:31], s[18:19] op_sel_hi:[1,0]
	v_pk_mul_f32 v[30:31], v[28:29], s[18:19] op_sel_hi:[1,0]
	v_cvt_pk_bf16_f32 v28, v36, v37
	v_cvt_pk_bf16_f32 v29, v38, v39
	s_nop 0
	v_cvt_pk_bf16_f32 v30, v30, v31
	v_cvt_pk_bf16_f32 v31, v40, v41
	global_store_dwordx4 v[44:45], v[28:31], off offset:384
	s_nop 1
	v_add_u32_e32 v28, 0xa0, v168
	v_mad_i64_i32 v[28:29], s[24:25], v28, s45, v[140:141]
	v_pk_mul_f32 v[30:31], v[34:35], s[18:19] op_sel_hi:[1,0]
	v_pk_mul_f32 v[34:35], v[26:27], s[18:19] op_sel_hi:[1,0]
	v_pk_mul_f32 v[26:27], v[24:25], s[18:19] op_sel_hi:[1,0]
	v_cvt_pk_bf16_f32 v24, v32, v33
	v_cvt_pk_bf16_f32 v25, v30, v31
	v_lshl_add_u64 v[28:29], v[28:29], 0, s[22:23]
	v_cvt_pk_bf16_f32 v26, v26, v27
	v_cvt_pk_bf16_f32 v27, v34, v35
	global_store_dwordx4 v[28:29], v[24:27], off
	s_nop 1
	v_pk_mul_f32 v[24:25], v[14:15], s[18:19] op_sel_hi:[1,0]
	v_pk_mul_f32 v[14:15], v[12:13], s[18:19] op_sel_hi:[1,0]
	v_cvt_pk_bf16_f32 v12, v20, v21
	v_cvt_pk_bf16_f32 v13, v22, v23
	s_nop 0
	v_cvt_pk_bf16_f32 v14, v14, v15
	v_cvt_pk_bf16_f32 v15, v24, v25
	global_store_dwordx4 v[28:29], v[12:15], off offset:384
	s_nop 1
	v_add_u32_e32 v12, 0xb0, v168
	v_mad_i64_i32 v[12:13], s[24:25], v12, s45, v[140:141]
	v_pk_mul_f32 v[14:15], v[18:19], s[18:19] op_sel_hi:[1,0]
	v_pk_mul_f32 v[18:19], v[10:11], s[18:19] op_sel_hi:[1,0]
	v_pk_mul_f32 v[10:11], v[8:9], s[18:19] op_sel_hi:[1,0]
	v_cvt_pk_bf16_f32 v8, v16, v17
	v_cvt_pk_bf16_f32 v9, v14, v15
	v_lshl_add_u64 v[12:13], v[12:13], 0, s[22:23]
	v_cvt_pk_bf16_f32 v10, v10, v11
	v_cvt_pk_bf16_f32 v11, v18, v19
	global_store_dwordx4 v[12:13], v[8:11], off
	s_nop 1
	v_pk_mul_f32 v[8:9], v[2:3], s[18:19] op_sel_hi:[1,0]
	v_pk_mul_f32 v[2:3], v[0:1], s[18:19] op_sel_hi:[1,0]
	v_cvt_pk_bf16_f32 v0, v4, v5
	v_cvt_pk_bf16_f32 v1, v6, v7
	s_nop 0
	v_cvt_pk_bf16_f32 v2, v2, v3
	v_cvt_pk_bf16_f32 v3, v8, v9
	global_store_dwordx4 v[12:13], v[0:3], off offset:384
	s_cbranch_vccnz .LBB0_2317
	s_andn2_b64 vcc, exec, s[12:13]
	s_cbranch_vccnz .LBB0_2316
	s_barrier
	s_branch .LBB0_2316

.LBB0_2348:
	v_lshl_add_u32 v170, s33, 8, v131
	v_and_b32_e32 v140, 0x1fcf, v170
	v_cmp_gt_i32_e32 vcc, s43, v170
	s_lshl_b32 s20, s66, 2
	v_mov_b64_e32 v[154:155], s[10:11]
	v_cndmask_b32_e32 v140, v163, v140, vcc
	v_lshlrev_b32_e32 v140, 8, v140
	v_lshl_add_u64 v[184:185], v[142:143], 0, v[140:141]
	flat_load_dwordx4 v[172:175], v[184:185]
	flat_load_dwordx4 v[176:179], v[184:185] offset:16
	s_or_b32 s22, s20, s39
	v_mad_i64_i32 v[194:195], s[20:21], v170, s48, v[154:155]
	v_mov_b32_e32 v186, v124
	v_mov_b32_e32 v187, v120
	v_mov_b32_e32 v188, v120
	v_mov_b32_e32 v189, v124
	v_mov_b32_e32 v120, v125
	v_mov_b32_e32 v124, v121
	v_mov_b32_e32 v190, v126
	v_mov_b32_e32 v191, v122
	s_mul_i32 s20, s22, 0xc0
	v_mov_b32_e32 v192, v122
	v_mov_b32_e32 v193, v126
	v_mov_b32_e32 v122, v127
	v_mov_b32_e32 v126, v123
	s_ashr_i32 s21, s20, 31
	s_lshl_b64 s[20:21], s[20:21], 1
	v_mov_b32_e32 v153, v141
	v_lshl_add_u64 v[194:195], v[194:195], 0, s[20:21]
	v_lshl_add_u64 v[194:195], v[194:195], 0, v[152:153]
	s_waitcnt vmcnt(0) lgkmcnt(0)
	v_pk_mul_f32 v[186:187], v[186:187], v[172:173]
	v_pk_mul_f32 v[120:121], v[120:121], v[174:175]
	v_pk_mul_f32 v[124:125], v[124:125], v[174:175]
	v_pk_mul_f32 v[174:175], v[190:191], v[176:177]
	v_pk_mul_f32 v[122:123], v[122:123], v[178:179]
	v_pk_mul_f32 v[126:127], v[126:127], v[178:179]
	v_sub_f32_e32 v140, v186, v187
	v_sub_f32_e32 v120, v120, v121
	v_add_f32_e32 v121, v125, v124
	v_sub_f32_e32 v124, v174, v175
	v_pk_mul_f32 v[172:173], v[188:189], v[172:173]
	v_pk_mul_f32 v[176:177], v[192:193], v[176:177]
	v_sub_f32_e32 v122, v122, v123
	v_add_f32_e32 v123, v127, v126
	v_mul_f32_e32 v126, 0x3dd53b94, v140
	v_mul_f32_e32 v120, 0x3dd53b94, v120
	v_mul_f32_e32 v140, 0x3dd53b94, v121
	v_mul_f32_e32 v121, 0x3dd53b94, v124
	v_add_f32_e32 v171, v173, v172
	v_add_f32_e32 v125, v177, v176
	v_mul_f32_e32 v122, 0x3dd53b94, v122
	v_cvt_pk_bf16_f32 v120, v126, v120
	v_cvt_pk_bf16_f32 v121, v121, v122
	v_mul_f32_e32 v127, 0x3dd53b94, v171
	v_mul_f32_e32 v124, 0x3dd53b94, v125
	v_mul_f32_e32 v123, 0x3dd53b94, v123
	global_store_dwordx2 v[194:195], v[120:121], off offset:256
	v_cvt_pk_bf16_f32 v120, v127, v140
	v_cvt_pk_bf16_f32 v121, v124, v123
	global_store_dwordx2 v[194:195], v[120:121], off offset:320
	flat_load_dwordx4 v[120:123], v[184:185] offset:32
	s_nop 0
	flat_load_dwordx4 v[124:127], v[184:185] offset:48
	v_mov_b32_e32 v172, v116
	v_mov_b32_e32 v173, v112
	v_mov_b32_e32 v174, v112
	v_mov_b32_e32 v175, v116
	v_mov_b32_e32 v112, v117
	v_mov_b32_e32 v116, v113
	v_mov_b32_e32 v176, v118
	v_mov_b32_e32 v177, v114
	v_mov_b32_e32 v178, v114
	v_mov_b32_e32 v179, v118
	v_mov_b32_e32 v114, v119
	v_mov_b32_e32 v118, v115
	v_or_b32_e32 v171, 16, v170
	v_bitop3_b32 v140, v170, s49, 16 bitop3:0xc8
	v_cmp_gt_i32_e32 vcc, s43, v171
	s_waitcnt vmcnt(0) lgkmcnt(0)
	v_pk_mul_f32 v[172:173], v[172:173], v[120:121]
	v_pk_mul_f32 v[120:121], v[174:175], v[120:121]
	v_pk_mul_f32 v[112:113], v[112:113], v[122:123]
	v_pk_mul_f32 v[116:117], v[116:117], v[122:123]
	v_pk_mul_f32 v[122:123], v[176:177], v[124:125]
	v_pk_mul_f32 v[114:115], v[114:115], v[126:127]
	v_pk_mul_f32 v[118:119], v[118:119], v[126:127]
	v_add_f32_e32 v120, v121, v120
	v_sub_f32_e32 v112, v112, v113
	v_add_f32_e32 v113, v117, v116
	v_sub_f32_e32 v116, v122, v123
	v_pk_mul_f32 v[124:125], v[178:179], v[124:125]
	v_sub_f32_e32 v126, v172, v173
	v_sub_f32_e32 v114, v114, v115
	v_add_f32_e32 v115, v119, v118
	v_mul_f32_e32 v119, 0x3dd53b94, v120
	v_mul_f32_e32 v112, 0x3dd53b94, v112
	v_mul_f32_e32 v120, 0x3dd53b94, v113
	v_mul_f32_e32 v113, 0x3dd53b94, v116
	v_cndmask_b32_e32 v140, v164, v140, vcc
	v_add_f32_e32 v117, v125, v124
	v_mul_f32_e32 v118, 0x3dd53b94, v126
	v_mul_f32_e32 v114, 0x3dd53b94, v114
	v_cvt_pk_bf16_f32 v112, v118, v112
	v_cvt_pk_bf16_f32 v113, v113, v114
	v_lshlrev_b32_e32 v140, 8, v140
	v_mul_f32_e32 v116, 0x3dd53b94, v117
	v_mul_f32_e32 v115, 0x3dd53b94, v115
	global_store_dwordx2 v[194:195], v[112:113], off offset:264
	v_cvt_pk_bf16_f32 v112, v119, v120
	v_cvt_pk_bf16_f32 v113, v116, v115
	global_store_dwordx2 v[194:195], v[112:113], off offset:328
	v_lshl_add_u64 v[184:185], v[142:143], 0, v[140:141]
	flat_load_dwordx4 v[112:115], v[184:185]
	flat_load_dwordx4 v[116:119], v[184:185] offset:16
	v_mov_b32_e32 v120, v108
	v_mov_b32_e32 v121, v104
	v_mov_b32_e32 v122, v104
	v_mov_b32_e32 v123, v108
	v_mov_b32_e32 v104, v109
	v_mov_b32_e32 v108, v105
	v_mov_b32_e32 v124, v110
	v_mov_b32_e32 v125, v106
	v_mov_b32_e32 v126, v106
	v_mov_b32_e32 v127, v110
	v_mov_b32_e32 v106, v111
	v_mov_b32_e32 v110, v107
	v_mad_i64_i32 v[172:173], s[22:23], v171, s48, v[154:155]
	v_lshl_add_u64 v[172:173], v[172:173], 0, s[20:21]
	v_lshl_add_u64 v[172:173], v[172:173], 0, v[152:153]
	s_waitcnt vmcnt(0) lgkmcnt(0)
	v_pk_mul_f32 v[120:121], v[120:121], v[112:113]
	v_pk_mul_f32 v[112:113], v[122:123], v[112:113]
	v_pk_mul_f32 v[104:105], v[104:105], v[114:115]
	v_pk_mul_f32 v[108:109], v[108:109], v[114:115]
	v_pk_mul_f32 v[114:115], v[124:125], v[116:117]
	v_pk_mul_f32 v[106:107], v[106:107], v[118:119]
	v_pk_mul_f32 v[110:111], v[110:111], v[118:119]
	v_add_f32_e32 v112, v113, v112
	v_sub_f32_e32 v104, v104, v105
	v_add_f32_e32 v105, v109, v108
	v_sub_f32_e32 v108, v114, v115
	v_pk_mul_f32 v[116:117], v[126:127], v[116:117]
	v_sub_f32_e32 v118, v120, v121
	v_sub_f32_e32 v106, v106, v107
	v_add_f32_e32 v107, v111, v110
	v_mul_f32_e32 v111, 0x3dd53b94, v112
	v_mul_f32_e32 v104, 0x3dd53b94, v104
	v_mul_f32_e32 v112, 0x3dd53b94, v105
	v_mul_f32_e32 v105, 0x3dd53b94, v108
	v_add_f32_e32 v109, v117, v116
	v_mul_f32_e32 v110, 0x3dd53b94, v118
	v_mul_f32_e32 v106, 0x3dd53b94, v106
	v_cvt_pk_bf16_f32 v104, v110, v104
	v_cvt_pk_bf16_f32 v105, v105, v106
	v_mul_f32_e32 v108, 0x3dd53b94, v109
	v_mul_f32_e32 v107, 0x3dd53b94, v107
	global_store_dwordx2 v[172:173], v[104:105], off offset:256
	v_cvt_pk_bf16_f32 v104, v111, v112
	v_cvt_pk_bf16_f32 v105, v108, v107
	global_store_dwordx2 v[172:173], v[104:105], off offset:320
	flat_load_dwordx4 v[104:107], v[184:185] offset:32
	s_nop 0
	flat_load_dwordx4 v[108:111], v[184:185] offset:48
	v_mov_b32_e32 v112, v100
	v_mov_b32_e32 v113, v96
	v_mov_b32_e32 v114, v96
	v_mov_b32_e32 v115, v100
	v_mov_b32_e32 v96, v101
	v_mov_b32_e32 v100, v97
	v_mov_b32_e32 v116, v102
	v_mov_b32_e32 v117, v98
	v_mov_b32_e32 v118, v98
	v_mov_b32_e32 v119, v102
	v_mov_b32_e32 v98, v103
	v_mov_b32_e32 v102, v99
	v_or_b32_e32 v122, 32, v170
	v_bitop3_b32 v120, v170, s57, 32 bitop3:0xc8
	v_cmp_gt_i32_e32 vcc, s43, v122
	s_waitcnt vmcnt(0) lgkmcnt(0)
	v_pk_mul_f32 v[112:113], v[112:113], v[104:105]
	v_pk_mul_f32 v[104:105], v[114:115], v[104:105]
	v_pk_mul_f32 v[96:97], v[96:97], v[106:107]
	v_pk_mul_f32 v[100:101], v[100:101], v[106:107]
	v_pk_mul_f32 v[106:107], v[116:117], v[108:109]
	v_pk_mul_f32 v[98:99], v[98:99], v[110:111]
	v_pk_mul_f32 v[102:103], v[102:103], v[110:111]
	v_add_f32_e32 v104, v105, v104
	v_sub_f32_e32 v96, v96, v97
	v_add_f32_e32 v97, v101, v100
	v_sub_f32_e32 v100, v106, v107
	v_pk_mul_f32 v[108:109], v[118:119], v[108:109]
	v_sub_f32_e32 v110, v112, v113
	v_sub_f32_e32 v98, v98, v99
	v_add_f32_e32 v99, v103, v102
	v_mul_f32_e32 v103, 0x3dd53b94, v104
	v_mul_f32_e32 v96, 0x3dd53b94, v96
	v_mul_f32_e32 v104, 0x3dd53b94, v97
	v_mul_f32_e32 v97, 0x3dd53b94, v100
	v_cndmask_b32_e32 v120, v165, v120, vcc
	v_add_f32_e32 v101, v109, v108
	v_mul_f32_e32 v102, 0x3dd53b94, v110
	v_mul_f32_e32 v98, 0x3dd53b94, v98
	v_cvt_pk_bf16_f32 v96, v102, v96
	v_cvt_pk_bf16_f32 v97, v97, v98
	v_lshlrev_b32_e32 v140, 8, v120
	v_mul_f32_e32 v100, 0x3dd53b94, v101
	v_mul_f32_e32 v99, 0x3dd53b94, v99
	global_store_dwordx2 v[172:173], v[96:97], off offset:264
	v_cvt_pk_bf16_f32 v96, v103, v104
	v_cvt_pk_bf16_f32 v97, v100, v99
	global_store_dwordx2 v[172:173], v[96:97], off offset:328
	v_lshl_add_u64 v[120:121], v[142:143], 0, v[140:141]
	flat_load_dwordx4 v[96:99], v[120:121]
	flat_load_dwordx4 v[100:103], v[120:121] offset:16
	v_mov_b32_e32 v104, v92
	v_mov_b32_e32 v105, v88
	v_mov_b32_e32 v106, v88
	v_mov_b32_e32 v107, v92
	v_mov_b32_e32 v88, v93
	v_mov_b32_e32 v92, v89
	v_mov_b32_e32 v108, v94
	v_mov_b32_e32 v109, v90
	v_mov_b32_e32 v110, v90
	v_mov_b32_e32 v111, v94
	v_mov_b32_e32 v90, v95
	v_mov_b32_e32 v94, v91
	v_mad_i64_i32 v[112:113], s[22:23], v122, s48, v[154:155]
	v_lshl_add_u64 v[112:113], v[112:113], 0, s[20:21]
	v_lshl_add_u64 v[112:113], v[112:113], 0, v[152:153]
	s_waitcnt vmcnt(0) lgkmcnt(0)
	v_pk_mul_f32 v[104:105], v[104:105], v[96:97]
	v_pk_mul_f32 v[96:97], v[106:107], v[96:97]
	v_pk_mul_f32 v[88:89], v[88:89], v[98:99]
	v_pk_mul_f32 v[92:93], v[92:93], v[98:99]
	v_pk_mul_f32 v[98:99], v[108:109], v[100:101]
	v_pk_mul_f32 v[90:91], v[90:91], v[102:103]
	v_pk_mul_f32 v[94:95], v[94:95], v[102:103]
	v_add_f32_e32 v96, v97, v96
	v_sub_f32_e32 v88, v88, v89
	v_add_f32_e32 v89, v93, v92
	v_sub_f32_e32 v92, v98, v99
	v_pk_mul_f32 v[100:101], v[110:111], v[100:101]
	v_sub_f32_e32 v102, v104, v105
	v_sub_f32_e32 v90, v90, v91
	v_add_f32_e32 v91, v95, v94
	v_mul_f32_e32 v95, 0x3dd53b94, v96
	v_mul_f32_e32 v88, 0x3dd53b94, v88
	v_mul_f32_e32 v96, 0x3dd53b94, v89
	v_mul_f32_e32 v89, 0x3dd53b94, v92
	v_add_f32_e32 v93, v101, v100
	v_mul_f32_e32 v94, 0x3dd53b94, v102
	v_mul_f32_e32 v90, 0x3dd53b94, v90
	v_cvt_pk_bf16_f32 v88, v94, v88
	v_cvt_pk_bf16_f32 v89, v89, v90
	v_mul_f32_e32 v92, 0x3dd53b94, v93
	v_mul_f32_e32 v91, 0x3dd53b94, v91
	global_store_dwordx2 v[112:113], v[88:89], off offset:256
	v_cvt_pk_bf16_f32 v88, v95, v96
	v_cvt_pk_bf16_f32 v89, v92, v91
	global_store_dwordx2 v[112:113], v[88:89], off offset:320
	flat_load_dwordx4 v[88:91], v[120:121] offset:32
	s_nop 0
	flat_load_dwordx4 v[92:95], v[120:121] offset:48
	v_mov_b32_e32 v96, v84
	v_mov_b32_e32 v97, v80
	v_mov_b32_e32 v98, v80
	v_mov_b32_e32 v99, v84
	v_mov_b32_e32 v80, v85
	v_mov_b32_e32 v84, v81
	v_mov_b32_e32 v100, v86
	v_mov_b32_e32 v101, v82
	v_mov_b32_e32 v102, v82
	v_mov_b32_e32 v103, v86
	v_mov_b32_e32 v82, v87
	v_mov_b32_e32 v86, v83
	v_or_b32_e32 v106, 48, v170
	v_bitop3_b32 v104, v170, s59, 48 bitop3:0xc8
	v_cmp_gt_i32_e32 vcc, s43, v106
	s_waitcnt vmcnt(0) lgkmcnt(0)
	v_pk_mul_f32 v[96:97], v[96:97], v[88:89]
	v_pk_mul_f32 v[88:89], v[98:99], v[88:89]
	v_pk_mul_f32 v[80:81], v[80:81], v[90:91]
	v_pk_mul_f32 v[84:85], v[84:85], v[90:91]
	v_pk_mul_f32 v[90:91], v[100:101], v[92:93]
	v_pk_mul_f32 v[82:83], v[82:83], v[94:95]
	v_pk_mul_f32 v[86:87], v[86:87], v[94:95]
	v_add_f32_e32 v88, v89, v88
	v_sub_f32_e32 v80, v80, v81
	v_add_f32_e32 v81, v85, v84
	v_sub_f32_e32 v84, v90, v91
	v_pk_mul_f32 v[92:93], v[102:103], v[92:93]
	v_sub_f32_e32 v94, v96, v97
	v_sub_f32_e32 v82, v82, v83
	v_add_f32_e32 v83, v87, v86
	v_mul_f32_e32 v87, 0x3dd53b94, v88
	v_mul_f32_e32 v80, 0x3dd53b94, v80
	v_mul_f32_e32 v88, 0x3dd53b94, v81
	v_mul_f32_e32 v81, 0x3dd53b94, v84
	v_cndmask_b32_e32 v104, v166, v104, vcc
	v_add_f32_e32 v85, v93, v92
	v_mul_f32_e32 v86, 0x3dd53b94, v94
	v_mul_f32_e32 v82, 0x3dd53b94, v82
	v_cvt_pk_bf16_f32 v80, v86, v80
	v_cvt_pk_bf16_f32 v81, v81, v82
	v_lshlrev_b32_e32 v140, 8, v104
	v_mul_f32_e32 v84, 0x3dd53b94, v85
	v_mul_f32_e32 v83, 0x3dd53b94, v83
	global_store_dwordx2 v[112:113], v[80:81], off offset:264
	v_cvt_pk_bf16_f32 v80, v87, v88
	v_cvt_pk_bf16_f32 v81, v84, v83
	global_store_dwordx2 v[112:113], v[80:81], off offset:328
	v_lshl_add_u64 v[104:105], v[142:143], 0, v[140:141]
	flat_load_dwordx4 v[80:83], v[104:105]
	flat_load_dwordx4 v[84:87], v[104:105] offset:16
	v_mov_b32_e32 v88, v76
	v_mov_b32_e32 v89, v72
	v_mov_b32_e32 v90, v72
	v_mov_b32_e32 v91, v76
	v_mov_b32_e32 v72, v77
	v_mov_b32_e32 v76, v73
	v_mov_b32_e32 v92, v78
	v_mov_b32_e32 v93, v74
	v_mov_b32_e32 v94, v74
	v_mov_b32_e32 v95, v78
	v_mov_b32_e32 v74, v79
	v_mov_b32_e32 v78, v75
	v_mad_i64_i32 v[96:97], s[22:23], v106, s48, v[154:155]
	v_lshl_add_u64 v[96:97], v[96:97], 0, s[20:21]
	v_lshl_add_u64 v[96:97], v[96:97], 0, v[152:153]
	v_cmp_gt_i32_e32 vcc, s60, v170
	s_waitcnt vmcnt(0) lgkmcnt(0)
	v_pk_mul_f32 v[88:89], v[88:89], v[80:81]
	v_pk_mul_f32 v[80:81], v[90:91], v[80:81]
	v_pk_mul_f32 v[72:73], v[72:73], v[82:83]
	v_pk_mul_f32 v[76:77], v[76:77], v[82:83]
	v_pk_mul_f32 v[82:83], v[92:93], v[84:85]
	v_pk_mul_f32 v[74:75], v[74:75], v[86:87]
	v_pk_mul_f32 v[78:79], v[78:79], v[86:87]
	v_add_f32_e32 v80, v81, v80
	v_sub_f32_e32 v72, v72, v73
	v_add_f32_e32 v73, v77, v76
	v_sub_f32_e32 v76, v82, v83
	v_pk_mul_f32 v[84:85], v[94:95], v[84:85]
	v_sub_f32_e32 v86, v88, v89
	v_sub_f32_e32 v74, v74, v75
	v_add_f32_e32 v75, v79, v78
	v_mul_f32_e32 v79, 0x3dd53b94, v80
	v_mul_f32_e32 v72, 0x3dd53b94, v72
	v_mul_f32_e32 v80, 0x3dd53b94, v73
	v_mul_f32_e32 v73, 0x3dd53b94, v76
	v_add_f32_e32 v77, v85, v84
	v_mul_f32_e32 v78, 0x3dd53b94, v86
	v_mul_f32_e32 v74, 0x3dd53b94, v74
	v_cvt_pk_bf16_f32 v72, v78, v72
	v_cvt_pk_bf16_f32 v73, v73, v74
	v_mul_f32_e32 v76, 0x3dd53b94, v77
	v_mul_f32_e32 v75, 0x3dd53b94, v75
	global_store_dwordx2 v[96:97], v[72:73], off offset:256
	v_cvt_pk_bf16_f32 v72, v79, v80
	v_cvt_pk_bf16_f32 v73, v76, v75
	global_store_dwordx2 v[96:97], v[72:73], off offset:320
	flat_load_dwordx4 v[72:75], v[104:105] offset:32
	s_nop 0
	flat_load_dwordx4 v[76:79], v[104:105] offset:48
	v_mov_b32_e32 v80, v68
	v_mov_b32_e32 v81, v64
	v_mov_b32_e32 v82, v64
	v_mov_b32_e32 v83, v68
	v_mov_b32_e32 v64, v69
	v_mov_b32_e32 v68, v65
	v_mov_b32_e32 v84, v70
	v_mov_b32_e32 v85, v66
	v_mov_b32_e32 v86, v66
	v_mov_b32_e32 v87, v70
	v_mov_b32_e32 v66, v71
	v_mov_b32_e32 v70, v67
	v_add_u32_e32 v90, 0x80, v170
	v_and_b32_e32 v88, 0x1fcf, v90
	v_cndmask_b32_e32 v88, v163, v88, vcc
	v_lshlrev_b32_e32 v140, 8, v88
	v_lshl_add_u64 v[88:89], v[142:143], 0, v[140:141]
	v_cmp_gt_i32_e32 vcc, s61, v170
	s_waitcnt vmcnt(0) lgkmcnt(0)
	v_pk_mul_f32 v[80:81], v[80:81], v[72:73]
	v_pk_mul_f32 v[72:73], v[82:83], v[72:73]
	v_pk_mul_f32 v[64:65], v[64:65], v[74:75]
	v_pk_mul_f32 v[68:69], v[68:69], v[74:75]
	v_pk_mul_f32 v[74:75], v[84:85], v[76:77]
	v_pk_mul_f32 v[66:67], v[66:67], v[78:79]
	v_pk_mul_f32 v[70:71], v[70:71], v[78:79]
	v_add_f32_e32 v72, v73, v72
	v_sub_f32_e32 v64, v64, v65
	v_add_f32_e32 v65, v69, v68
	v_sub_f32_e32 v68, v74, v75
	v_pk_mul_f32 v[76:77], v[86:87], v[76:77]
	v_sub_f32_e32 v78, v80, v81
	v_sub_f32_e32 v66, v66, v67
	v_add_f32_e32 v67, v71, v70
	v_mul_f32_e32 v71, 0x3dd53b94, v72
	v_mul_f32_e32 v64, 0x3dd53b94, v64
	v_mul_f32_e32 v72, 0x3dd53b94, v65
	v_mul_f32_e32 v65, 0x3dd53b94, v68
	v_add_f32_e32 v69, v77, v76
	v_mul_f32_e32 v70, 0x3dd53b94, v78
	v_mul_f32_e32 v66, 0x3dd53b94, v66
	v_cvt_pk_bf16_f32 v64, v70, v64
	v_cvt_pk_bf16_f32 v65, v65, v66
	v_mul_f32_e32 v68, 0x3dd53b94, v69
	v_mul_f32_e32 v67, 0x3dd53b94, v67
	global_store_dwordx2 v[96:97], v[64:65], off offset:264
	v_cvt_pk_bf16_f32 v64, v71, v72
	v_cvt_pk_bf16_f32 v65, v68, v67
	global_store_dwordx2 v[96:97], v[64:65], off offset:328
	flat_load_dwordx4 v[64:67], v[88:89]
	flat_load_dwordx4 v[68:71], v[88:89] offset:16
	v_mov_b32_e32 v72, v60
	v_mov_b32_e32 v73, v56
	v_mov_b32_e32 v74, v56
	v_mov_b32_e32 v75, v60
	v_mov_b32_e32 v56, v61
	v_mov_b32_e32 v60, v57
	v_mov_b32_e32 v76, v62
	v_mov_b32_e32 v77, v58
	v_mov_b32_e32 v78, v58
	v_mov_b32_e32 v79, v62
	v_mov_b32_e32 v58, v63
	v_mov_b32_e32 v62, v59
	v_mad_i64_i32 v[80:81], s[22:23], v90, s48, v[154:155]
	v_lshl_add_u64 v[80:81], v[80:81], 0, s[20:21]
	v_lshl_add_u64 v[80:81], v[80:81], 0, v[152:153]
	s_waitcnt vmcnt(0) lgkmcnt(0)
	v_pk_mul_f32 v[72:73], v[72:73], v[64:65]
	v_pk_mul_f32 v[64:65], v[74:75], v[64:65]
	v_pk_mul_f32 v[56:57], v[56:57], v[66:67]
	v_pk_mul_f32 v[60:61], v[60:61], v[66:67]
	v_pk_mul_f32 v[66:67], v[76:77], v[68:69]
	v_pk_mul_f32 v[58:59], v[58:59], v[70:71]
	v_pk_mul_f32 v[62:63], v[62:63], v[70:71]
	v_add_f32_e32 v64, v65, v64
	v_sub_f32_e32 v56, v56, v57
	v_add_f32_e32 v57, v61, v60
	v_sub_f32_e32 v60, v66, v67
	v_pk_mul_f32 v[68:69], v[78:79], v[68:69]
	v_sub_f32_e32 v70, v72, v73
	v_sub_f32_e32 v58, v58, v59
	v_add_f32_e32 v59, v63, v62
	v_mul_f32_e32 v63, 0x3dd53b94, v64
	v_mul_f32_e32 v56, 0x3dd53b94, v56
	v_mul_f32_e32 v64, 0x3dd53b94, v57
	v_mul_f32_e32 v57, 0x3dd53b94, v60
	v_add_f32_e32 v61, v69, v68
	v_mul_f32_e32 v62, 0x3dd53b94, v70
	v_mul_f32_e32 v58, 0x3dd53b94, v58
	v_cvt_pk_bf16_f32 v56, v62, v56
	v_cvt_pk_bf16_f32 v57, v57, v58
	v_mul_f32_e32 v60, 0x3dd53b94, v61
	v_mul_f32_e32 v59, 0x3dd53b94, v59
	global_store_dwordx2 v[80:81], v[56:57], off offset:256
	v_cvt_pk_bf16_f32 v56, v63, v64
	v_cvt_pk_bf16_f32 v57, v60, v59
	global_store_dwordx2 v[80:81], v[56:57], off offset:320
	flat_load_dwordx4 v[56:59], v[88:89] offset:32
	s_nop 0
	flat_load_dwordx4 v[60:63], v[88:89] offset:48
	v_mov_b32_e32 v64, v52
	v_mov_b32_e32 v65, v48
	v_mov_b32_e32 v66, v48
	v_mov_b32_e32 v67, v52
	v_mov_b32_e32 v48, v53
	v_mov_b32_e32 v52, v49
	v_mov_b32_e32 v68, v54
	v_mov_b32_e32 v69, v50
	v_mov_b32_e32 v70, v50
	v_mov_b32_e32 v71, v54
	v_mov_b32_e32 v50, v55
	v_mov_b32_e32 v54, v51
	v_add_u32_e32 v74, 0x90, v170
	v_and_b32_e32 v72, 0x1fdf, v74
	v_cndmask_b32_e32 v72, v164, v72, vcc
	v_lshlrev_b32_e32 v140, 8, v72
	v_lshl_add_u64 v[72:73], v[142:143], 0, v[140:141]
	v_cmp_gt_i32_e32 vcc, s62, v170
	s_waitcnt vmcnt(0) lgkmcnt(0)
	v_pk_mul_f32 v[64:65], v[64:65], v[56:57]
	v_pk_mul_f32 v[56:57], v[66:67], v[56:57]
	v_pk_mul_f32 v[48:49], v[48:49], v[58:59]
	v_pk_mul_f32 v[52:53], v[52:53], v[58:59]
	v_pk_mul_f32 v[58:59], v[68:69], v[60:61]
	v_pk_mul_f32 v[50:51], v[50:51], v[62:63]
	v_pk_mul_f32 v[54:55], v[54:55], v[62:63]
	v_add_f32_e32 v56, v57, v56
	v_sub_f32_e32 v48, v48, v49
	v_add_f32_e32 v49, v53, v52
	v_sub_f32_e32 v52, v58, v59
	v_pk_mul_f32 v[60:61], v[70:71], v[60:61]
	v_sub_f32_e32 v62, v64, v65
	v_sub_f32_e32 v50, v50, v51
	v_add_f32_e32 v51, v55, v54
	v_mul_f32_e32 v55, 0x3dd53b94, v56
	v_mul_f32_e32 v48, 0x3dd53b94, v48
	v_mul_f32_e32 v56, 0x3dd53b94, v49
	v_mul_f32_e32 v49, 0x3dd53b94, v52
	v_add_f32_e32 v53, v61, v60
	v_mul_f32_e32 v54, 0x3dd53b94, v62
	v_mul_f32_e32 v50, 0x3dd53b94, v50
	v_cvt_pk_bf16_f32 v48, v54, v48
	v_cvt_pk_bf16_f32 v49, v49, v50
	v_mul_f32_e32 v52, 0x3dd53b94, v53
	v_mul_f32_e32 v51, 0x3dd53b94, v51
	global_store_dwordx2 v[80:81], v[48:49], off offset:264
	v_cvt_pk_bf16_f32 v48, v55, v56
	v_cvt_pk_bf16_f32 v49, v52, v51
	global_store_dwordx2 v[80:81], v[48:49], off offset:328
	flat_load_dwordx4 v[48:51], v[72:73]
	flat_load_dwordx4 v[52:55], v[72:73] offset:16
	v_mov_b32_e32 v56, v44
	v_mov_b32_e32 v57, v40
	v_mov_b32_e32 v58, v40
	v_mov_b32_e32 v59, v44
	v_mov_b32_e32 v40, v45
	v_mov_b32_e32 v44, v41
	v_mov_b32_e32 v60, v46
	v_mov_b32_e32 v61, v42
	v_mov_b32_e32 v62, v42
	v_mov_b32_e32 v63, v46
	v_mov_b32_e32 v42, v47
	v_mov_b32_e32 v46, v43
	v_mad_i64_i32 v[64:65], s[22:23], v74, s48, v[154:155]
	v_lshl_add_u64 v[64:65], v[64:65], 0, s[20:21]
	v_lshl_add_u64 v[64:65], v[64:65], 0, v[152:153]
	s_waitcnt vmcnt(0) lgkmcnt(0)
	v_pk_mul_f32 v[56:57], v[56:57], v[48:49]
	v_pk_mul_f32 v[48:49], v[58:59], v[48:49]
	v_pk_mul_f32 v[40:41], v[40:41], v[50:51]
	v_pk_mul_f32 v[44:45], v[44:45], v[50:51]
	v_pk_mul_f32 v[50:51], v[60:61], v[52:53]
	v_pk_mul_f32 v[42:43], v[42:43], v[54:55]
	v_pk_mul_f32 v[46:47], v[46:47], v[54:55]
	v_add_f32_e32 v48, v49, v48
	v_sub_f32_e32 v40, v40, v41
	v_add_f32_e32 v41, v45, v44
	v_sub_f32_e32 v44, v50, v51
	v_pk_mul_f32 v[52:53], v[62:63], v[52:53]
	v_sub_f32_e32 v54, v56, v57
	v_sub_f32_e32 v42, v42, v43
	v_add_f32_e32 v43, v47, v46
	v_mul_f32_e32 v47, 0x3dd53b94, v48
	v_mul_f32_e32 v40, 0x3dd53b94, v40
	v_mul_f32_e32 v48, 0x3dd53b94, v41
	v_mul_f32_e32 v41, 0x3dd53b94, v44
	v_add_f32_e32 v45, v53, v52
	v_mul_f32_e32 v46, 0x3dd53b94, v54
	v_mul_f32_e32 v42, 0x3dd53b94, v42
	v_cvt_pk_bf16_f32 v40, v46, v40
	v_cvt_pk_bf16_f32 v41, v41, v42
	v_mul_f32_e32 v44, 0x3dd53b94, v45
	v_mul_f32_e32 v43, 0x3dd53b94, v43
	global_store_dwordx2 v[64:65], v[40:41], off offset:256
	v_cvt_pk_bf16_f32 v40, v47, v48
	v_cvt_pk_bf16_f32 v41, v44, v43
	global_store_dwordx2 v[64:65], v[40:41], off offset:320
	flat_load_dwordx4 v[40:43], v[72:73] offset:32
	s_nop 0
	flat_load_dwordx4 v[44:47], v[72:73] offset:48
	v_mov_b32_e32 v48, v36
	v_mov_b32_e32 v49, v32
	v_mov_b32_e32 v50, v32
	v_mov_b32_e32 v51, v36
	v_mov_b32_e32 v32, v37
	v_mov_b32_e32 v36, v33
	v_mov_b32_e32 v52, v38
	v_mov_b32_e32 v53, v34
	v_mov_b32_e32 v54, v34
	v_mov_b32_e32 v55, v38
	v_mov_b32_e32 v34, v39
	v_mov_b32_e32 v38, v35
	v_add_u32_e32 v58, 0xa0, v170
	v_and_b32_e32 v56, 0x1fef, v58
	v_cndmask_b32_e32 v56, v165, v56, vcc
	v_lshlrev_b32_e32 v140, 8, v56
	v_lshl_add_u64 v[56:57], v[142:143], 0, v[140:141]
	v_cmp_gt_i32_e32 vcc, s63, v170
	s_waitcnt vmcnt(0) lgkmcnt(0)
	v_pk_mul_f32 v[48:49], v[48:49], v[40:41]
	v_pk_mul_f32 v[40:41], v[50:51], v[40:41]
	v_pk_mul_f32 v[32:33], v[32:33], v[42:43]
	v_pk_mul_f32 v[36:37], v[36:37], v[42:43]
	v_pk_mul_f32 v[42:43], v[52:53], v[44:45]
	v_pk_mul_f32 v[34:35], v[34:35], v[46:47]
	v_pk_mul_f32 v[38:39], v[38:39], v[46:47]
	v_add_f32_e32 v40, v41, v40
	v_sub_f32_e32 v32, v32, v33
	v_add_f32_e32 v33, v37, v36
	v_sub_f32_e32 v36, v42, v43
	v_pk_mul_f32 v[44:45], v[54:55], v[44:45]
	v_sub_f32_e32 v46, v48, v49
	v_sub_f32_e32 v34, v34, v35
	v_add_f32_e32 v35, v39, v38
	v_mul_f32_e32 v39, 0x3dd53b94, v40
	v_mul_f32_e32 v32, 0x3dd53b94, v32
	v_mul_f32_e32 v40, 0x3dd53b94, v33
	v_mul_f32_e32 v33, 0x3dd53b94, v36
	v_add_f32_e32 v37, v45, v44
	v_mul_f32_e32 v38, 0x3dd53b94, v46
	v_mul_f32_e32 v34, 0x3dd53b94, v34
	v_cvt_pk_bf16_f32 v32, v38, v32
	v_cvt_pk_bf16_f32 v33, v33, v34
	v_mul_f32_e32 v36, 0x3dd53b94, v37
	v_mul_f32_e32 v35, 0x3dd53b94, v35
	global_store_dwordx2 v[64:65], v[32:33], off offset:264
	v_cvt_pk_bf16_f32 v32, v39, v40
	v_cvt_pk_bf16_f32 v33, v36, v35
	global_store_dwordx2 v[64:65], v[32:33], off offset:328
	flat_load_dwordx4 v[32:35], v[56:57]
	flat_load_dwordx4 v[36:39], v[56:57] offset:16
	v_mov_b32_e32 v40, v28
	v_mov_b32_e32 v41, v24
	v_mov_b32_e32 v42, v24
	v_mov_b32_e32 v43, v28
	v_mov_b32_e32 v24, v29
	v_mov_b32_e32 v28, v25
	v_mov_b32_e32 v44, v30
	v_mov_b32_e32 v45, v26
	v_mov_b32_e32 v46, v26
	v_mov_b32_e32 v47, v30
	v_mov_b32_e32 v26, v31
	v_mov_b32_e32 v30, v27
	v_mad_i64_i32 v[48:49], s[22:23], v58, s48, v[154:155]
	v_lshl_add_u64 v[48:49], v[48:49], 0, s[20:21]
	v_lshl_add_u64 v[48:49], v[48:49], 0, v[152:153]
	s_waitcnt vmcnt(0) lgkmcnt(0)
	v_pk_mul_f32 v[40:41], v[40:41], v[32:33]
	v_pk_mul_f32 v[32:33], v[42:43], v[32:33]
	v_pk_mul_f32 v[24:25], v[24:25], v[34:35]
	v_pk_mul_f32 v[28:29], v[28:29], v[34:35]
	v_pk_mul_f32 v[34:35], v[44:45], v[36:37]
	v_pk_mul_f32 v[26:27], v[26:27], v[38:39]
	v_pk_mul_f32 v[30:31], v[30:31], v[38:39]
	v_add_f32_e32 v32, v33, v32
	v_sub_f32_e32 v24, v24, v25
	v_add_f32_e32 v25, v29, v28
	v_sub_f32_e32 v28, v34, v35
	v_pk_mul_f32 v[36:37], v[46:47], v[36:37]
	v_sub_f32_e32 v38, v40, v41
	v_sub_f32_e32 v26, v26, v27
	v_add_f32_e32 v27, v31, v30
	v_mul_f32_e32 v31, 0x3dd53b94, v32
	v_mul_f32_e32 v24, 0x3dd53b94, v24
	v_mul_f32_e32 v32, 0x3dd53b94, v25
	v_mul_f32_e32 v25, 0x3dd53b94, v28
	v_add_f32_e32 v29, v37, v36
	v_mul_f32_e32 v30, 0x3dd53b94, v38
	v_mul_f32_e32 v26, 0x3dd53b94, v26
	v_cvt_pk_bf16_f32 v24, v30, v24
	v_cvt_pk_bf16_f32 v25, v25, v26
	v_mul_f32_e32 v28, 0x3dd53b94, v29
	v_mul_f32_e32 v27, 0x3dd53b94, v27
	global_store_dwordx2 v[48:49], v[24:25], off offset:256
	v_cvt_pk_bf16_f32 v24, v31, v32
	v_cvt_pk_bf16_f32 v25, v28, v27
	global_store_dwordx2 v[48:49], v[24:25], off offset:320
	flat_load_dwordx4 v[24:27], v[56:57] offset:32
	s_nop 0
	flat_load_dwordx4 v[28:31], v[56:57] offset:48
	v_mov_b32_e32 v32, v20
	v_mov_b32_e32 v33, v16
	v_mov_b32_e32 v34, v16
	v_mov_b32_e32 v35, v20
	v_mov_b32_e32 v16, v21
	v_mov_b32_e32 v20, v17
	v_mov_b32_e32 v36, v22
	v_mov_b32_e32 v37, v18
	v_mov_b32_e32 v38, v18
	v_mov_b32_e32 v39, v22
	v_mov_b32_e32 v18, v23
	v_mov_b32_e32 v22, v19
	v_add_u32_e32 v42, 0xb0, v170
	v_and_b32_e32 v40, 0x1fff, v42
	v_cndmask_b32_e32 v40, v166, v40, vcc
	v_lshlrev_b32_e32 v140, 8, v40
	v_lshl_add_u64 v[40:41], v[142:143], 0, v[140:141]
	s_and_b64 vcc, exec, s[6:7]
	s_mov_b64 s[6:7], -1
	s_waitcnt vmcnt(0) lgkmcnt(0)
	v_pk_mul_f32 v[32:33], v[32:33], v[24:25]
	v_pk_mul_f32 v[24:25], v[34:35], v[24:25]
	v_pk_mul_f32 v[16:17], v[16:17], v[26:27]
	v_pk_mul_f32 v[20:21], v[20:21], v[26:27]
	v_pk_mul_f32 v[26:27], v[36:37], v[28:29]
	v_pk_mul_f32 v[18:19], v[18:19], v[30:31]
	v_pk_mul_f32 v[22:23], v[22:23], v[30:31]
	v_add_f32_e32 v24, v25, v24
	v_sub_f32_e32 v16, v16, v17
	v_add_f32_e32 v17, v21, v20
	v_sub_f32_e32 v20, v26, v27
	v_pk_mul_f32 v[28:29], v[38:39], v[28:29]
	v_sub_f32_e32 v30, v32, v33
	v_sub_f32_e32 v18, v18, v19
	v_add_f32_e32 v19, v23, v22
	v_mul_f32_e32 v23, 0x3dd53b94, v24
	v_mul_f32_e32 v16, 0x3dd53b94, v16
	v_mul_f32_e32 v24, 0x3dd53b94, v17
	v_mul_f32_e32 v17, 0x3dd53b94, v20
	v_add_f32_e32 v21, v29, v28
	v_mul_f32_e32 v22, 0x3dd53b94, v30
	v_mul_f32_e32 v18, 0x3dd53b94, v18
	v_cvt_pk_bf16_f32 v16, v22, v16
	v_cvt_pk_bf16_f32 v17, v17, v18
	v_mul_f32_e32 v20, 0x3dd53b94, v21
	v_mul_f32_e32 v19, 0x3dd53b94, v19
	global_store_dwordx2 v[48:49], v[16:17], off offset:264
	v_cvt_pk_bf16_f32 v16, v23, v24
	v_cvt_pk_bf16_f32 v17, v20, v19
	global_store_dwordx2 v[48:49], v[16:17], off offset:328
	flat_load_dwordx4 v[16:19], v[40:41]
	flat_load_dwordx4 v[20:23], v[40:41] offset:16
	v_mov_b32_e32 v24, v12
	v_mov_b32_e32 v25, v8
	v_mov_b32_e32 v26, v8
	v_mov_b32_e32 v27, v12
	v_mov_b32_e32 v8, v13
	v_mov_b32_e32 v12, v9
	v_mov_b32_e32 v28, v14
	v_mov_b32_e32 v29, v10
	v_mov_b32_e32 v30, v10
	v_mov_b32_e32 v31, v14
	v_mov_b32_e32 v10, v15
	v_mov_b32_e32 v14, v11
	v_mad_i64_i32 v[32:33], s[22:23], v42, s48, v[154:155]
	v_lshl_add_u64 v[32:33], v[32:33], 0, s[20:21]
	v_lshl_add_u64 v[32:33], v[32:33], 0, v[152:153]
	s_waitcnt vmcnt(0) lgkmcnt(0)
	v_pk_mul_f32 v[24:25], v[24:25], v[16:17]
	v_pk_mul_f32 v[16:17], v[26:27], v[16:17]
	v_pk_mul_f32 v[8:9], v[8:9], v[18:19]
	v_pk_mul_f32 v[12:13], v[12:13], v[18:19]
	v_pk_mul_f32 v[18:19], v[28:29], v[20:21]
	v_pk_mul_f32 v[10:11], v[10:11], v[22:23]
	v_pk_mul_f32 v[14:15], v[14:15], v[22:23]
	v_add_f32_e32 v16, v17, v16
	v_sub_f32_e32 v8, v8, v9
	v_add_f32_e32 v9, v13, v12
	v_sub_f32_e32 v12, v18, v19
	v_pk_mul_f32 v[20:21], v[30:31], v[20:21]
	v_sub_f32_e32 v22, v24, v25
	v_sub_f32_e32 v10, v10, v11
	v_add_f32_e32 v11, v15, v14
	v_mul_f32_e32 v15, 0x3dd53b94, v16
	v_mul_f32_e32 v8, 0x3dd53b94, v8
	v_mul_f32_e32 v16, 0x3dd53b94, v9
	v_mul_f32_e32 v9, 0x3dd53b94, v12
	v_add_f32_e32 v13, v21, v20
	v_mul_f32_e32 v14, 0x3dd53b94, v22
	v_mul_f32_e32 v10, 0x3dd53b94, v10
	v_cvt_pk_bf16_f32 v8, v14, v8
	v_cvt_pk_bf16_f32 v9, v9, v10
	v_mul_f32_e32 v12, 0x3dd53b94, v13
	v_mul_f32_e32 v11, 0x3dd53b94, v11
	global_store_dwordx2 v[32:33], v[8:9], off offset:256
	v_cvt_pk_bf16_f32 v8, v15, v16
	v_cvt_pk_bf16_f32 v9, v12, v11
	global_store_dwordx2 v[32:33], v[8:9], off offset:320
	flat_load_dwordx4 v[8:11], v[40:41] offset:32
	s_nop 0
	flat_load_dwordx4 v[12:15], v[40:41] offset:48
	v_mov_b32_e32 v16, v4
	v_mov_b32_e32 v17, v0
	v_mov_b32_e32 v18, v0
	v_mov_b32_e32 v19, v4
	v_mov_b32_e32 v0, v5
	v_mov_b32_e32 v4, v1
	v_mov_b32_e32 v20, v6
	v_mov_b32_e32 v21, v2
	v_mov_b32_e32 v22, v2
	v_mov_b32_e32 v23, v6
	v_mov_b32_e32 v2, v7
	v_mov_b32_e32 v6, v3
	s_waitcnt vmcnt(0) lgkmcnt(0)
	v_pk_mul_f32 v[16:17], v[16:17], v[8:9]
	v_pk_mul_f32 v[8:9], v[18:19], v[8:9]
	v_pk_mul_f32 v[0:1], v[0:1], v[10:11]
	v_pk_mul_f32 v[4:5], v[4:5], v[10:11]
	v_pk_mul_f32 v[10:11], v[20:21], v[12:13]
	v_pk_mul_f32 v[2:3], v[2:3], v[14:15]
	v_pk_mul_f32 v[6:7], v[6:7], v[14:15]
	v_add_f32_e32 v8, v9, v8
	v_sub_f32_e32 v0, v0, v1
	v_add_f32_e32 v1, v5, v4
	v_sub_f32_e32 v4, v10, v11
	v_pk_mul_f32 v[12:13], v[22:23], v[12:13]
	v_sub_f32_e32 v14, v16, v17
	v_sub_f32_e32 v2, v2, v3
	v_add_f32_e32 v3, v7, v6
	v_mul_f32_e32 v7, 0x3dd53b94, v8
	v_mul_f32_e32 v0, 0x3dd53b94, v0
	v_mul_f32_e32 v8, 0x3dd53b94, v1
	v_mul_f32_e32 v1, 0x3dd53b94, v4
	v_add_f32_e32 v5, v13, v12
	v_mul_f32_e32 v6, 0x3dd53b94, v14
	v_mul_f32_e32 v2, 0x3dd53b94, v2
	v_cvt_pk_bf16_f32 v0, v6, v0
	v_cvt_pk_bf16_f32 v1, v1, v2
	v_mul_f32_e32 v4, 0x3dd53b94, v5
	v_mul_f32_e32 v3, 0x3dd53b94, v3
	global_store_dwordx2 v[32:33], v[0:1], off offset:264
	v_cvt_pk_bf16_f32 v0, v7, v8
	v_cvt_pk_bf16_f32 v1, v4, v3
	global_store_dwordx2 v[32:33], v[0:1], off offset:328
	s_cbranch_vccnz .LBB0_2337
	s_andn2_b64 vcc, exec, s[12:13]
	s_cbranch_vccnz .LBB0_2336
	s_barrier
	s_branch .LBB0_2336

.LBB0_2364:
	s_cmp_lt_i32 s85, 2
	s_cselect_b32 s23, s78, 0x18800000
	s_add_u32 s34, s50, s23
	s_addc_u32 s35, s51, 0
	s_lshl_b32 s23, s85, 8
	s_and_b32 s23, s23, 0x100
	v_lshl_add_u32 v150, s30, 8, v144
	v_or_b32_e32 v128, s23, v146
	v_lshlrev_b32_e32 v128, 1, v128
	v_ashrrev_i32_e32 v151, 31, v150
	v_lshl_add_u64 v[152:153], s[34:35], 0, v[128:129]
	v_lshlrev_b64 v[142:143], 10, v[150:151]
	v_lshl_add_u64 v[142:143], v[152:153], 0, v[142:143]
	v_cvt_pk_bf16_f32 v124, v124, v125
	v_cvt_pk_bf16_f32 v125, v126, v127
	v_cvt_pk_bf16_f32 v126, v120, v121
	v_cvt_pk_bf16_f32 v127, v122, v123
	global_store_dwordx4 v[142:143], v[124:127], off
	v_cvt_pk_bf16_f32 v112, v112, v113
	v_cvt_pk_bf16_f32 v113, v114, v115
	v_cvt_pk_bf16_f32 v114, v104, v105
	v_or_b32_e32 v104, 16, v150
	v_ashrrev_i32_e32 v105, 31, v104
	v_lshlrev_b64 v[104:105], 10, v[104:105]
	v_cvt_pk_bf16_f32 v115, v106, v107
	global_store_dwordx4 v[142:143], v[112:115], off offset:256
	s_nop 1
	v_lshl_add_u64 v[112:113], v[152:153], 0, v[104:105]
	v_cvt_pk_bf16_f32 v104, v116, v117
	v_cvt_pk_bf16_f32 v105, v118, v119
	v_cvt_pk_bf16_f32 v106, v108, v109
	v_cvt_pk_bf16_f32 v107, v110, v111
	global_store_dwordx4 v[112:113], v[104:107], off
	v_cvt_pk_bf16_f32 v96, v96, v97
	v_cvt_pk_bf16_f32 v97, v98, v99
	v_cvt_pk_bf16_f32 v98, v88, v89
	v_or_b32_e32 v88, 32, v150
	v_ashrrev_i32_e32 v89, 31, v88
	v_lshlrev_b64 v[88:89], 10, v[88:89]
	v_cvt_pk_bf16_f32 v99, v90, v91
	global_store_dwordx4 v[112:113], v[96:99], off offset:256
	s_nop 1
	v_lshl_add_u64 v[96:97], v[152:153], 0, v[88:89]
	v_cvt_pk_bf16_f32 v88, v100, v101
	v_cvt_pk_bf16_f32 v89, v102, v103
	v_cvt_pk_bf16_f32 v90, v92, v93
	v_cvt_pk_bf16_f32 v91, v94, v95
	global_store_dwordx4 v[96:97], v[88:91], off
	v_cvt_pk_bf16_f32 v80, v80, v81
	v_cvt_pk_bf16_f32 v81, v82, v83
	v_cvt_pk_bf16_f32 v82, v72, v73
	v_or_b32_e32 v72, 48, v150
	v_ashrrev_i32_e32 v73, 31, v72
	v_lshlrev_b64 v[72:73], 10, v[72:73]
	v_cvt_pk_bf16_f32 v83, v74, v75
	global_store_dwordx4 v[96:97], v[80:83], off offset:256
	s_nop 1
	v_lshl_add_u64 v[80:81], v[152:153], 0, v[72:73]
	v_cvt_pk_bf16_f32 v72, v84, v85
	v_cvt_pk_bf16_f32 v73, v86, v87
	v_cvt_pk_bf16_f32 v74, v76, v77
	v_cvt_pk_bf16_f32 v75, v78, v79
	global_store_dwordx4 v[80:81], v[72:75], off
	v_cvt_pk_bf16_f32 v68, v68, v69
	v_cvt_pk_bf16_f32 v69, v70, v71
	v_cvt_pk_bf16_f32 v70, v64, v65
	v_cvt_pk_bf16_f32 v71, v66, v67
	global_store_dwordx4 v[80:81], v[68:71], off offset:256
	v_cvt_pk_bf16_f32 v60, v60, v61
	v_cvt_pk_bf16_f32 v61, v62, v63
	v_cvt_pk_bf16_f32 v62, v56, v57
	v_add_co_u32_e32 v56, vcc, s81, v142
	v_lshl_add_u64 v[64:65], v[142:143], 0, s[14:15]
	s_nop 0
	v_addc_co_u32_e32 v57, vcc, 0, v143, vcc
	v_cvt_pk_bf16_f32 v63, v58, v59
	global_store_dwordx4 v[56:57], v[60:63], off
	v_cvt_pk_bf16_f32 v48, v48, v49
	v_cvt_pk_bf16_f32 v49, v50, v51
	v_cvt_pk_bf16_f32 v50, v40, v41
	v_cvt_pk_bf16_f32 v51, v42, v43
	global_store_dwordx4 v[64:65], v[48:51], off offset:256
	v_cvt_pk_bf16_f32 v40, v52, v53
	v_cvt_pk_bf16_f32 v41, v54, v55
	v_cvt_pk_bf16_f32 v42, v44, v45
	v_add_co_u32_e32 v44, vcc, s82, v142
	s_nop 0
	v_lshl_add_u64 v[48:49], v[142:143], 0, s[16:17]
	v_addc_co_u32_e32 v45, vcc, 0, v143, vcc
	v_cvt_pk_bf16_f32 v43, v46, v47
	global_store_dwordx4 v[44:45], v[40:43], off
	v_cvt_pk_bf16_f32 v32, v32, v33
	v_cvt_pk_bf16_f32 v33, v34, v35
	v_cvt_pk_bf16_f32 v34, v24, v25
	v_cvt_pk_bf16_f32 v35, v26, v27
	global_store_dwordx4 v[48:49], v[32:35], off offset:256
	v_cvt_pk_bf16_f32 v24, v36, v37
	v_cvt_pk_bf16_f32 v25, v38, v39
	v_cvt_pk_bf16_f32 v26, v28, v29
	v_add_co_u32_e32 v28, vcc, s83, v142
	s_nop 0
	v_lshl_add_u64 v[32:33], v[142:143], 0, s[18:19]
	v_addc_co_u32_e32 v29, vcc, 0, v143, vcc
	v_cvt_pk_bf16_f32 v27, v30, v31
	global_store_dwordx4 v[28:29], v[24:27], off
	v_cvt_pk_bf16_f32 v16, v16, v17
	v_cvt_pk_bf16_f32 v17, v18, v19
	v_cvt_pk_bf16_f32 v18, v8, v9
	v_cvt_pk_bf16_f32 v19, v10, v11
	global_store_dwordx4 v[32:33], v[16:19], off offset:256
	v_cvt_pk_bf16_f32 v8, v20, v21
	v_cvt_pk_bf16_f32 v9, v22, v23
	v_cvt_pk_bf16_f32 v10, v12, v13
	v_add_co_u32_e32 v12, vcc, s84, v142
	s_nop 0
	v_lshl_add_u64 v[16:17], v[142:143], 0, s[20:21]
	v_addc_co_u32_e32 v13, vcc, 0, v143, vcc
	s_andn2_b64 vcc, exec, s[6:7]
	s_mov_b64 s[6:7], -1
	v_cvt_pk_bf16_f32 v11, v14, v15
	global_store_dwordx4 v[12:13], v[8:11], off
	v_cvt_pk_bf16_f32 v4, v4, v5
	v_cvt_pk_bf16_f32 v5, v6, v7
	v_cvt_pk_bf16_f32 v6, v0, v1
	v_cvt_pk_bf16_f32 v7, v2, v3
	global_store_dwordx4 v[16:17], v[4:7], off offset:256
	s_cbranch_vccnz .LBB0_2357
	s_andn2_b64 vcc, exec, s[8:9]
	s_cbranch_vccnz .LBB0_2356
	s_barrier
	s_branch .LBB0_2356

.LBB0_2505:
	s_cmp_lt_i32 s84, 2
	s_cselect_b32 s23, s75, 0x18800000
	s_add_u32 s34, s50, s23
	s_addc_u32 s35, s51, 0
	s_lshl_b32 s23, s84, 8
	s_and_b32 s23, s23, 0x100
	v_lshl_add_u32 v150, s30, 8, v144
	v_or_b32_e32 v136, s23, v146
	v_lshlrev_b32_e32 v136, 1, v136
	v_ashrrev_i32_e32 v151, 31, v150
	v_lshl_add_u64 v[152:153], s[34:35], 0, v[136:137]
	v_lshlrev_b64 v[142:143], 10, v[150:151]
	v_lshl_add_u64 v[142:143], v[152:153], 0, v[142:143]
	v_cvt_pk_bf16_f32 v124, v124, v125
	v_cvt_pk_bf16_f32 v125, v126, v127
	v_cvt_pk_bf16_f32 v126, v120, v121
	v_cvt_pk_bf16_f32 v127, v122, v123
	global_store_dwordx4 v[142:143], v[124:127], off
	v_cvt_pk_bf16_f32 v112, v112, v113
	v_cvt_pk_bf16_f32 v113, v114, v115
	v_cvt_pk_bf16_f32 v114, v104, v105
	v_or_b32_e32 v104, 16, v150
	v_ashrrev_i32_e32 v105, 31, v104
	v_lshlrev_b64 v[104:105], 10, v[104:105]
	v_cvt_pk_bf16_f32 v115, v106, v107
	global_store_dwordx4 v[142:143], v[112:115], off offset:256
	s_nop 1
	v_lshl_add_u64 v[112:113], v[152:153], 0, v[104:105]
	v_cvt_pk_bf16_f32 v104, v116, v117
	v_cvt_pk_bf16_f32 v105, v118, v119
	v_cvt_pk_bf16_f32 v106, v108, v109
	v_cvt_pk_bf16_f32 v107, v110, v111
	global_store_dwordx4 v[112:113], v[104:107], off
	v_cvt_pk_bf16_f32 v96, v96, v97
	v_cvt_pk_bf16_f32 v97, v98, v99
	v_cvt_pk_bf16_f32 v98, v88, v89
	v_or_b32_e32 v88, 32, v150
	v_ashrrev_i32_e32 v89, 31, v88
	v_lshlrev_b64 v[88:89], 10, v[88:89]
	v_cvt_pk_bf16_f32 v99, v90, v91
	global_store_dwordx4 v[112:113], v[96:99], off offset:256
	s_nop 1
	v_lshl_add_u64 v[96:97], v[152:153], 0, v[88:89]
	v_cvt_pk_bf16_f32 v88, v100, v101
	v_cvt_pk_bf16_f32 v89, v102, v103
	v_cvt_pk_bf16_f32 v90, v92, v93
	v_cvt_pk_bf16_f32 v91, v94, v95
	global_store_dwordx4 v[96:97], v[88:91], off
	v_cvt_pk_bf16_f32 v80, v80, v81
	v_cvt_pk_bf16_f32 v81, v82, v83
	v_cvt_pk_bf16_f32 v82, v72, v73
	v_or_b32_e32 v72, 48, v150
	v_ashrrev_i32_e32 v73, 31, v72
	v_lshlrev_b64 v[72:73], 10, v[72:73]
	v_cvt_pk_bf16_f32 v83, v74, v75
	global_store_dwordx4 v[96:97], v[80:83], off offset:256
	s_nop 1
	v_lshl_add_u64 v[80:81], v[152:153], 0, v[72:73]
	v_cvt_pk_bf16_f32 v72, v84, v85
	v_cvt_pk_bf16_f32 v73, v86, v87
	v_cvt_pk_bf16_f32 v74, v76, v77
	v_cvt_pk_bf16_f32 v75, v78, v79
	global_store_dwordx4 v[80:81], v[72:75], off
	v_cvt_pk_bf16_f32 v68, v68, v69
	v_cvt_pk_bf16_f32 v69, v70, v71
	v_cvt_pk_bf16_f32 v70, v64, v65
	v_cvt_pk_bf16_f32 v71, v66, v67
	global_store_dwordx4 v[80:81], v[68:71], off offset:256
	v_cvt_pk_bf16_f32 v60, v60, v61
	v_cvt_pk_bf16_f32 v61, v62, v63
	v_cvt_pk_bf16_f32 v62, v56, v57
	v_add_co_u32_e32 v56, vcc, s78, v142
	v_lshl_add_u64 v[64:65], v[142:143], 0, s[14:15]
	s_nop 0
	v_addc_co_u32_e32 v57, vcc, 0, v143, vcc
	v_cvt_pk_bf16_f32 v63, v58, v59
	global_store_dwordx4 v[56:57], v[60:63], off
	v_cvt_pk_bf16_f32 v48, v48, v49
	v_cvt_pk_bf16_f32 v49, v50, v51
	v_cvt_pk_bf16_f32 v50, v40, v41
	v_cvt_pk_bf16_f32 v51, v42, v43
	global_store_dwordx4 v[64:65], v[48:51], off offset:256
	v_cvt_pk_bf16_f32 v40, v52, v53
	v_cvt_pk_bf16_f32 v41, v54, v55
	v_cvt_pk_bf16_f32 v42, v44, v45
	v_add_co_u32_e32 v44, vcc, s81, v142
	s_nop 0
	v_lshl_add_u64 v[48:49], v[142:143], 0, s[16:17]
	v_addc_co_u32_e32 v45, vcc, 0, v143, vcc
	v_cvt_pk_bf16_f32 v43, v46, v47
	global_store_dwordx4 v[44:45], v[40:43], off
	v_cvt_pk_bf16_f32 v32, v32, v33
	v_cvt_pk_bf16_f32 v33, v34, v35
	v_cvt_pk_bf16_f32 v34, v24, v25
	v_cvt_pk_bf16_f32 v35, v26, v27
	global_store_dwordx4 v[48:49], v[32:35], off offset:256
	v_cvt_pk_bf16_f32 v24, v36, v37
	v_cvt_pk_bf16_f32 v25, v38, v39
	v_cvt_pk_bf16_f32 v26, v28, v29
	v_add_co_u32_e32 v28, vcc, s82, v142
	s_nop 0
	v_lshl_add_u64 v[32:33], v[142:143], 0, s[18:19]
	v_addc_co_u32_e32 v29, vcc, 0, v143, vcc
	v_cvt_pk_bf16_f32 v27, v30, v31
	global_store_dwordx4 v[28:29], v[24:27], off
	v_cvt_pk_bf16_f32 v16, v16, v17
	v_cvt_pk_bf16_f32 v17, v18, v19
	v_cvt_pk_bf16_f32 v18, v8, v9
	v_cvt_pk_bf16_f32 v19, v10, v11
	global_store_dwordx4 v[32:33], v[16:19], off offset:256
	v_cvt_pk_bf16_f32 v8, v20, v21
	v_cvt_pk_bf16_f32 v9, v22, v23
	v_cvt_pk_bf16_f32 v10, v12, v13
	v_add_co_u32_e32 v12, vcc, s83, v142
	s_nop 0
	v_lshl_add_u64 v[16:17], v[142:143], 0, s[20:21]
	v_addc_co_u32_e32 v13, vcc, 0, v143, vcc
	s_andn2_b64 vcc, exec, s[6:7]
	s_mov_b64 s[6:7], -1
	v_cvt_pk_bf16_f32 v11, v14, v15
	global_store_dwordx4 v[12:13], v[8:11], off
	v_cvt_pk_bf16_f32 v4, v4, v5
	v_cvt_pk_bf16_f32 v5, v6, v7
	v_cvt_pk_bf16_f32 v6, v0, v1
	v_cvt_pk_bf16_f32 v7, v2, v3
	global_store_dwordx4 v[16:17], v[4:7], off offset:256
	s_cbranch_vccnz .LBB0_2498
	s_andn2_b64 vcc, exec, s[8:9]
	s_cbranch_vccnz .LBB0_2497
	s_barrier
	s_branch .LBB0_2497
